# GEMM MFMA segments: removed the duplicate lgkmcnt(0) after the barrier (already waited before it)
# speedup vs baseline: 1.0031x; 1.0012x over previous
; #define PG8_STAGE(bufoff, gbase, voff) do { _Pragma("unroll") for (int _i = 0; _i < 2; ++_i) \
;         __builtin_amdgcn_global_load_lds((const unsigned*)((const char*)(gbase) + (voff)[_i]), (LAS unsigned*)(lds + (bufoff) + ldsw + _i * 8192), 16, 0, 0); } while (0)
; #define PG8_LDA(dst, b, h) do { _Pragma("unroll") for (int m = 0; m < 4; ++m) _Pragma("unroll") for (int k = 0; k < 2; ++k) dst[m][k] = *(const LAS bf16x8*)(lds + PG8_SA(b, h) + aoff + m * 2048 + k * 1024); } while (0)
; #define PG8_LDB(dst, b, h) do { _Pragma("unroll") for (int n = 0; n < 2; ++n) _Pragma("unroll") for (int k = 0; k < 2; ++k) dst[n][k] = *(const LAS bf16x8*)(lds + PG8_SB(b, h) + boff + n * 2048 + k * 1024); } while (0)
; #define PG8_MMA(ai, bj, At, Bt) do { __builtin_amdgcn_s_setprio(1); _Pragma("unroll") for (int m = 0; m < 4; ++m) _Pragma("unroll") for (int n = 0; n < 2; ++n) _Pragma("unroll") for (int k = 0; k < 2; ++k) \
;         acc[ai][bj][m][n] = __builtin_amdgcn_mfma_f32_16x16x32_bf16(Bt[n][k], At[m][k], acc[ai][bj][m][n], 0, 0, 0); __builtin_amdgcn_s_setprio(0); } while (0)
; #define PG8_WAIT_V(n) asm volatile("s_waitcnt vmcnt(" #n ")" ::: "memory")
; #define PG8_WAIT_L(n) asm volatile("s_waitcnt lgkmcnt(" #n ")" ::: "memory")
; #define PG8_BAR __builtin_amdgcn_s_barrier()
; #define PG8_SCHED __builtin_amdgcn_sched_barrier(0)
; template <class Epi>
; DI void gemm_phase(LAS unsigned char* lds, const Gemm g, const Epi& E, const int tid) {
;     ...
;             PG8_LDB(B0, 0, 0); PG8_LDB(B1, 0, 1); PG8_SCHED; PG8_LDA(At, 0, 0); PG8_STAGE(PG8_SA(1, 1), a1 + hstepA, voffA);
;             PG8_WAIT_V(8); PG8_WAIT_L(0); PG8_BAR; PG8_MMA(0, 0, At, B0); PG8_MMA(0, 1, At, B1); PG8_BAR; PG8_SCHED;
;             PG8_LDA(At, 0, 1); PG8_STAGE(PG8_SB(0, 0), b2, voffB); PG8_STAGE(PG8_SB(0, 1), b2 + hstepB, voffB); PG8_STAGE(PG8_SA(0, 0), a2, voffA);
;             PG8_WAIT_V(8); PG8_WAIT_L(0); PG8_BAR; PG8_MMA(1, 0, At, B0); PG8_MMA(1, 1, At, B1); PG8_BAR; PG8_SCHED;
.LBB0_92:
	s_add_u32 s12, s46, 0x7fc000
	s_addc_u32 s48, s47, 0
	s_cmp_eq_u32 s67, 60
	s_cselect_b32 s52, s63, s12
	s_cselect_b32 s53, s35, s48
	s_cselect_b32 s50, s64, s65
	s_cselect_b32 s51, s41, s66
	s_add_u32 s48, s52, 0x800000
	s_addc_u32 s49, s53, 0
	s_add_i32 s12, 0, 0x10000
	v_add_u32_e32 v144, s12, v147
	s_add_i32 s70, 0, 0x14000
	ds_read_b128 v[140:143], v144
	ds_read_b128 v[150:153], v144 offset:1024
	ds_read_b128 v[154:157], v144 offset:2048
	ds_read_b128 v[158:161], v144 offset:3072
	v_add_u32_e32 v144, s70, v147
	ds_read_b128 v[162:165], v144
	ds_read_b128 v[166:169], v144 offset:1024
	ds_read_b128 v[170:173], v144 offset:2048
	ds_read_b128 v[174:177], v144 offset:3072
	v_lshl_add_u64 v[144:145], s[46:47], 0, v[136:137]
	s_add_i32 m0, s54, 0xc000
	ds_read_b128 v[178:181], v149
	ds_read_b128 v[196:199], v149 offset:1024
	ds_read_b128 v[200:203], v149 offset:2048
	ds_read_b128 v[204:207], v149 offset:3072
	ds_read_b128 v[208:211], v149 offset:4096
	ds_read_b128 v[226:229], v149 offset:5120
	ds_read_b128 v[230:233], v149 offset:6144
	ds_read_b128 v[234:237], v149 offset:7168
	global_load_lds_dwordx4 v[144:145], off
	v_lshl_add_u64 v[144:145], s[46:47], 0, v[138:139]
	s_add_i32 m0, s54, 0xe000
	s_nop 0
	global_load_lds_dwordx4 v[144:145], off
	s_waitcnt vmcnt(8)
	s_waitcnt lgkmcnt(0)
	s_barrier
	s_setprio 1
	v_mfma_f32_16x16x32_bf16 v[126:129], v[140:143], v[178:181], v[126:129]
	v_mfma_f32_16x16x32_bf16 v[122:125], v[154:157], v[178:181], v[122:125]
	v_mfma_f32_16x16x32_bf16 v[118:121], v[140:143], v[200:203], v[118:121]
	v_mfma_f32_16x16x32_bf16 v[110:113], v[154:157], v[200:203], v[110:113]
	v_mfma_f32_16x16x32_bf16 v[94:97], v[140:143], v[208:211], v[94:97]
	v_mfma_f32_16x16x32_bf16 v[90:93], v[154:157], v[208:211], v[90:93]
	v_mfma_f32_16x16x32_bf16 v[86:89], v[140:143], v[230:233], v[86:89]
	v_mfma_f32_16x16x32_bf16 v[78:81], v[154:157], v[230:233], v[78:81]
	v_mfma_f32_16x16x32_bf16 v[126:129], v[150:153], v[196:199], v[126:129]
	v_mfma_f32_16x16x32_bf16 v[122:125], v[158:161], v[196:199], v[122:125]
	v_mfma_f32_16x16x32_bf16 v[118:121], v[150:153], v[204:207], v[118:121]
	v_mfma_f32_16x16x32_bf16 v[110:113], v[158:161], v[204:207], v[110:113]
	v_mfma_f32_16x16x32_bf16 v[94:97], v[150:153], v[226:229], v[94:97]
	v_mfma_f32_16x16x32_bf16 v[90:93], v[158:161], v[226:229], v[90:93]
	v_mfma_f32_16x16x32_bf16 v[86:89], v[150:153], v[234:237], v[86:89]
	v_mfma_f32_16x16x32_bf16 v[78:81], v[158:161], v[234:237], v[78:81]
	v_mfma_f32_16x16x32_bf16 v[114:117], v[162:165], v[178:181], v[114:117]
	v_mfma_f32_16x16x32_bf16 v[106:109], v[170:173], v[178:181], v[106:109]
	v_mfma_f32_16x16x32_bf16 v[102:105], v[162:165], v[200:203], v[102:105]
	v_mfma_f32_16x16x32_bf16 v[98:101], v[170:173], v[200:203], v[98:101]
	v_mfma_f32_16x16x32_bf16 v[82:85], v[162:165], v[208:211], v[82:85]
	v_mfma_f32_16x16x32_bf16 v[74:77], v[170:173], v[208:211], v[74:77]
	v_mfma_f32_16x16x32_bf16 v[70:73], v[162:165], v[230:233], v[70:73]
	v_mfma_f32_16x16x32_bf16 v[66:69], v[170:173], v[230:233], v[66:69]
	v_mfma_f32_16x16x32_bf16 v[114:117], v[166:169], v[196:199], v[114:117]
	v_mfma_f32_16x16x32_bf16 v[106:109], v[174:177], v[196:199], v[106:109]
	v_mfma_f32_16x16x32_bf16 v[102:105], v[166:169], v[204:207], v[102:105]
	v_mfma_f32_16x16x32_bf16 v[98:101], v[174:177], v[204:207], v[98:101]
	v_mfma_f32_16x16x32_bf16 v[82:85], v[166:169], v[226:229], v[82:85]
	v_mfma_f32_16x16x32_bf16 v[74:77], v[174:177], v[226:229], v[74:77]
	v_mfma_f32_16x16x32_bf16 v[70:73], v[166:169], v[234:237], v[70:73]
	v_mfma_f32_16x16x32_bf16 v[66:69], v[174:177], v[234:237], v[66:69]
	s_setprio 0
	s_barrier
	s_add_i32 s12, s12, s13
	v_lshl_add_u64 v[144:145], s[50:51], 0, v[0:1]
	s_mov_b32 m0, s12
	ds_read_b128 v[178:181], v149 offset:16384
	ds_read_b128 v[196:199], v149 offset:17408
	ds_read_b128 v[200:203], v149 offset:18432
	ds_read_b128 v[204:207], v149 offset:19456
	ds_read_b128 v[208:211], v149 offset:20480
	ds_read_b128 v[226:229], v149 offset:21504
	ds_read_b128 v[230:233], v149 offset:22528
	ds_read_b128 v[234:237], v149 offset:23552
	global_load_lds_dwordx4 v[144:145], off
	s_add_i32 m0, s12, 0x2000
	s_add_u32 s68, s50, 0x100000
	v_lshl_add_u64 v[182:183], s[50:51], 0, v[130:131]
	s_addc_u32 s69, s51, 0
	s_add_i32 s12, s70, s13
	global_load_lds_dwordx4 v[182:183], off
	v_lshl_add_u64 v[186:187], s[68:69], 0, v[0:1]
	s_mov_b32 m0, s12
	s_nop 0
	global_load_lds_dwordx4 v[186:187], off
	v_lshl_add_u64 v[186:187], s[68:69], 0, v[130:131]
	s_add_i32 m0, s12, 0x2000
	s_nop 0
	global_load_lds_dwordx4 v[186:187], off
	v_lshl_add_u64 v[186:187], s[52:53], 0, v[134:135]
	s_mov_b32 m0, s54
	s_nop 0
	global_load_lds_dwordx4 v[186:187], off
	v_lshl_add_u64 v[186:187], s[52:53], 0, v[132:133]
	s_mov_b32 m0, s55
	s_nop 0
	global_load_lds_dwordx4 v[186:187], off
	s_waitcnt vmcnt(8)
	s_waitcnt lgkmcnt(0)
	s_barrier
; #define PG8_STAGE(bufoff, gbase, voff) do { _Pragma("unroll") for (int _i = 0; _i < 2; ++_i) \
;         __builtin_amdgcn_global_load_lds((const unsigned*)((const char*)(gbase) + (voff)[_i]), (LAS unsigned*)(lds + (bufoff) + ldsw + _i * 8192), 16, 0, 0); } while (0)
; #define PG8_LDA(dst, b, h) do { _Pragma("unroll") for (int m = 0; m < 4; ++m) _Pragma("unroll") for (int k = 0; k < 2; ++k) dst[m][k] = *(const LAS bf16x8*)(lds + PG8_SA(b, h) + aoff + m * 2048 + k * 1024); } while (0)
; #define PG8_LDB(dst, b, h) do { _Pragma("unroll") for (int n = 0; n < 2; ++n) _Pragma("unroll") for (int k = 0; k < 2; ++k) dst[n][k] = *(const LAS bf16x8*)(lds + PG8_SB(b, h) + boff + n * 2048 + k * 1024); } while (0)
; #define PG8_MMA(ai, bj, At, Bt) do { __builtin_amdgcn_s_setprio(1); _Pragma("unroll") for (int m = 0; m < 4; ++m) _Pragma("unroll") for (int n = 0; n < 2; ++n) _Pragma("unroll") for (int k = 0; k < 2; ++k) \
;         acc[ai][bj][m][n] = __builtin_amdgcn_mfma_f32_16x16x32_bf16(Bt[n][k], At[m][k], acc[ai][bj][m][n], 0, 0, 0); __builtin_amdgcn_s_setprio(0); } while (0)
; #define PG8_WAIT_V(n) asm volatile("s_waitcnt vmcnt(" #n ")" ::: "memory")
; #define PG8_WAIT_L(n) asm volatile("s_waitcnt lgkmcnt(" #n ")" ::: "memory")
; #define PG8_BAR __builtin_amdgcn_s_barrier()
; #define PG8_SCHED __builtin_amdgcn_sched_barrier(0)
; template <class Epi>
; DI void gemm_phase(LAS unsigned char* lds, const Gemm g, const Epi& E, const int tid) {
;     ...
;             PG8_WAIT_V(8); PG8_WAIT_L(0); PG8_BAR; PG8_MMA(1, 0, At, B0); PG8_MMA(1, 1, At, B1); PG8_BAR; PG8_SCHED;
;             PG8_LDB(B0, 1, 0); PG8_LDB(B1, 1, 1); PG8_SCHED; PG8_LDA(At, 1, 0); PG8_STAGE(PG8_SA(0, 1), a2 + hstepA, voffA);
;             PG8_WAIT_V(8); PG8_WAIT_L(0); PG8_BAR; PG8_MMA(0, 0, At, B0); PG8_MMA(0, 1, At, B1); PG8_BAR; PG8_SCHED;
	s_setprio 1
	v_mfma_f32_16x16x32_bf16 v[62:65], v[140:143], v[178:181], v[62:65]
	v_mfma_f32_16x16x32_bf16 v[58:61], v[154:157], v[178:181], v[58:61]
	v_mfma_f32_16x16x32_bf16 v[54:57], v[140:143], v[200:203], v[54:57]
	v_mfma_f32_16x16x32_bf16 v[46:49], v[154:157], v[200:203], v[46:49]
	v_mfma_f32_16x16x32_bf16 v[34:37], v[140:143], v[208:211], v[34:37]
	v_mfma_f32_16x16x32_bf16 v[26:29], v[154:157], v[208:211], v[26:29]
	v_mfma_f32_16x16x32_bf16 v[22:25], v[140:143], v[230:233], v[22:25]
	v_mfma_f32_16x16x32_bf16 v[14:17], v[154:157], v[230:233], v[14:17]
	v_mfma_f32_16x16x32_bf16 v[62:65], v[150:153], v[196:199], v[62:65]
	v_mfma_f32_16x16x32_bf16 v[58:61], v[158:161], v[196:199], v[58:61]
	v_mfma_f32_16x16x32_bf16 v[54:57], v[150:153], v[204:207], v[54:57]
	v_mfma_f32_16x16x32_bf16 v[46:49], v[158:161], v[204:207], v[46:49]
	v_mfma_f32_16x16x32_bf16 v[34:37], v[150:153], v[226:229], v[34:37]
	v_mfma_f32_16x16x32_bf16 v[26:29], v[158:161], v[226:229], v[26:29]
	v_mfma_f32_16x16x32_bf16 v[22:25], v[150:153], v[234:237], v[22:25]
	v_mfma_f32_16x16x32_bf16 v[14:17], v[158:161], v[234:237], v[14:17]
	v_mfma_f32_16x16x32_bf16 v[50:53], v[162:165], v[178:181], v[50:53]
	v_mfma_f32_16x16x32_bf16 v[42:45], v[170:173], v[178:181], v[42:45]
	v_mfma_f32_16x16x32_bf16 v[38:41], v[162:165], v[200:203], v[38:41]
	v_mfma_f32_16x16x32_bf16 v[30:33], v[170:173], v[200:203], v[30:33]
	v_mfma_f32_16x16x32_bf16 v[18:21], v[162:165], v[208:211], v[18:21]
	v_mfma_f32_16x16x32_bf16 v[10:13], v[170:173], v[208:211], v[10:13]
	v_mfma_f32_16x16x32_bf16 v[6:9], v[162:165], v[230:233], v[6:9]
	v_mfma_f32_16x16x32_bf16 v[2:5], v[170:173], v[230:233], v[2:5]
	v_mfma_f32_16x16x32_bf16 v[50:53], v[166:169], v[196:199], v[50:53]
	v_mfma_f32_16x16x32_bf16 v[42:45], v[174:177], v[196:199], v[42:45]
	v_mfma_f32_16x16x32_bf16 v[38:41], v[166:169], v[204:207], v[38:41]
	v_mfma_f32_16x16x32_bf16 v[30:33], v[174:177], v[204:207], v[30:33]
	v_mfma_f32_16x16x32_bf16 v[18:21], v[166:169], v[226:229], v[18:21]
	v_mfma_f32_16x16x32_bf16 v[10:13], v[174:177], v[226:229], v[10:13]
	v_mfma_f32_16x16x32_bf16 v[6:9], v[166:169], v[234:237], v[6:9]
	v_mfma_f32_16x16x32_bf16 v[2:5], v[174:177], v[234:237], v[2:5]
	s_setprio 0
	s_barrier
	s_add_i32 s12, 0, 0x18000
	s_add_i32 s68, 0, 0x1c000
	v_add_u32_e32 v158, s12, v147
	v_add_u32_e32 v174, s68, v147
	ds_read_b128 v[140:143], v158
	ds_read_b128 v[150:153], v158 offset:1024
	ds_read_b128 v[154:157], v158 offset:2048
	ds_read_b128 v[158:161], v158 offset:3072
	ds_read_b128 v[162:165], v174
	ds_read_b128 v[166:169], v174 offset:1024
	ds_read_b128 v[170:173], v174 offset:2048
	ds_read_b128 v[174:177], v174 offset:3072
	s_add_u32 s52, s52, 0x4000
	s_addc_u32 s53, s53, 0
	s_mov_b32 m0, s56
	v_lshl_add_u64 v[186:187], s[52:53], 0, v[134:135]
	ds_read_b128 v[178:181], v149 offset:32768
	ds_read_b128 v[196:199], v149 offset:33792
	ds_read_b128 v[200:203], v149 offset:34816
	ds_read_b128 v[204:207], v149 offset:35840
	ds_read_b128 v[208:211], v149 offset:36864
	ds_read_b128 v[226:229], v149 offset:37888
	ds_read_b128 v[230:233], v149 offset:38912
	ds_read_b128 v[234:237], v149 offset:39936
	global_load_lds_dwordx4 v[186:187], off
	v_lshl_add_u64 v[186:187], s[52:53], 0, v[132:133]
	s_mov_b32 m0, s57
	s_nop 0
	global_load_lds_dwordx4 v[186:187], off
	s_waitcnt vmcnt(8)
	s_waitcnt lgkmcnt(0)
	s_barrier
	s_setprio 1
	v_mfma_f32_16x16x32_bf16 v[126:129], v[140:143], v[178:181], v[126:129]
	v_mfma_f32_16x16x32_bf16 v[122:125], v[154:157], v[178:181], v[122:125]
	v_mfma_f32_16x16x32_bf16 v[118:121], v[140:143], v[200:203], v[118:121]
	v_mfma_f32_16x16x32_bf16 v[110:113], v[154:157], v[200:203], v[110:113]
	v_mfma_f32_16x16x32_bf16 v[94:97], v[140:143], v[208:211], v[94:97]
	v_mfma_f32_16x16x32_bf16 v[90:93], v[154:157], v[208:211], v[90:93]
	v_mfma_f32_16x16x32_bf16 v[86:89], v[140:143], v[230:233], v[86:89]
	v_mfma_f32_16x16x32_bf16 v[78:81], v[154:157], v[230:233], v[78:81]
	v_mfma_f32_16x16x32_bf16 v[126:129], v[150:153], v[196:199], v[126:129]
	v_mfma_f32_16x16x32_bf16 v[122:125], v[158:161], v[196:199], v[122:125]
	v_mfma_f32_16x16x32_bf16 v[118:121], v[150:153], v[204:207], v[118:121]
	v_mfma_f32_16x16x32_bf16 v[110:113], v[158:161], v[204:207], v[110:113]
	v_mfma_f32_16x16x32_bf16 v[94:97], v[150:153], v[226:229], v[94:97]
	v_mfma_f32_16x16x32_bf16 v[90:93], v[158:161], v[226:229], v[90:93]
	v_mfma_f32_16x16x32_bf16 v[86:89], v[150:153], v[234:237], v[86:89]
	v_mfma_f32_16x16x32_bf16 v[78:81], v[158:161], v[234:237], v[78:81]
	v_mfma_f32_16x16x32_bf16 v[114:117], v[162:165], v[178:181], v[114:117]
	v_mfma_f32_16x16x32_bf16 v[106:109], v[170:173], v[178:181], v[106:109]
	v_mfma_f32_16x16x32_bf16 v[102:105], v[162:165], v[200:203], v[102:105]
	v_mfma_f32_16x16x32_bf16 v[98:101], v[170:173], v[200:203], v[98:101]
	v_mfma_f32_16x16x32_bf16 v[82:85], v[162:165], v[208:211], v[82:85]
	v_mfma_f32_16x16x32_bf16 v[74:77], v[170:173], v[208:211], v[74:77]
	v_mfma_f32_16x16x32_bf16 v[70:73], v[162:165], v[230:233], v[70:73]
	v_mfma_f32_16x16x32_bf16 v[66:69], v[170:173], v[230:233], v[66:69]
	v_mfma_f32_16x16x32_bf16 v[114:117], v[166:169], v[196:199], v[114:117]
	v_mfma_f32_16x16x32_bf16 v[106:109], v[174:177], v[196:199], v[106:109]
	v_mfma_f32_16x16x32_bf16 v[102:105], v[166:169], v[204:207], v[102:105]
	v_mfma_f32_16x16x32_bf16 v[98:101], v[174:177], v[204:207], v[98:101]
	v_mfma_f32_16x16x32_bf16 v[82:85], v[166:169], v[226:229], v[82:85]
	v_mfma_f32_16x16x32_bf16 v[74:77], v[174:177], v[226:229], v[74:77]
	v_mfma_f32_16x16x32_bf16 v[70:73], v[166:169], v[234:237], v[70:73]
	v_mfma_f32_16x16x32_bf16 v[66:69], v[174:177], v[234:237], v[66:69]
	s_setprio 0
	s_barrier
; #define PG8_STAGE(bufoff, gbase, voff) do { _Pragma("unroll") for (int _i = 0; _i < 2; ++_i) \
;         __builtin_amdgcn_global_load_lds((const unsigned*)((const char*)(gbase) + (voff)[_i]), (LAS unsigned*)(lds + (bufoff) + ldsw + _i * 8192), 16, 0, 0); } while (0)
; #define PG8_LDA(dst, b, h) do { _Pragma("unroll") for (int m = 0; m < 4; ++m) _Pragma("unroll") for (int k = 0; k < 2; ++k) dst[m][k] = *(const LAS bf16x8*)(lds + PG8_SA(b, h) + aoff + m * 2048 + k * 1024); } while (0)
; #define PG8_MMA(ai, bj, At, Bt) do { __builtin_amdgcn_s_setprio(1); _Pragma("unroll") for (int m = 0; m < 4; ++m) _Pragma("unroll") for (int n = 0; n < 2; ++n) _Pragma("unroll") for (int k = 0; k < 2; ++k) \
;         acc[ai][bj][m][n] = __builtin_amdgcn_mfma_f32_16x16x32_bf16(Bt[n][k], At[m][k], acc[ai][bj][m][n], 0, 0, 0); __builtin_amdgcn_s_setprio(0); } while (0)
; #define PG8_WAIT_V(n) asm volatile("s_waitcnt vmcnt(" #n ")" ::: "memory")
; #define PG8_WAIT_L(n) asm volatile("s_waitcnt lgkmcnt(" #n ")" ::: "memory")
; #define PG8_BAR __builtin_amdgcn_s_barrier()
; #define PG8_SCHED __builtin_amdgcn_sched_barrier(0)
; template <class Epi>
; DI void gemm_phase(LAS unsigned char* lds, const Gemm g, const Epi& E, const int tid) {
;     ...
;             PG8_LDA(At, 1, 1); PG8_STAGE(PG8_SB(1, 0), b3, voffB); PG8_STAGE(PG8_SB(1, 1), b3 + hstepB, voffB); PG8_STAGE(PG8_SA(1, 0), a3, voffA);
;             PG8_WAIT_V(8); PG8_WAIT_L(0); PG8_BAR; PG8_MMA(1, 0, At, B0); PG8_MMA(1, 1, At, B1); PG8_BAR; PG8_SCHED;
	s_add_i32 s12, s12, s13
	v_lshl_add_u64 v[144:145], v[144:145], 0, s[8:9]
	s_mov_b32 m0, s12
	ds_read_b128 v[178:181], v149 offset:49152
	ds_read_b128 v[196:199], v149 offset:50176
	ds_read_b128 v[200:203], v149 offset:51200
	ds_read_b128 v[204:207], v149 offset:52224
	ds_read_b128 v[208:211], v149 offset:53248
	ds_read_b128 v[226:229], v149 offset:54272
	ds_read_b128 v[230:233], v149 offset:55296
	ds_read_b128 v[234:237], v149 offset:56320
	global_load_lds_dwordx4 v[144:145], off
	s_add_i32 m0, s12, 0x2000
	s_add_u32 s50, s50, 0x100080
	v_lshl_add_u64 v[144:145], v[182:183], 0, s[8:9]
	s_addc_u32 s51, s51, 0
	s_add_i32 s12, s68, s13
	global_load_lds_dwordx4 v[144:145], off
	v_lshl_add_u64 v[144:145], s[50:51], 0, v[0:1]
	s_mov_b32 m0, s12
	s_nop 0
	global_load_lds_dwordx4 v[144:145], off
	v_lshl_add_u64 v[144:145], s[50:51], 0, v[130:131]
	s_add_i32 m0, s12, 0x2000
	s_nop 0
	global_load_lds_dwordx4 v[144:145], off
	v_lshl_add_u64 v[144:145], s[48:49], 0, v[134:135]
	s_mov_b32 m0, s58
	s_nop 0
	global_load_lds_dwordx4 v[144:145], off
	v_lshl_add_u64 v[144:145], s[48:49], 0, v[132:133]
	s_mov_b32 m0, s59
	s_nop 0
	global_load_lds_dwordx4 v[144:145], off
	s_waitcnt vmcnt(8)
	s_waitcnt lgkmcnt(0)
	s_barrier
	s_setprio 1
	v_mfma_f32_16x16x32_bf16 v[62:65], v[140:143], v[178:181], v[62:65]
	v_mfma_f32_16x16x32_bf16 v[58:61], v[154:157], v[178:181], v[58:61]
	v_mfma_f32_16x16x32_bf16 v[54:57], v[140:143], v[200:203], v[54:57]
	v_mfma_f32_16x16x32_bf16 v[46:49], v[154:157], v[200:203], v[46:49]
	v_mfma_f32_16x16x32_bf16 v[34:37], v[140:143], v[208:211], v[34:37]
	v_mfma_f32_16x16x32_bf16 v[26:29], v[154:157], v[208:211], v[26:29]
	v_mfma_f32_16x16x32_bf16 v[22:25], v[140:143], v[230:233], v[22:25]
	v_mfma_f32_16x16x32_bf16 v[14:17], v[154:157], v[230:233], v[14:17]
	v_mfma_f32_16x16x32_bf16 v[62:65], v[150:153], v[196:199], v[62:65]
	v_mfma_f32_16x16x32_bf16 v[58:61], v[158:161], v[196:199], v[58:61]
	v_mfma_f32_16x16x32_bf16 v[54:57], v[150:153], v[204:207], v[54:57]
	v_mfma_f32_16x16x32_bf16 v[46:49], v[158:161], v[204:207], v[46:49]
	v_mfma_f32_16x16x32_bf16 v[34:37], v[150:153], v[226:229], v[34:37]
	v_mfma_f32_16x16x32_bf16 v[26:29], v[158:161], v[226:229], v[26:29]
	v_mfma_f32_16x16x32_bf16 v[22:25], v[150:153], v[234:237], v[22:25]
	v_mfma_f32_16x16x32_bf16 v[14:17], v[158:161], v[234:237], v[14:17]
	v_mfma_f32_16x16x32_bf16 v[50:53], v[162:165], v[178:181], v[50:53]
	v_mfma_f32_16x16x32_bf16 v[42:45], v[170:173], v[178:181], v[42:45]
	v_mfma_f32_16x16x32_bf16 v[38:41], v[162:165], v[200:203], v[38:41]
	v_mfma_f32_16x16x32_bf16 v[30:33], v[170:173], v[200:203], v[30:33]
	v_mfma_f32_16x16x32_bf16 v[18:21], v[162:165], v[208:211], v[18:21]
	v_mfma_f32_16x16x32_bf16 v[10:13], v[170:173], v[208:211], v[10:13]
	v_mfma_f32_16x16x32_bf16 v[6:9], v[162:165], v[230:233], v[6:9]
	v_mfma_f32_16x16x32_bf16 v[2:5], v[170:173], v[230:233], v[2:5]
	v_mfma_f32_16x16x32_bf16 v[50:53], v[166:169], v[196:199], v[50:53]
	v_mfma_f32_16x16x32_bf16 v[42:45], v[174:177], v[196:199], v[42:45]
	v_mfma_f32_16x16x32_bf16 v[38:41], v[166:169], v[204:207], v[38:41]
	v_mfma_f32_16x16x32_bf16 v[30:33], v[174:177], v[204:207], v[30:33]
	v_mfma_f32_16x16x32_bf16 v[18:21], v[166:169], v[226:229], v[18:21]
	v_mfma_f32_16x16x32_bf16 v[10:13], v[174:177], v[226:229], v[10:13]
	v_mfma_f32_16x16x32_bf16 v[6:9], v[166:169], v[234:237], v[6:9]
	v_mfma_f32_16x16x32_bf16 v[2:5], v[174:177], v[234:237], v[2:5]
	s_setprio 0
	s_barrier
	s_add_i32 s67, s67, 2
	s_add_u32 s65, s65, 0x100
	s_addc_u32 s66, s66, 0
	s_add_u32 s46, s46, 0x1000000
	s_addc_u32 s47, s47, 0
	s_cmp_gt_u32 s67, 61
	s_cbranch_scc0 .LBB0_92
	s_and_b64 vcc, exec, s[24:25]
	s_cbranch_vccz .LBB0_95
	s_barrier

; #define PG8_STAGE(bufoff, gbase, voff) do { _Pragma("unroll") for (int _i = 0; _i < 2; ++_i) \
;         __builtin_amdgcn_global_load_lds((const unsigned*)((const char*)(gbase) + (voff)[_i]), (LAS unsigned*)(lds + (bufoff) + ldsw + _i * 8192), 16, 0, 0); } while (0)
; #define PG8_LDA(dst, b, h) do { _Pragma("unroll") for (int m = 0; m < 4; ++m) _Pragma("unroll") for (int k = 0; k < 2; ++k) dst[m][k] = *(const LAS bf16x8*)(lds + PG8_SA(b, h) + aoff + m * 2048 + k * 1024); } while (0)
; #define PG8_LDB(dst, b, h) do { _Pragma("unroll") for (int n = 0; n < 2; ++n) _Pragma("unroll") for (int k = 0; k < 2; ++k) dst[n][k] = *(const LAS bf16x8*)(lds + PG8_SB(b, h) + boff + n * 2048 + k * 1024); } while (0)
; #define PG8_MMA(ai, bj, At, Bt) do { __builtin_amdgcn_s_setprio(1); _Pragma("unroll") for (int m = 0; m < 4; ++m) _Pragma("unroll") for (int n = 0; n < 2; ++n) _Pragma("unroll") for (int k = 0; k < 2; ++k) \
;         acc[ai][bj][m][n] = __builtin_amdgcn_mfma_f32_16x16x32_bf16(Bt[n][k], At[m][k], acc[ai][bj][m][n], 0, 0, 0); __builtin_amdgcn_s_setprio(0); } while (0)
; #define PG8_WAIT_V(n) asm volatile("s_waitcnt vmcnt(" #n ")" ::: "memory")
; #define PG8_WAIT_L(n) asm volatile("s_waitcnt lgkmcnt(" #n ")" ::: "memory")
; #define PG8_BAR __builtin_amdgcn_s_barrier()
; #define PG8_SCHED __builtin_amdgcn_sched_barrier(0)
; template <class Epi>
; DI void gemm_phase(LAS unsigned char* lds, const Gemm g, const Epi& E, const int tid) {
;     ...
;             PG8_LDB(B0, 0, 0); PG8_LDB(B1, 0, 1); PG8_SCHED; PG8_LDA(At, 0, 0); PG8_STAGE(PG8_SA(1, 1), a1 + hstepA, voffA);
;             PG8_WAIT_V(8); PG8_WAIT_L(0); PG8_BAR; PG8_MMA(0, 0, At, B0); PG8_MMA(0, 1, At, B1); PG8_BAR; PG8_SCHED;
;             PG8_LDA(At, 0, 1); PG8_STAGE(PG8_SB(0, 0), b2, voffB); PG8_STAGE(PG8_SB(0, 1), b2 + hstepB, voffB); PG8_STAGE(PG8_SA(0, 0), a2, voffA);
;             PG8_WAIT_V(8); PG8_WAIT_L(0); PG8_BAR; PG8_MMA(1, 0, At, B0); PG8_MMA(1, 1, At, B1); PG8_BAR; PG8_SCHED;
.LBB0_115:
	s_add_u32 s12, s48, 0xfffc0080
	s_addc_u32 s50, s49, -1
	s_add_i32 s69, 0, 0x10000
	s_cmp_eq_u32 s68, 12
	s_cselect_b32 s53, s41, s50
	s_cselect_b32 s52, s64, s12
	v_add_u32_e32 v149, s69, v147
	s_cselect_b32 s51, s43, s67
	s_cselect_b32 s50, s65, s66
	s_add_i32 s12, 0, 0x14000
	ds_read_b128 v[142:145], v149
	ds_read_b128 v[150:153], v149 offset:1024
	ds_read_b128 v[154:157], v149 offset:2048
	ds_read_b128 v[158:161], v149 offset:3072
	v_add_u32_e32 v149, s12, v147
	ds_read_b128 v[162:165], v149
	ds_read_b128 v[166:169], v149 offset:1024
	ds_read_b128 v[170:173], v149 offset:2048
	ds_read_b128 v[174:177], v149 offset:3072
	v_lshl_add_u64 v[182:183], s[48:49], 0, v[138:139]
	s_add_i32 m0, s54, 0xc000
	ds_read_b128 v[178:181], v148
	ds_read_b128 v[196:199], v148 offset:1024
	ds_read_b128 v[200:203], v148 offset:2048
	ds_read_b128 v[204:207], v148 offset:3072
	ds_read_b128 v[208:211], v148 offset:4096
	ds_read_b128 v[226:229], v148 offset:5120
	ds_read_b128 v[230:233], v148 offset:6144
	ds_read_b128 v[234:237], v148 offset:7168
	global_load_lds_dwordx4 v[182:183], off
	v_lshl_add_u64 v[182:183], s[48:49], 0, v[140:141]
	s_add_i32 m0, s54, 0xe000
	s_nop 0
	global_load_lds_dwordx4 v[182:183], off
	s_waitcnt vmcnt(8)
	s_waitcnt lgkmcnt(0)
	s_barrier
	s_setprio 1
	v_mfma_f32_16x16x32_bf16 v[126:129], v[142:145], v[178:181], v[126:129]
	v_mfma_f32_16x16x32_bf16 v[122:125], v[154:157], v[178:181], v[122:125]
	v_mfma_f32_16x16x32_bf16 v[110:113], v[142:145], v[200:203], v[110:113]
	v_mfma_f32_16x16x32_bf16 v[106:109], v[154:157], v[200:203], v[106:109]
	v_mfma_f32_16x16x32_bf16 v[94:97], v[142:145], v[208:211], v[94:97]
	v_mfma_f32_16x16x32_bf16 v[90:93], v[154:157], v[208:211], v[90:93]
	v_mfma_f32_16x16x32_bf16 v[78:81], v[142:145], v[230:233], v[78:81]
	v_mfma_f32_16x16x32_bf16 v[74:77], v[154:157], v[230:233], v[74:77]
	v_mfma_f32_16x16x32_bf16 v[126:129], v[150:153], v[196:199], v[126:129]
	v_mfma_f32_16x16x32_bf16 v[122:125], v[158:161], v[196:199], v[122:125]
	v_mfma_f32_16x16x32_bf16 v[110:113], v[150:153], v[204:207], v[110:113]
	v_mfma_f32_16x16x32_bf16 v[106:109], v[158:161], v[204:207], v[106:109]
	v_mfma_f32_16x16x32_bf16 v[94:97], v[150:153], v[226:229], v[94:97]
	v_mfma_f32_16x16x32_bf16 v[90:93], v[158:161], v[226:229], v[90:93]
	v_mfma_f32_16x16x32_bf16 v[78:81], v[150:153], v[234:237], v[78:81]
	v_mfma_f32_16x16x32_bf16 v[74:77], v[158:161], v[234:237], v[74:77]
	v_mfma_f32_16x16x32_bf16 v[118:121], v[162:165], v[178:181], v[118:121]
	v_mfma_f32_16x16x32_bf16 v[114:117], v[170:173], v[178:181], v[114:117]
	v_mfma_f32_16x16x32_bf16 v[102:105], v[162:165], v[200:203], v[102:105]
	v_mfma_f32_16x16x32_bf16 v[98:101], v[170:173], v[200:203], v[98:101]
	v_mfma_f32_16x16x32_bf16 v[86:89], v[162:165], v[208:211], v[86:89]
	v_mfma_f32_16x16x32_bf16 v[82:85], v[170:173], v[208:211], v[82:85]
	v_mfma_f32_16x16x32_bf16 v[70:73], v[162:165], v[230:233], v[70:73]
	v_mfma_f32_16x16x32_bf16 v[66:69], v[170:173], v[230:233], v[66:69]
	v_mfma_f32_16x16x32_bf16 v[118:121], v[166:169], v[196:199], v[118:121]
	v_mfma_f32_16x16x32_bf16 v[114:117], v[174:177], v[196:199], v[114:117]
	v_mfma_f32_16x16x32_bf16 v[102:105], v[166:169], v[204:207], v[102:105]
	v_mfma_f32_16x16x32_bf16 v[98:101], v[174:177], v[204:207], v[98:101]
	v_mfma_f32_16x16x32_bf16 v[86:89], v[166:169], v[226:229], v[86:89]
	v_mfma_f32_16x16x32_bf16 v[82:85], v[174:177], v[226:229], v[82:85]
	v_mfma_f32_16x16x32_bf16 v[70:73], v[166:169], v[234:237], v[70:73]
	v_mfma_f32_16x16x32_bf16 v[66:69], v[174:177], v[234:237], v[66:69]
	s_setprio 0
	s_barrier
	s_add_i32 s69, s69, s13
	v_lshl_add_u64 v[182:183], s[50:51], 0, v[134:135]
	s_mov_b32 m0, s69
	ds_read_b128 v[178:181], v148 offset:16384
	ds_read_b128 v[196:199], v148 offset:17408
	ds_read_b128 v[200:203], v148 offset:18432
	ds_read_b128 v[204:207], v148 offset:19456
	ds_read_b128 v[208:211], v148 offset:20480
	ds_read_b128 v[226:229], v148 offset:21504
	ds_read_b128 v[230:233], v148 offset:22528
	ds_read_b128 v[234:237], v148 offset:23552
	global_load_lds_dwordx4 v[182:183], off
	s_add_i32 m0, s69, 0x2000
	s_add_u32 s70, s50, 0x40000
	v_lshl_add_u64 v[186:187], s[50:51], 0, v[130:131]
	s_addc_u32 s71, s51, 0
	s_add_i32 s12, s12, s13
	global_load_lds_dwordx4 v[186:187], off
	v_lshl_add_u64 v[188:189], s[70:71], 0, v[134:135]
	s_mov_b32 m0, s12
	v_lshl_add_u64 v[212:213], s[52:53], 0, v[132:133]
	global_load_lds_dwordx4 v[188:189], off
	v_lshl_add_u64 v[188:189], s[70:71], 0, v[130:131]
	s_add_i32 m0, s12, 0x2000
	s_nop 0
	global_load_lds_dwordx4 v[188:189], off
	v_lshl_add_u64 v[188:189], s[52:53], 0, v[136:137]
	s_mov_b32 m0, s54
	s_nop 0
	global_load_lds_dwordx4 v[188:189], off
	s_mov_b32 m0, s55
	s_nop 0
	global_load_lds_dwordx4 v[212:213], off
	s_waitcnt vmcnt(8)
	s_waitcnt lgkmcnt(0)
	s_barrier
; #define PG8_STAGE(bufoff, gbase, voff) do { _Pragma("unroll") for (int _i = 0; _i < 2; ++_i) \
;         __builtin_amdgcn_global_load_lds((const unsigned*)((const char*)(gbase) + (voff)[_i]), (LAS unsigned*)(lds + (bufoff) + ldsw + _i * 8192), 16, 0, 0); } while (0)
; #define PG8_LDA(dst, b, h) do { _Pragma("unroll") for (int m = 0; m < 4; ++m) _Pragma("unroll") for (int k = 0; k < 2; ++k) dst[m][k] = *(const LAS bf16x8*)(lds + PG8_SA(b, h) + aoff + m * 2048 + k * 1024); } while (0)
; #define PG8_LDB(dst, b, h) do { _Pragma("unroll") for (int n = 0; n < 2; ++n) _Pragma("unroll") for (int k = 0; k < 2; ++k) dst[n][k] = *(const LAS bf16x8*)(lds + PG8_SB(b, h) + boff + n * 2048 + k * 1024); } while (0)
; #define PG8_MMA(ai, bj, At, Bt) do { __builtin_amdgcn_s_setprio(1); _Pragma("unroll") for (int m = 0; m < 4; ++m) _Pragma("unroll") for (int n = 0; n < 2; ++n) _Pragma("unroll") for (int k = 0; k < 2; ++k) \
;         acc[ai][bj][m][n] = __builtin_amdgcn_mfma_f32_16x16x32_bf16(Bt[n][k], At[m][k], acc[ai][bj][m][n], 0, 0, 0); __builtin_amdgcn_s_setprio(0); } while (0)
; #define PG8_WAIT_V(n) asm volatile("s_waitcnt vmcnt(" #n ")" ::: "memory")
; #define PG8_WAIT_L(n) asm volatile("s_waitcnt lgkmcnt(" #n ")" ::: "memory")
; #define PG8_BAR __builtin_amdgcn_s_barrier()
; #define PG8_SCHED __builtin_amdgcn_sched_barrier(0)
; template <class Epi>
; DI void gemm_phase(LAS unsigned char* lds, const Gemm g, const Epi& E, const int tid) {
;     ...
;             PG8_WAIT_V(8); PG8_WAIT_L(0); PG8_BAR; PG8_MMA(1, 0, At, B0); PG8_MMA(1, 1, At, B1); PG8_BAR; PG8_SCHED;
;             PG8_LDB(B0, 1, 0); PG8_LDB(B1, 1, 1); PG8_SCHED; PG8_LDA(At, 1, 0); PG8_STAGE(PG8_SA(0, 1), a2 + hstepA, voffA);
;             PG8_WAIT_V(8); PG8_WAIT_L(0); PG8_BAR; PG8_MMA(0, 0, At, B0); PG8_MMA(0, 1, At, B1); PG8_BAR; PG8_SCHED;
	s_setprio 1
	v_mfma_f32_16x16x32_bf16 v[62:65], v[142:145], v[178:181], v[62:65]
	v_mfma_f32_16x16x32_bf16 v[58:61], v[154:157], v[178:181], v[58:61]
	v_mfma_f32_16x16x32_bf16 v[46:49], v[142:145], v[200:203], v[46:49]
	v_mfma_f32_16x16x32_bf16 v[42:45], v[154:157], v[200:203], v[42:45]
	v_mfma_f32_16x16x32_bf16 v[30:33], v[142:145], v[208:211], v[30:33]
	v_mfma_f32_16x16x32_bf16 v[26:29], v[154:157], v[208:211], v[26:29]
	v_mfma_f32_16x16x32_bf16 v[14:17], v[142:145], v[230:233], v[14:17]
	v_mfma_f32_16x16x32_bf16 v[10:13], v[154:157], v[230:233], v[10:13]
	v_mfma_f32_16x16x32_bf16 v[62:65], v[150:153], v[196:199], v[62:65]
	v_mfma_f32_16x16x32_bf16 v[58:61], v[158:161], v[196:199], v[58:61]
	v_mfma_f32_16x16x32_bf16 v[46:49], v[150:153], v[204:207], v[46:49]
	v_mfma_f32_16x16x32_bf16 v[42:45], v[158:161], v[204:207], v[42:45]
	v_mfma_f32_16x16x32_bf16 v[30:33], v[150:153], v[226:229], v[30:33]
	v_mfma_f32_16x16x32_bf16 v[26:29], v[158:161], v[226:229], v[26:29]
	v_mfma_f32_16x16x32_bf16 v[14:17], v[150:153], v[234:237], v[14:17]
	v_mfma_f32_16x16x32_bf16 v[10:13], v[158:161], v[234:237], v[10:13]
	v_mfma_f32_16x16x32_bf16 v[54:57], v[162:165], v[178:181], v[54:57]
	v_mfma_f32_16x16x32_bf16 v[50:53], v[170:173], v[178:181], v[50:53]
	v_mfma_f32_16x16x32_bf16 v[38:41], v[162:165], v[200:203], v[38:41]
	v_mfma_f32_16x16x32_bf16 v[34:37], v[170:173], v[200:203], v[34:37]
	v_mfma_f32_16x16x32_bf16 v[22:25], v[162:165], v[208:211], v[22:25]
	v_mfma_f32_16x16x32_bf16 v[18:21], v[170:173], v[208:211], v[18:21]
	v_mfma_f32_16x16x32_bf16 v[6:9], v[162:165], v[230:233], v[6:9]
	v_mfma_f32_16x16x32_bf16 v[2:5], v[170:173], v[230:233], v[2:5]
	v_mfma_f32_16x16x32_bf16 v[54:57], v[166:169], v[196:199], v[54:57]
	v_mfma_f32_16x16x32_bf16 v[50:53], v[174:177], v[196:199], v[50:53]
	v_mfma_f32_16x16x32_bf16 v[38:41], v[166:169], v[204:207], v[38:41]
	v_mfma_f32_16x16x32_bf16 v[34:37], v[174:177], v[204:207], v[34:37]
	v_mfma_f32_16x16x32_bf16 v[22:25], v[166:169], v[226:229], v[22:25]
	v_mfma_f32_16x16x32_bf16 v[18:21], v[174:177], v[226:229], v[18:21]
	v_mfma_f32_16x16x32_bf16 v[6:9], v[166:169], v[234:237], v[6:9]
	v_mfma_f32_16x16x32_bf16 v[2:5], v[174:177], v[234:237], v[2:5]
	s_setprio 0
	s_barrier
	s_add_i32 s12, 0, 0x18000
	v_add_u32_e32 v149, s12, v147
	s_add_i32 s69, 0, 0x1c000
	ds_read_b128 v[142:145], v149
	ds_read_b128 v[150:153], v149 offset:1024
	ds_read_b128 v[154:157], v149 offset:2048
	ds_read_b128 v[158:161], v149 offset:3072
	v_add_u32_e32 v149, s69, v147
	ds_read_b128 v[162:165], v149
	ds_read_b128 v[166:169], v149 offset:1024
	ds_read_b128 v[170:173], v149 offset:2048
	ds_read_b128 v[174:177], v149 offset:3072
	s_add_u32 s52, s52, 0x40000
	s_addc_u32 s53, s53, 0
	s_mov_b32 m0, s56
	v_lshl_add_u64 v[214:215], s[52:53], 0, v[136:137]
	ds_read_b128 v[178:181], v148 offset:32768
	ds_read_b128 v[196:199], v148 offset:33792
	ds_read_b128 v[200:203], v148 offset:34816
	ds_read_b128 v[204:207], v148 offset:35840
	ds_read_b128 v[208:211], v148 offset:36864
	ds_read_b128 v[226:229], v148 offset:37888
	ds_read_b128 v[230:233], v148 offset:38912
	ds_read_b128 v[234:237], v148 offset:39936
	global_load_lds_dwordx4 v[214:215], off
	v_lshl_add_u64 v[214:215], s[52:53], 0, v[132:133]
	s_mov_b32 m0, s57
	s_nop 0
	global_load_lds_dwordx4 v[214:215], off
	s_waitcnt vmcnt(8)
	s_waitcnt lgkmcnt(0)
	s_barrier
	s_setprio 1
	v_mfma_f32_16x16x32_bf16 v[126:129], v[142:145], v[178:181], v[126:129]
	v_mfma_f32_16x16x32_bf16 v[122:125], v[154:157], v[178:181], v[122:125]
	v_mfma_f32_16x16x32_bf16 v[110:113], v[142:145], v[200:203], v[110:113]
	v_mfma_f32_16x16x32_bf16 v[106:109], v[154:157], v[200:203], v[106:109]
	v_mfma_f32_16x16x32_bf16 v[94:97], v[142:145], v[208:211], v[94:97]
	v_mfma_f32_16x16x32_bf16 v[90:93], v[154:157], v[208:211], v[90:93]
	v_mfma_f32_16x16x32_bf16 v[78:81], v[142:145], v[230:233], v[78:81]
	v_mfma_f32_16x16x32_bf16 v[74:77], v[154:157], v[230:233], v[74:77]
	v_mfma_f32_16x16x32_bf16 v[126:129], v[150:153], v[196:199], v[126:129]
	v_mfma_f32_16x16x32_bf16 v[122:125], v[158:161], v[196:199], v[122:125]
	v_mfma_f32_16x16x32_bf16 v[110:113], v[150:153], v[204:207], v[110:113]
	v_mfma_f32_16x16x32_bf16 v[106:109], v[158:161], v[204:207], v[106:109]
	v_mfma_f32_16x16x32_bf16 v[94:97], v[150:153], v[226:229], v[94:97]
	v_mfma_f32_16x16x32_bf16 v[90:93], v[158:161], v[226:229], v[90:93]
	v_mfma_f32_16x16x32_bf16 v[78:81], v[150:153], v[234:237], v[78:81]
	v_mfma_f32_16x16x32_bf16 v[74:77], v[158:161], v[234:237], v[74:77]
	v_mfma_f32_16x16x32_bf16 v[118:121], v[162:165], v[178:181], v[118:121]
	v_mfma_f32_16x16x32_bf16 v[114:117], v[170:173], v[178:181], v[114:117]
	v_mfma_f32_16x16x32_bf16 v[102:105], v[162:165], v[200:203], v[102:105]
	v_mfma_f32_16x16x32_bf16 v[98:101], v[170:173], v[200:203], v[98:101]
	v_mfma_f32_16x16x32_bf16 v[86:89], v[162:165], v[208:211], v[86:89]
	v_mfma_f32_16x16x32_bf16 v[82:85], v[170:173], v[208:211], v[82:85]
	v_mfma_f32_16x16x32_bf16 v[70:73], v[162:165], v[230:233], v[70:73]
	v_mfma_f32_16x16x32_bf16 v[66:69], v[170:173], v[230:233], v[66:69]
	v_mfma_f32_16x16x32_bf16 v[118:121], v[166:169], v[196:199], v[118:121]
	v_mfma_f32_16x16x32_bf16 v[114:117], v[174:177], v[196:199], v[114:117]
	v_mfma_f32_16x16x32_bf16 v[102:105], v[166:169], v[204:207], v[102:105]
	v_mfma_f32_16x16x32_bf16 v[98:101], v[174:177], v[204:207], v[98:101]
	v_mfma_f32_16x16x32_bf16 v[86:89], v[166:169], v[226:229], v[86:89]
	v_mfma_f32_16x16x32_bf16 v[82:85], v[174:177], v[226:229], v[82:85]
	v_mfma_f32_16x16x32_bf16 v[70:73], v[166:169], v[234:237], v[70:73]
	v_mfma_f32_16x16x32_bf16 v[66:69], v[174:177], v[234:237], v[66:69]
	s_setprio 0
	s_barrier
; #define PG8_STAGE(bufoff, gbase, voff) do { _Pragma("unroll") for (int _i = 0; _i < 2; ++_i) \
;         __builtin_amdgcn_global_load_lds((const unsigned*)((const char*)(gbase) + (voff)[_i]), (LAS unsigned*)(lds + (bufoff) + ldsw + _i * 8192), 16, 0, 0); } while (0)
; #define PG8_LDA(dst, b, h) do { _Pragma("unroll") for (int m = 0; m < 4; ++m) _Pragma("unroll") for (int k = 0; k < 2; ++k) dst[m][k] = *(const LAS bf16x8*)(lds + PG8_SA(b, h) + aoff + m * 2048 + k * 1024); } while (0)
; #define PG8_MMA(ai, bj, At, Bt) do { __builtin_amdgcn_s_setprio(1); _Pragma("unroll") for (int m = 0; m < 4; ++m) _Pragma("unroll") for (int n = 0; n < 2; ++n) _Pragma("unroll") for (int k = 0; k < 2; ++k) \
;         acc[ai][bj][m][n] = __builtin_amdgcn_mfma_f32_16x16x32_bf16(Bt[n][k], At[m][k], acc[ai][bj][m][n], 0, 0, 0); __builtin_amdgcn_s_setprio(0); } while (0)
; #define PG8_WAIT_V(n) asm volatile("s_waitcnt vmcnt(" #n ")" ::: "memory")
; #define PG8_WAIT_L(n) asm volatile("s_waitcnt lgkmcnt(" #n ")" ::: "memory")
; #define PG8_BAR __builtin_amdgcn_s_barrier()
; #define PG8_SCHED __builtin_amdgcn_sched_barrier(0)
; template <class Epi>
; DI void gemm_phase(LAS unsigned char* lds, const Gemm g, const Epi& E, const int tid) {
;     ...
;             PG8_LDA(At, 1, 1); PG8_STAGE(PG8_SB(1, 0), b3, voffB); PG8_STAGE(PG8_SB(1, 1), b3 + hstepB, voffB); PG8_STAGE(PG8_SA(1, 0), a3, voffA);
;             PG8_WAIT_V(8); PG8_WAIT_L(0); PG8_BAR; PG8_MMA(1, 0, At, B0); PG8_MMA(1, 1, At, B1); PG8_BAR; PG8_SCHED;
	s_add_i32 s12, s12, s13
	v_lshl_add_u64 v[182:183], v[182:183], 0, s[8:9]
	s_mov_b32 m0, s12
	ds_read_b128 v[178:181], v148 offset:49152
	ds_read_b128 v[196:199], v148 offset:50176
	ds_read_b128 v[200:203], v148 offset:51200
	ds_read_b128 v[204:207], v148 offset:52224
	ds_read_b128 v[208:211], v148 offset:53248
	ds_read_b128 v[226:229], v148 offset:54272
	ds_read_b128 v[230:233], v148 offset:55296
	ds_read_b128 v[234:237], v148 offset:56320
	global_load_lds_dwordx4 v[182:183], off
	s_add_i32 m0, s12, 0x2000
	s_add_u32 s50, s50, 0x40080
	v_lshl_add_u64 v[182:183], v[186:187], 0, s[8:9]
	s_addc_u32 s51, s51, 0
	s_add_i32 s12, s69, s13
	global_load_lds_dwordx4 v[182:183], off
	v_lshl_add_u64 v[182:183], s[50:51], 0, v[134:135]
	s_mov_b32 m0, s12
	s_nop 0
	global_load_lds_dwordx4 v[182:183], off
	v_lshl_add_u64 v[182:183], s[50:51], 0, v[130:131]
	s_add_i32 m0, s12, 0x2000
	s_nop 0
	global_load_lds_dwordx4 v[182:183], off
	v_lshl_add_u64 v[182:183], v[188:189], 0, s[8:9]
	s_mov_b32 m0, s58
	s_nop 0
	global_load_lds_dwordx4 v[182:183], off
	v_lshl_add_u64 v[182:183], v[212:213], 0, s[8:9]
	s_mov_b32 m0, s59
	s_nop 0
	global_load_lds_dwordx4 v[182:183], off
	s_waitcnt vmcnt(8)
	s_waitcnt lgkmcnt(0)
	s_barrier
	s_setprio 1
	v_mfma_f32_16x16x32_bf16 v[62:65], v[142:145], v[178:181], v[62:65]
	v_mfma_f32_16x16x32_bf16 v[58:61], v[154:157], v[178:181], v[58:61]
	v_mfma_f32_16x16x32_bf16 v[46:49], v[142:145], v[200:203], v[46:49]
	v_mfma_f32_16x16x32_bf16 v[42:45], v[154:157], v[200:203], v[42:45]
	v_mfma_f32_16x16x32_bf16 v[30:33], v[142:145], v[208:211], v[30:33]
	v_mfma_f32_16x16x32_bf16 v[26:29], v[154:157], v[208:211], v[26:29]
	v_mfma_f32_16x16x32_bf16 v[14:17], v[142:145], v[230:233], v[14:17]
	v_mfma_f32_16x16x32_bf16 v[10:13], v[154:157], v[230:233], v[10:13]
	v_mfma_f32_16x16x32_bf16 v[62:65], v[150:153], v[196:199], v[62:65]
	v_mfma_f32_16x16x32_bf16 v[58:61], v[158:161], v[196:199], v[58:61]
	v_mfma_f32_16x16x32_bf16 v[46:49], v[150:153], v[204:207], v[46:49]
	v_mfma_f32_16x16x32_bf16 v[42:45], v[158:161], v[204:207], v[42:45]
	v_mfma_f32_16x16x32_bf16 v[30:33], v[150:153], v[226:229], v[30:33]
	v_mfma_f32_16x16x32_bf16 v[26:29], v[158:161], v[226:229], v[26:29]
	v_mfma_f32_16x16x32_bf16 v[14:17], v[150:153], v[234:237], v[14:17]
	v_mfma_f32_16x16x32_bf16 v[10:13], v[158:161], v[234:237], v[10:13]
	v_mfma_f32_16x16x32_bf16 v[54:57], v[162:165], v[178:181], v[54:57]
	v_mfma_f32_16x16x32_bf16 v[50:53], v[170:173], v[178:181], v[50:53]
	v_mfma_f32_16x16x32_bf16 v[38:41], v[162:165], v[200:203], v[38:41]
	v_mfma_f32_16x16x32_bf16 v[34:37], v[170:173], v[200:203], v[34:37]
	v_mfma_f32_16x16x32_bf16 v[22:25], v[162:165], v[208:211], v[22:25]
	v_mfma_f32_16x16x32_bf16 v[18:21], v[170:173], v[208:211], v[18:21]
	v_mfma_f32_16x16x32_bf16 v[6:9], v[162:165], v[230:233], v[6:9]
	v_mfma_f32_16x16x32_bf16 v[2:5], v[170:173], v[230:233], v[2:5]
	v_mfma_f32_16x16x32_bf16 v[54:57], v[166:169], v[196:199], v[54:57]
	v_mfma_f32_16x16x32_bf16 v[50:53], v[174:177], v[196:199], v[50:53]
	v_mfma_f32_16x16x32_bf16 v[38:41], v[166:169], v[204:207], v[38:41]
	v_mfma_f32_16x16x32_bf16 v[34:37], v[174:177], v[204:207], v[34:37]
	v_mfma_f32_16x16x32_bf16 v[22:25], v[166:169], v[226:229], v[22:25]
	v_mfma_f32_16x16x32_bf16 v[18:21], v[174:177], v[226:229], v[18:21]
	v_mfma_f32_16x16x32_bf16 v[6:9], v[166:169], v[234:237], v[6:9]
	v_mfma_f32_16x16x32_bf16 v[2:5], v[174:177], v[234:237], v[2:5]
	s_setprio 0
	s_barrier
	s_add_i32 s68, s68, 2
	s_add_u32 s48, s48, 0x100
	s_addc_u32 s49, s49, 0
	s_add_u32 s66, s66, 0x100
	s_addc_u32 s67, s67, 0
	s_cmp_gt_u32 s68, 13
	s_cbranch_scc0 .LBB0_115
	s_and_b64 vcc, exec, s[34:35]
	s_cbranch_vccz .LBB0_118
	s_barrier

; #define PG8_STAGE(bufoff, gbase, voff) do { _Pragma("unroll") for (int _i = 0; _i < 2; ++_i) \
;         __builtin_amdgcn_global_load_lds((const unsigned*)((const char*)(gbase) + (voff)[_i]), (LAS unsigned*)(lds + (bufoff) + ldsw + _i * 8192), 16, 0, 0); } while (0)
; #define PG8_LDA(dst, b, h) do { _Pragma("unroll") for (int m = 0; m < 4; ++m) _Pragma("unroll") for (int k = 0; k < 2; ++k) dst[m][k] = *(const LAS bf16x8*)(lds + PG8_SA(b, h) + aoff + m * 2048 + k * 1024); } while (0)
; #define PG8_LDB(dst, b, h) do { _Pragma("unroll") for (int n = 0; n < 2; ++n) _Pragma("unroll") for (int k = 0; k < 2; ++k) dst[n][k] = *(const LAS bf16x8*)(lds + PG8_SB(b, h) + boff + n * 2048 + k * 1024); } while (0)
; #define PG8_MMA(ai, bj, At, Bt) do { __builtin_amdgcn_s_setprio(1); _Pragma("unroll") for (int m = 0; m < 4; ++m) _Pragma("unroll") for (int n = 0; n < 2; ++n) _Pragma("unroll") for (int k = 0; k < 2; ++k) \
;         acc[ai][bj][m][n] = __builtin_amdgcn_mfma_f32_16x16x32_bf16(Bt[n][k], At[m][k], acc[ai][bj][m][n], 0, 0, 0); __builtin_amdgcn_s_setprio(0); } while (0)
; #define PG8_WAIT_V(n) asm volatile("s_waitcnt vmcnt(" #n ")" ::: "memory")
; #define PG8_WAIT_L(n) asm volatile("s_waitcnt lgkmcnt(" #n ")" ::: "memory")
; #define PG8_BAR __builtin_amdgcn_s_barrier()
; #define PG8_SCHED __builtin_amdgcn_sched_barrier(0)
; template <class Epi>
; DI void gemm_phase(LAS unsigned char* lds, const Gemm g, const Epi& E, const int tid) {
;     ...
;             PG8_LDB(B0, 0, 0); PG8_LDB(B1, 0, 1); PG8_SCHED; PG8_LDA(At, 0, 0); PG8_STAGE(PG8_SA(1, 1), a1 + hstepA, voffA);
;             PG8_WAIT_V(8); PG8_WAIT_L(0); PG8_BAR; PG8_MMA(0, 0, At, B0); PG8_MMA(0, 1, At, B1); PG8_BAR; PG8_SCHED;
;             PG8_LDA(At, 0, 1); PG8_STAGE(PG8_SB(0, 0), b2, voffB); PG8_STAGE(PG8_SB(0, 1), b2 + hstepB, voffB); PG8_STAGE(PG8_SA(0, 0), a2, voffA);
;             PG8_WAIT_V(8); PG8_WAIT_L(0); PG8_BAR; PG8_MMA(1, 0, At, B0); PG8_MMA(1, 1, At, B1); PG8_BAR; PG8_SCHED;
.LBB0_150:
	s_add_u32 s12, s48, 0xfffc0080
	s_addc_u32 s50, s49, -1
	s_add_i32 s69, 0, 0x10000
	s_cmp_eq_u32 s68, 12
	s_cselect_b32 s53, s41, s50
	s_cselect_b32 s52, s64, s12
	v_add_u32_e32 v140, s69, v143
	s_cselect_b32 s51, s43, s67
	s_cselect_b32 s50, s65, s66
	s_add_i32 s12, 0, 0x14000
	ds_read_b128 v[136:139], v140
	ds_read_b128 v[146:149], v140 offset:1024
	ds_read_b128 v[150:153], v140 offset:2048
	ds_read_b128 v[154:157], v140 offset:3072
	v_add_u32_e32 v140, s12, v143
	ds_read_b128 v[158:161], v140
	ds_read_b128 v[162:165], v140 offset:1024
	ds_read_b128 v[166:169], v140 offset:2048
	ds_read_b128 v[170:173], v140 offset:3072
	v_lshl_add_u64 v[140:141], s[48:49], 0, v[132:133]
	s_add_i32 m0, s55, 0xc000
	ds_read_b128 v[174:177], v145
	ds_read_b128 v[178:181], v145 offset:1024
	ds_read_b128 v[186:189], v145 offset:2048
	ds_read_b128 v[196:199], v145 offset:3072
	ds_read_b128 v[200:203], v145 offset:4096
	ds_read_b128 v[204:207], v145 offset:5120
	ds_read_b128 v[208:211], v145 offset:6144
	ds_read_b128 v[212:215], v145 offset:7168
	global_load_lds_dwordx4 v[140:141], off
	v_lshl_add_u64 v[140:141], s[48:49], 0, v[134:135]
	s_add_i32 m0, s55, 0xe000
	s_nop 0
	global_load_lds_dwordx4 v[140:141], off
	s_waitcnt vmcnt(8)
	s_waitcnt lgkmcnt(0)
	s_barrier
	s_setprio 1
	v_mfma_f32_16x16x32_bf16 v[126:129], v[136:139], v[174:177], v[126:129]
	v_mfma_f32_16x16x32_bf16 v[122:125], v[150:153], v[174:177], v[122:125]
	v_mfma_f32_16x16x32_bf16 v[118:121], v[136:139], v[186:189], v[118:121]
	v_mfma_f32_16x16x32_bf16 v[110:113], v[150:153], v[186:189], v[110:113]
	v_mfma_f32_16x16x32_bf16 v[94:97], v[136:139], v[200:203], v[94:97]
	v_mfma_f32_16x16x32_bf16 v[90:93], v[150:153], v[200:203], v[90:93]
	v_mfma_f32_16x16x32_bf16 v[86:89], v[136:139], v[208:211], v[86:89]
	v_mfma_f32_16x16x32_bf16 v[78:81], v[150:153], v[208:211], v[78:81]
	v_mfma_f32_16x16x32_bf16 v[126:129], v[146:149], v[178:181], v[126:129]
	v_mfma_f32_16x16x32_bf16 v[122:125], v[154:157], v[178:181], v[122:125]
	v_mfma_f32_16x16x32_bf16 v[118:121], v[146:149], v[196:199], v[118:121]
	v_mfma_f32_16x16x32_bf16 v[110:113], v[154:157], v[196:199], v[110:113]
	v_mfma_f32_16x16x32_bf16 v[94:97], v[146:149], v[204:207], v[94:97]
	v_mfma_f32_16x16x32_bf16 v[90:93], v[154:157], v[204:207], v[90:93]
	v_mfma_f32_16x16x32_bf16 v[86:89], v[146:149], v[212:215], v[86:89]
	v_mfma_f32_16x16x32_bf16 v[78:81], v[154:157], v[212:215], v[78:81]
	v_mfma_f32_16x16x32_bf16 v[114:117], v[158:161], v[174:177], v[114:117]
	v_mfma_f32_16x16x32_bf16 v[106:109], v[166:169], v[174:177], v[106:109]
	v_mfma_f32_16x16x32_bf16 v[102:105], v[158:161], v[186:189], v[102:105]
	v_mfma_f32_16x16x32_bf16 v[98:101], v[166:169], v[186:189], v[98:101]
	v_mfma_f32_16x16x32_bf16 v[82:85], v[158:161], v[200:203], v[82:85]
	v_mfma_f32_16x16x32_bf16 v[74:77], v[166:169], v[200:203], v[74:77]
	v_mfma_f32_16x16x32_bf16 v[70:73], v[158:161], v[208:211], v[70:73]
	v_mfma_f32_16x16x32_bf16 v[66:69], v[166:169], v[208:211], v[66:69]
	v_mfma_f32_16x16x32_bf16 v[114:117], v[162:165], v[178:181], v[114:117]
	v_mfma_f32_16x16x32_bf16 v[106:109], v[170:173], v[178:181], v[106:109]
	v_mfma_f32_16x16x32_bf16 v[102:105], v[162:165], v[196:199], v[102:105]
	v_mfma_f32_16x16x32_bf16 v[98:101], v[170:173], v[196:199], v[98:101]
	v_mfma_f32_16x16x32_bf16 v[82:85], v[162:165], v[204:207], v[82:85]
	v_mfma_f32_16x16x32_bf16 v[74:77], v[170:173], v[204:207], v[74:77]
	v_mfma_f32_16x16x32_bf16 v[70:73], v[162:165], v[212:215], v[70:73]
	v_mfma_f32_16x16x32_bf16 v[66:69], v[170:173], v[212:215], v[66:69]
	s_setprio 0
	s_barrier
	s_add_i32 s69, s69, s54
	v_lshl_add_u64 v[140:141], s[50:51], 0, v[0:1]
	s_mov_b32 m0, s69
	ds_read_b128 v[174:177], v145 offset:16384
	ds_read_b128 v[178:181], v145 offset:17408
	ds_read_b128 v[186:189], v145 offset:18432
	ds_read_b128 v[196:199], v145 offset:19456
	ds_read_b128 v[200:203], v145 offset:20480
	ds_read_b128 v[204:207], v145 offset:21504
	ds_read_b128 v[208:211], v145 offset:22528
	ds_read_b128 v[212:215], v145 offset:23552
	global_load_lds_dwordx4 v[140:141], off
	s_add_i32 m0, s69, 0x2000
	s_add_u32 s70, s50, 0x40000
	v_lshl_add_u64 v[182:183], s[50:51], 0, v[130:131]
	s_addc_u32 s71, s51, 0
	s_add_i32 s12, s12, s54
	global_load_lds_dwordx4 v[182:183], off
	v_lshl_add_u64 v[192:193], s[70:71], 0, v[0:1]
	s_mov_b32 m0, s12
	v_lshl_add_u64 v[216:217], s[52:53], 0, v[130:131]
	global_load_lds_dwordx4 v[192:193], off
	v_lshl_add_u64 v[192:193], s[70:71], 0, v[130:131]
	s_add_i32 m0, s12, 0x2000
	s_nop 0
	global_load_lds_dwordx4 v[192:193], off
	v_lshl_add_u64 v[192:193], s[52:53], 0, v[0:1]
	s_mov_b32 m0, s55
	s_nop 0
	global_load_lds_dwordx4 v[192:193], off
	s_mov_b32 m0, s56
	s_nop 0
	global_load_lds_dwordx4 v[216:217], off
	s_waitcnt vmcnt(8)
	s_waitcnt lgkmcnt(0)
	s_barrier
; #define PG8_STAGE(bufoff, gbase, voff) do { _Pragma("unroll") for (int _i = 0; _i < 2; ++_i) \
;         __builtin_amdgcn_global_load_lds((const unsigned*)((const char*)(gbase) + (voff)[_i]), (LAS unsigned*)(lds + (bufoff) + ldsw + _i * 8192), 16, 0, 0); } while (0)
; #define PG8_LDA(dst, b, h) do { _Pragma("unroll") for (int m = 0; m < 4; ++m) _Pragma("unroll") for (int k = 0; k < 2; ++k) dst[m][k] = *(const LAS bf16x8*)(lds + PG8_SA(b, h) + aoff + m * 2048 + k * 1024); } while (0)
; #define PG8_LDB(dst, b, h) do { _Pragma("unroll") for (int n = 0; n < 2; ++n) _Pragma("unroll") for (int k = 0; k < 2; ++k) dst[n][k] = *(const LAS bf16x8*)(lds + PG8_SB(b, h) + boff + n * 2048 + k * 1024); } while (0)
; #define PG8_MMA(ai, bj, At, Bt) do { __builtin_amdgcn_s_setprio(1); _Pragma("unroll") for (int m = 0; m < 4; ++m) _Pragma("unroll") for (int n = 0; n < 2; ++n) _Pragma("unroll") for (int k = 0; k < 2; ++k) \
;         acc[ai][bj][m][n] = __builtin_amdgcn_mfma_f32_16x16x32_bf16(Bt[n][k], At[m][k], acc[ai][bj][m][n], 0, 0, 0); __builtin_amdgcn_s_setprio(0); } while (0)
; #define PG8_WAIT_V(n) asm volatile("s_waitcnt vmcnt(" #n ")" ::: "memory")
; #define PG8_WAIT_L(n) asm volatile("s_waitcnt lgkmcnt(" #n ")" ::: "memory")
; #define PG8_BAR __builtin_amdgcn_s_barrier()
; #define PG8_SCHED __builtin_amdgcn_sched_barrier(0)
; template <class Epi>
; DI void gemm_phase(LAS unsigned char* lds, const Gemm g, const Epi& E, const int tid) {
;     ...
;             PG8_WAIT_V(8); PG8_WAIT_L(0); PG8_BAR; PG8_MMA(1, 0, At, B0); PG8_MMA(1, 1, At, B1); PG8_BAR; PG8_SCHED;
;             PG8_LDB(B0, 1, 0); PG8_LDB(B1, 1, 1); PG8_SCHED; PG8_LDA(At, 1, 0); PG8_STAGE(PG8_SA(0, 1), a2 + hstepA, voffA);
;             PG8_WAIT_V(8); PG8_WAIT_L(0); PG8_BAR; PG8_MMA(0, 0, At, B0); PG8_MMA(0, 1, At, B1); PG8_BAR; PG8_SCHED;
	s_setprio 1
	v_mfma_f32_16x16x32_bf16 v[62:65], v[136:139], v[174:177], v[62:65]
	v_mfma_f32_16x16x32_bf16 v[58:61], v[150:153], v[174:177], v[58:61]
	v_mfma_f32_16x16x32_bf16 v[54:57], v[136:139], v[186:189], v[54:57]
	v_mfma_f32_16x16x32_bf16 v[46:49], v[150:153], v[186:189], v[46:49]
	v_mfma_f32_16x16x32_bf16 v[34:37], v[136:139], v[200:203], v[34:37]
	v_mfma_f32_16x16x32_bf16 v[26:29], v[150:153], v[200:203], v[26:29]
	v_mfma_f32_16x16x32_bf16 v[22:25], v[136:139], v[208:211], v[22:25]
	v_mfma_f32_16x16x32_bf16 v[14:17], v[150:153], v[208:211], v[14:17]
	v_mfma_f32_16x16x32_bf16 v[62:65], v[146:149], v[178:181], v[62:65]
	v_mfma_f32_16x16x32_bf16 v[58:61], v[154:157], v[178:181], v[58:61]
	v_mfma_f32_16x16x32_bf16 v[54:57], v[146:149], v[196:199], v[54:57]
	v_mfma_f32_16x16x32_bf16 v[46:49], v[154:157], v[196:199], v[46:49]
	v_mfma_f32_16x16x32_bf16 v[34:37], v[146:149], v[204:207], v[34:37]
	v_mfma_f32_16x16x32_bf16 v[26:29], v[154:157], v[204:207], v[26:29]
	v_mfma_f32_16x16x32_bf16 v[22:25], v[146:149], v[212:215], v[22:25]
	v_mfma_f32_16x16x32_bf16 v[14:17], v[154:157], v[212:215], v[14:17]
	v_mfma_f32_16x16x32_bf16 v[50:53], v[158:161], v[174:177], v[50:53]
	v_mfma_f32_16x16x32_bf16 v[42:45], v[166:169], v[174:177], v[42:45]
	v_mfma_f32_16x16x32_bf16 v[38:41], v[158:161], v[186:189], v[38:41]
	v_mfma_f32_16x16x32_bf16 v[30:33], v[166:169], v[186:189], v[30:33]
	v_mfma_f32_16x16x32_bf16 v[18:21], v[158:161], v[200:203], v[18:21]
	v_mfma_f32_16x16x32_bf16 v[10:13], v[166:169], v[200:203], v[10:13]
	v_mfma_f32_16x16x32_bf16 v[6:9], v[158:161], v[208:211], v[6:9]
	v_mfma_f32_16x16x32_bf16 v[2:5], v[166:169], v[208:211], v[2:5]
	v_mfma_f32_16x16x32_bf16 v[50:53], v[162:165], v[178:181], v[50:53]
	v_mfma_f32_16x16x32_bf16 v[42:45], v[170:173], v[178:181], v[42:45]
	v_mfma_f32_16x16x32_bf16 v[38:41], v[162:165], v[196:199], v[38:41]
	v_mfma_f32_16x16x32_bf16 v[30:33], v[170:173], v[196:199], v[30:33]
	v_mfma_f32_16x16x32_bf16 v[18:21], v[162:165], v[204:207], v[18:21]
	v_mfma_f32_16x16x32_bf16 v[10:13], v[170:173], v[204:207], v[10:13]
	v_mfma_f32_16x16x32_bf16 v[6:9], v[162:165], v[212:215], v[6:9]
	v_mfma_f32_16x16x32_bf16 v[2:5], v[170:173], v[212:215], v[2:5]
	s_setprio 0
	s_barrier
	s_add_i32 s12, 0, 0x18000
	s_add_i32 s69, 0, 0x1c000
	v_add_u32_e32 v154, s12, v143
	v_add_u32_e32 v170, s69, v143
	ds_read_b128 v[136:139], v154
	ds_read_b128 v[146:149], v154 offset:1024
	ds_read_b128 v[150:153], v154 offset:2048
	ds_read_b128 v[154:157], v154 offset:3072
	ds_read_b128 v[158:161], v170
	ds_read_b128 v[162:165], v170 offset:1024
	ds_read_b128 v[166:169], v170 offset:2048
	ds_read_b128 v[170:173], v170 offset:3072
	s_add_u32 s52, s52, 0x40000
	s_addc_u32 s53, s53, 0
	s_mov_b32 m0, s57
	v_lshl_add_u64 v[228:229], s[52:53], 0, v[0:1]
	ds_read_b128 v[174:177], v145 offset:32768
	ds_read_b128 v[178:181], v145 offset:33792
	ds_read_b128 v[186:189], v145 offset:34816
	ds_read_b128 v[196:199], v145 offset:35840
	ds_read_b128 v[200:203], v145 offset:36864
	ds_read_b128 v[204:207], v145 offset:37888
	ds_read_b128 v[208:211], v145 offset:38912
	ds_read_b128 v[212:215], v145 offset:39936
	global_load_lds_dwordx4 v[228:229], off
	v_lshl_add_u64 v[228:229], s[52:53], 0, v[130:131]
	s_mov_b32 m0, s58
	s_nop 0
	global_load_lds_dwordx4 v[228:229], off
	s_waitcnt vmcnt(8)
	s_waitcnt lgkmcnt(0)
	s_barrier
	s_setprio 1
	v_mfma_f32_16x16x32_bf16 v[126:129], v[136:139], v[174:177], v[126:129]
	v_mfma_f32_16x16x32_bf16 v[122:125], v[150:153], v[174:177], v[122:125]
	v_mfma_f32_16x16x32_bf16 v[118:121], v[136:139], v[186:189], v[118:121]
	v_mfma_f32_16x16x32_bf16 v[110:113], v[150:153], v[186:189], v[110:113]
	v_mfma_f32_16x16x32_bf16 v[94:97], v[136:139], v[200:203], v[94:97]
	v_mfma_f32_16x16x32_bf16 v[90:93], v[150:153], v[200:203], v[90:93]
	v_mfma_f32_16x16x32_bf16 v[86:89], v[136:139], v[208:211], v[86:89]
	v_mfma_f32_16x16x32_bf16 v[78:81], v[150:153], v[208:211], v[78:81]
	v_mfma_f32_16x16x32_bf16 v[126:129], v[146:149], v[178:181], v[126:129]
	v_mfma_f32_16x16x32_bf16 v[122:125], v[154:157], v[178:181], v[122:125]
	v_mfma_f32_16x16x32_bf16 v[118:121], v[146:149], v[196:199], v[118:121]
	v_mfma_f32_16x16x32_bf16 v[110:113], v[154:157], v[196:199], v[110:113]
	v_mfma_f32_16x16x32_bf16 v[94:97], v[146:149], v[204:207], v[94:97]
	v_mfma_f32_16x16x32_bf16 v[90:93], v[154:157], v[204:207], v[90:93]
	v_mfma_f32_16x16x32_bf16 v[86:89], v[146:149], v[212:215], v[86:89]
	v_mfma_f32_16x16x32_bf16 v[78:81], v[154:157], v[212:215], v[78:81]
	v_mfma_f32_16x16x32_bf16 v[114:117], v[158:161], v[174:177], v[114:117]
	v_mfma_f32_16x16x32_bf16 v[106:109], v[166:169], v[174:177], v[106:109]
	v_mfma_f32_16x16x32_bf16 v[102:105], v[158:161], v[186:189], v[102:105]
	v_mfma_f32_16x16x32_bf16 v[98:101], v[166:169], v[186:189], v[98:101]
	v_mfma_f32_16x16x32_bf16 v[82:85], v[158:161], v[200:203], v[82:85]
	v_mfma_f32_16x16x32_bf16 v[74:77], v[166:169], v[200:203], v[74:77]
	v_mfma_f32_16x16x32_bf16 v[70:73], v[158:161], v[208:211], v[70:73]
	v_mfma_f32_16x16x32_bf16 v[66:69], v[166:169], v[208:211], v[66:69]
	v_mfma_f32_16x16x32_bf16 v[114:117], v[162:165], v[178:181], v[114:117]
	v_mfma_f32_16x16x32_bf16 v[106:109], v[170:173], v[178:181], v[106:109]
	v_mfma_f32_16x16x32_bf16 v[102:105], v[162:165], v[196:199], v[102:105]
	v_mfma_f32_16x16x32_bf16 v[98:101], v[170:173], v[196:199], v[98:101]
	v_mfma_f32_16x16x32_bf16 v[82:85], v[162:165], v[204:207], v[82:85]
	v_mfma_f32_16x16x32_bf16 v[74:77], v[170:173], v[204:207], v[74:77]
	v_mfma_f32_16x16x32_bf16 v[70:73], v[162:165], v[212:215], v[70:73]
	v_mfma_f32_16x16x32_bf16 v[66:69], v[170:173], v[212:215], v[66:69]
	s_setprio 0
	s_barrier
; #define PG8_STAGE(bufoff, gbase, voff) do { _Pragma("unroll") for (int _i = 0; _i < 2; ++_i) \
;         __builtin_amdgcn_global_load_lds((const unsigned*)((const char*)(gbase) + (voff)[_i]), (LAS unsigned*)(lds + (bufoff) + ldsw + _i * 8192), 16, 0, 0); } while (0)
; #define PG8_LDA(dst, b, h) do { _Pragma("unroll") for (int m = 0; m < 4; ++m) _Pragma("unroll") for (int k = 0; k < 2; ++k) dst[m][k] = *(const LAS bf16x8*)(lds + PG8_SA(b, h) + aoff + m * 2048 + k * 1024); } while (0)
; #define PG8_MMA(ai, bj, At, Bt) do { __builtin_amdgcn_s_setprio(1); _Pragma("unroll") for (int m = 0; m < 4; ++m) _Pragma("unroll") for (int n = 0; n < 2; ++n) _Pragma("unroll") for (int k = 0; k < 2; ++k) \
;         acc[ai][bj][m][n] = __builtin_amdgcn_mfma_f32_16x16x32_bf16(Bt[n][k], At[m][k], acc[ai][bj][m][n], 0, 0, 0); __builtin_amdgcn_s_setprio(0); } while (0)
; #define PG8_WAIT_V(n) asm volatile("s_waitcnt vmcnt(" #n ")" ::: "memory")
; #define PG8_WAIT_L(n) asm volatile("s_waitcnt lgkmcnt(" #n ")" ::: "memory")
; #define PG8_BAR __builtin_amdgcn_s_barrier()
; #define PG8_SCHED __builtin_amdgcn_sched_barrier(0)
; template <class Epi>
; DI void gemm_phase(LAS unsigned char* lds, const Gemm g, const Epi& E, const int tid) {
;     ...
;             PG8_LDA(At, 1, 1); PG8_STAGE(PG8_SB(1, 0), b3, voffB); PG8_STAGE(PG8_SB(1, 1), b3 + hstepB, voffB); PG8_STAGE(PG8_SA(1, 0), a3, voffA);
;             PG8_WAIT_V(8); PG8_WAIT_L(0); PG8_BAR; PG8_MMA(1, 0, At, B0); PG8_MMA(1, 1, At, B1); PG8_BAR; PG8_SCHED;
	s_add_i32 s12, s12, s54
	v_lshl_add_u64 v[140:141], v[140:141], 0, s[8:9]
	s_mov_b32 m0, s12
	ds_read_b128 v[174:177], v145 offset:49152
	ds_read_b128 v[178:181], v145 offset:50176
	ds_read_b128 v[186:189], v145 offset:51200
	ds_read_b128 v[196:199], v145 offset:52224
	ds_read_b128 v[200:203], v145 offset:53248
	ds_read_b128 v[204:207], v145 offset:54272
	ds_read_b128 v[208:211], v145 offset:55296
	ds_read_b128 v[212:215], v145 offset:56320
	global_load_lds_dwordx4 v[140:141], off
	s_add_i32 m0, s12, 0x2000
	s_add_u32 s50, s50, 0x40080
	v_lshl_add_u64 v[140:141], v[182:183], 0, s[8:9]
	s_addc_u32 s51, s51, 0
	s_add_i32 s12, s69, s54
	global_load_lds_dwordx4 v[140:141], off
	v_lshl_add_u64 v[140:141], s[50:51], 0, v[0:1]
	s_mov_b32 m0, s12
	s_nop 0
	global_load_lds_dwordx4 v[140:141], off
	v_lshl_add_u64 v[140:141], s[50:51], 0, v[130:131]
	s_add_i32 m0, s12, 0x2000
	s_nop 0
	global_load_lds_dwordx4 v[140:141], off
	v_lshl_add_u64 v[140:141], v[192:193], 0, s[8:9]
	s_mov_b32 m0, s59
	s_nop 0
	global_load_lds_dwordx4 v[140:141], off
	v_lshl_add_u64 v[140:141], v[216:217], 0, s[8:9]
	s_mov_b32 m0, s60
	s_nop 0
	global_load_lds_dwordx4 v[140:141], off
	s_waitcnt vmcnt(8)
	s_waitcnt lgkmcnt(0)
	s_barrier
	s_setprio 1
	v_mfma_f32_16x16x32_bf16 v[62:65], v[136:139], v[174:177], v[62:65]
	v_mfma_f32_16x16x32_bf16 v[58:61], v[150:153], v[174:177], v[58:61]
	v_mfma_f32_16x16x32_bf16 v[54:57], v[136:139], v[186:189], v[54:57]
	v_mfma_f32_16x16x32_bf16 v[46:49], v[150:153], v[186:189], v[46:49]
	v_mfma_f32_16x16x32_bf16 v[34:37], v[136:139], v[200:203], v[34:37]
	v_mfma_f32_16x16x32_bf16 v[26:29], v[150:153], v[200:203], v[26:29]
	v_mfma_f32_16x16x32_bf16 v[22:25], v[136:139], v[208:211], v[22:25]
	v_mfma_f32_16x16x32_bf16 v[14:17], v[150:153], v[208:211], v[14:17]
	v_mfma_f32_16x16x32_bf16 v[62:65], v[146:149], v[178:181], v[62:65]
	v_mfma_f32_16x16x32_bf16 v[58:61], v[154:157], v[178:181], v[58:61]
	v_mfma_f32_16x16x32_bf16 v[54:57], v[146:149], v[196:199], v[54:57]
	v_mfma_f32_16x16x32_bf16 v[46:49], v[154:157], v[196:199], v[46:49]
	v_mfma_f32_16x16x32_bf16 v[34:37], v[146:149], v[204:207], v[34:37]
	v_mfma_f32_16x16x32_bf16 v[26:29], v[154:157], v[204:207], v[26:29]
	v_mfma_f32_16x16x32_bf16 v[22:25], v[146:149], v[212:215], v[22:25]
	v_mfma_f32_16x16x32_bf16 v[14:17], v[154:157], v[212:215], v[14:17]
	v_mfma_f32_16x16x32_bf16 v[50:53], v[158:161], v[174:177], v[50:53]
	v_mfma_f32_16x16x32_bf16 v[42:45], v[166:169], v[174:177], v[42:45]
	v_mfma_f32_16x16x32_bf16 v[38:41], v[158:161], v[186:189], v[38:41]
	v_mfma_f32_16x16x32_bf16 v[30:33], v[166:169], v[186:189], v[30:33]
	v_mfma_f32_16x16x32_bf16 v[18:21], v[158:161], v[200:203], v[18:21]
	v_mfma_f32_16x16x32_bf16 v[10:13], v[166:169], v[200:203], v[10:13]
	v_mfma_f32_16x16x32_bf16 v[6:9], v[158:161], v[208:211], v[6:9]
	v_mfma_f32_16x16x32_bf16 v[2:5], v[166:169], v[208:211], v[2:5]
	v_mfma_f32_16x16x32_bf16 v[50:53], v[162:165], v[178:181], v[50:53]
	v_mfma_f32_16x16x32_bf16 v[42:45], v[170:173], v[178:181], v[42:45]
	v_mfma_f32_16x16x32_bf16 v[38:41], v[162:165], v[196:199], v[38:41]
	v_mfma_f32_16x16x32_bf16 v[30:33], v[170:173], v[196:199], v[30:33]
	v_mfma_f32_16x16x32_bf16 v[18:21], v[162:165], v[204:207], v[18:21]
	v_mfma_f32_16x16x32_bf16 v[10:13], v[170:173], v[204:207], v[10:13]
	v_mfma_f32_16x16x32_bf16 v[6:9], v[162:165], v[212:215], v[6:9]
	v_mfma_f32_16x16x32_bf16 v[2:5], v[170:173], v[212:215], v[2:5]
	s_setprio 0
	s_barrier
	s_add_i32 s68, s68, 2
	s_add_u32 s48, s48, 0x100
	s_addc_u32 s49, s49, 0
	s_add_u32 s66, s66, 0x100
	s_addc_u32 s67, s67, 0
	s_cmp_gt_u32 s68, 13
	s_cbranch_scc0 .LBB0_150
	s_and_b64 vcc, exec, s[34:35]
	s_cbranch_vccz .LBB0_153
	s_barrier

; #define PG8_STAGE(bufoff, gbase, voff) do { _Pragma("unroll") for (int _i = 0; _i < 2; ++_i) \
;         __builtin_amdgcn_global_load_lds((const unsigned*)((const char*)(gbase) + (voff)[_i]), (LAS unsigned*)(lds + (bufoff) + ldsw + _i * 8192), 16, 0, 0); } while (0)
; #define PG8_LDA(dst, b, h) do { _Pragma("unroll") for (int m = 0; m < 4; ++m) _Pragma("unroll") for (int k = 0; k < 2; ++k) dst[m][k] = *(const LAS bf16x8*)(lds + PG8_SA(b, h) + aoff + m * 2048 + k * 1024); } while (0)
; #define PG8_LDB(dst, b, h) do { _Pragma("unroll") for (int n = 0; n < 2; ++n) _Pragma("unroll") for (int k = 0; k < 2; ++k) dst[n][k] = *(const LAS bf16x8*)(lds + PG8_SB(b, h) + boff + n * 2048 + k * 1024); } while (0)
; #define PG8_MMA(ai, bj, At, Bt) do { __builtin_amdgcn_s_setprio(1); _Pragma("unroll") for (int m = 0; m < 4; ++m) _Pragma("unroll") for (int n = 0; n < 2; ++n) _Pragma("unroll") for (int k = 0; k < 2; ++k) \
;         acc[ai][bj][m][n] = __builtin_amdgcn_mfma_f32_16x16x32_bf16(Bt[n][k], At[m][k], acc[ai][bj][m][n], 0, 0, 0); __builtin_amdgcn_s_setprio(0); } while (0)
; #define PG8_WAIT_V(n) asm volatile("s_waitcnt vmcnt(" #n ")" ::: "memory")
; #define PG8_WAIT_L(n) asm volatile("s_waitcnt lgkmcnt(" #n ")" ::: "memory")
; #define PG8_BAR __builtin_amdgcn_s_barrier()
; #define PG8_SCHED __builtin_amdgcn_sched_barrier(0)
; template <class Epi>
; DI void gemm_phase(LAS unsigned char* lds, const Gemm g, const Epi& E, const int tid) {
;     ...
;             PG8_LDB(B0, 0, 0); PG8_LDB(B1, 0, 1); PG8_SCHED; PG8_LDA(At, 0, 0); PG8_STAGE(PG8_SA(1, 1), a1 + hstepA, voffA);
;             PG8_WAIT_V(8); PG8_WAIT_L(0); PG8_BAR; PG8_MMA(0, 0, At, B0); PG8_MMA(0, 1, At, B1); PG8_BAR; PG8_SCHED;
;             PG8_LDA(At, 0, 1); PG8_STAGE(PG8_SB(0, 0), b2, voffB); PG8_STAGE(PG8_SB(0, 1), b2 + hstepB, voffB); PG8_STAGE(PG8_SA(0, 0), a2, voffA);
;             PG8_WAIT_V(8); PG8_WAIT_L(0); PG8_BAR; PG8_MMA(1, 0, At, B0); PG8_MMA(1, 1, At, B1); PG8_BAR; PG8_SCHED;
.LBB0_172:
	s_add_u32 s12, s44, 0xfffc0080
	s_addc_u32 s46, s45, -1
	s_add_i32 s67, 0, 0x10000
	s_cmp_eq_u32 s66, 12
	s_cselect_b32 s49, s25, s46
	s_cselect_b32 s48, s62, s12
	s_cselect_b32 s47, s35, s65
	s_cselect_b32 s46, s63, s64
	s_add_i32 s12, 0, 0x14000
	v_add_u32_e32 v148, s67, v173
	v_add_u32_e32 v164, s12, v173
	ds_read_b128 v[136:139], v148
	ds_read_b128 v[140:143], v148 offset:1024
	ds_read_b128 v[144:147], v148 offset:2048
	ds_read_b128 v[148:151], v148 offset:3072
	ds_read_b128 v[152:155], v164
	ds_read_b128 v[156:159], v164 offset:1024
	ds_read_b128 v[160:163], v164 offset:2048
	ds_read_b128 v[164:167], v164 offset:3072
	v_lshl_add_u64 v[192:193], s[44:45], 0, v[132:133]
	s_add_i32 m0, s53, 0xc000
	ds_read_b128 v[168:171], v175
	ds_read_b128 v[176:179], v175 offset:1024
	ds_read_b128 v[180:183], v175 offset:2048
	ds_read_b128 v[186:189], v175 offset:3072
	ds_read_b128 v[196:199], v175 offset:4096
	ds_read_b128 v[200:203], v175 offset:5120
	ds_read_b128 v[204:207], v175 offset:6144
	ds_read_b128 v[208:211], v175 offset:7168
	global_load_lds_dwordx4 v[192:193], off
	v_lshl_add_u64 v[192:193], s[44:45], 0, v[134:135]
	s_add_i32 m0, s53, 0xe000
	s_nop 0
	global_load_lds_dwordx4 v[192:193], off
	s_waitcnt vmcnt(8)
	s_waitcnt lgkmcnt(0)
	s_barrier
	s_setprio 1
	v_mfma_f32_16x16x32_bf16 v[126:129], v[136:139], v[168:171], v[126:129]
	v_mfma_f32_16x16x32_bf16 v[122:125], v[144:147], v[168:171], v[122:125]
	v_mfma_f32_16x16x32_bf16 v[110:113], v[136:139], v[180:183], v[110:113]
	v_mfma_f32_16x16x32_bf16 v[106:109], v[144:147], v[180:183], v[106:109]
	v_mfma_f32_16x16x32_bf16 v[94:97], v[136:139], v[196:199], v[94:97]
	v_mfma_f32_16x16x32_bf16 v[90:93], v[144:147], v[196:199], v[90:93]
	v_mfma_f32_16x16x32_bf16 v[78:81], v[136:139], v[204:207], v[78:81]
	v_mfma_f32_16x16x32_bf16 v[74:77], v[144:147], v[204:207], v[74:77]
	v_mfma_f32_16x16x32_bf16 v[126:129], v[140:143], v[176:179], v[126:129]
	v_mfma_f32_16x16x32_bf16 v[122:125], v[148:151], v[176:179], v[122:125]
	v_mfma_f32_16x16x32_bf16 v[110:113], v[140:143], v[186:189], v[110:113]
	v_mfma_f32_16x16x32_bf16 v[106:109], v[148:151], v[186:189], v[106:109]
	v_mfma_f32_16x16x32_bf16 v[94:97], v[140:143], v[200:203], v[94:97]
	v_mfma_f32_16x16x32_bf16 v[90:93], v[148:151], v[200:203], v[90:93]
	v_mfma_f32_16x16x32_bf16 v[78:81], v[140:143], v[208:211], v[78:81]
	v_mfma_f32_16x16x32_bf16 v[74:77], v[148:151], v[208:211], v[74:77]
	v_mfma_f32_16x16x32_bf16 v[118:121], v[152:155], v[168:171], v[118:121]
	v_mfma_f32_16x16x32_bf16 v[114:117], v[160:163], v[168:171], v[114:117]
	v_mfma_f32_16x16x32_bf16 v[102:105], v[152:155], v[180:183], v[102:105]
	v_mfma_f32_16x16x32_bf16 v[98:101], v[160:163], v[180:183], v[98:101]
	v_mfma_f32_16x16x32_bf16 v[86:89], v[152:155], v[196:199], v[86:89]
	v_mfma_f32_16x16x32_bf16 v[82:85], v[160:163], v[196:199], v[82:85]
	v_mfma_f32_16x16x32_bf16 v[70:73], v[152:155], v[204:207], v[70:73]
	v_mfma_f32_16x16x32_bf16 v[66:69], v[160:163], v[204:207], v[66:69]
	v_mfma_f32_16x16x32_bf16 v[118:121], v[156:159], v[176:179], v[118:121]
	v_mfma_f32_16x16x32_bf16 v[114:117], v[164:167], v[176:179], v[114:117]
	v_mfma_f32_16x16x32_bf16 v[102:105], v[156:159], v[186:189], v[102:105]
	v_mfma_f32_16x16x32_bf16 v[98:101], v[164:167], v[186:189], v[98:101]
	v_mfma_f32_16x16x32_bf16 v[86:89], v[156:159], v[200:203], v[86:89]
	v_mfma_f32_16x16x32_bf16 v[82:85], v[164:167], v[200:203], v[82:85]
	v_mfma_f32_16x16x32_bf16 v[70:73], v[156:159], v[208:211], v[70:73]
	v_mfma_f32_16x16x32_bf16 v[66:69], v[164:167], v[208:211], v[66:69]
	s_setprio 0
	s_barrier
	s_add_i32 s67, s67, s52
	v_lshl_add_u64 v[192:193], s[46:47], 0, v[0:1]
	s_mov_b32 m0, s67
	ds_read_b128 v[168:171], v175 offset:16384
	ds_read_b128 v[176:179], v175 offset:17408
	ds_read_b128 v[180:183], v175 offset:18432
	ds_read_b128 v[186:189], v175 offset:19456
	ds_read_b128 v[196:199], v175 offset:20480
	ds_read_b128 v[200:203], v175 offset:21504
	ds_read_b128 v[204:207], v175 offset:22528
	ds_read_b128 v[208:211], v175 offset:23552
	global_load_lds_dwordx4 v[192:193], off
	s_add_i32 m0, s67, 0x2000
	s_add_u32 s68, s46, 0x40000
	v_lshl_add_u64 v[212:213], s[46:47], 0, v[130:131]
	s_addc_u32 s69, s47, 0
	s_add_i32 s12, s12, s52
	global_load_lds_dwordx4 v[212:213], off
	v_lshl_add_u64 v[214:215], s[68:69], 0, v[0:1]
	s_mov_b32 m0, s12
	v_lshl_add_u64 v[216:217], s[48:49], 0, v[130:131]
	global_load_lds_dwordx4 v[214:215], off
	v_lshl_add_u64 v[214:215], s[68:69], 0, v[130:131]
	s_add_i32 m0, s12, 0x2000
	s_nop 0
	global_load_lds_dwordx4 v[214:215], off
	v_lshl_add_u64 v[214:215], s[48:49], 0, v[0:1]
	s_mov_b32 m0, s53
	s_nop 0
	global_load_lds_dwordx4 v[214:215], off
	s_mov_b32 m0, s54
	s_nop 0
	global_load_lds_dwordx4 v[216:217], off
	s_waitcnt vmcnt(8)
	s_waitcnt lgkmcnt(0)
	s_barrier
; #define PG8_STAGE(bufoff, gbase, voff) do { _Pragma("unroll") for (int _i = 0; _i < 2; ++_i) \
;         __builtin_amdgcn_global_load_lds((const unsigned*)((const char*)(gbase) + (voff)[_i]), (LAS unsigned*)(lds + (bufoff) + ldsw + _i * 8192), 16, 0, 0); } while (0)
; #define PG8_LDA(dst, b, h) do { _Pragma("unroll") for (int m = 0; m < 4; ++m) _Pragma("unroll") for (int k = 0; k < 2; ++k) dst[m][k] = *(const LAS bf16x8*)(lds + PG8_SA(b, h) + aoff + m * 2048 + k * 1024); } while (0)
; #define PG8_LDB(dst, b, h) do { _Pragma("unroll") for (int n = 0; n < 2; ++n) _Pragma("unroll") for (int k = 0; k < 2; ++k) dst[n][k] = *(const LAS bf16x8*)(lds + PG8_SB(b, h) + boff + n * 2048 + k * 1024); } while (0)
; #define PG8_MMA(ai, bj, At, Bt) do { __builtin_amdgcn_s_setprio(1); _Pragma("unroll") for (int m = 0; m < 4; ++m) _Pragma("unroll") for (int n = 0; n < 2; ++n) _Pragma("unroll") for (int k = 0; k < 2; ++k) \
;         acc[ai][bj][m][n] = __builtin_amdgcn_mfma_f32_16x16x32_bf16(Bt[n][k], At[m][k], acc[ai][bj][m][n], 0, 0, 0); __builtin_amdgcn_s_setprio(0); } while (0)
; #define PG8_WAIT_V(n) asm volatile("s_waitcnt vmcnt(" #n ")" ::: "memory")
; #define PG8_WAIT_L(n) asm volatile("s_waitcnt lgkmcnt(" #n ")" ::: "memory")
; #define PG8_BAR __builtin_amdgcn_s_barrier()
; #define PG8_SCHED __builtin_amdgcn_sched_barrier(0)
; template <class Epi>
; DI void gemm_phase(LAS unsigned char* lds, const Gemm g, const Epi& E, const int tid) {
;     ...
;             PG8_WAIT_V(8); PG8_WAIT_L(0); PG8_BAR; PG8_MMA(1, 0, At, B0); PG8_MMA(1, 1, At, B1); PG8_BAR; PG8_SCHED;
;             PG8_LDB(B0, 1, 0); PG8_LDB(B1, 1, 1); PG8_SCHED; PG8_LDA(At, 1, 0); PG8_STAGE(PG8_SA(0, 1), a2 + hstepA, voffA);
;             PG8_WAIT_V(8); PG8_WAIT_L(0); PG8_BAR; PG8_MMA(0, 0, At, B0); PG8_MMA(0, 1, At, B1); PG8_BAR; PG8_SCHED;
	s_setprio 1
	v_mfma_f32_16x16x32_bf16 v[62:65], v[136:139], v[168:171], v[62:65]
	v_mfma_f32_16x16x32_bf16 v[58:61], v[144:147], v[168:171], v[58:61]
	v_mfma_f32_16x16x32_bf16 v[46:49], v[136:139], v[180:183], v[46:49]
	v_mfma_f32_16x16x32_bf16 v[42:45], v[144:147], v[180:183], v[42:45]
	v_mfma_f32_16x16x32_bf16 v[30:33], v[136:139], v[196:199], v[30:33]
	v_mfma_f32_16x16x32_bf16 v[26:29], v[144:147], v[196:199], v[26:29]
	v_mfma_f32_16x16x32_bf16 v[14:17], v[136:139], v[204:207], v[14:17]
	v_mfma_f32_16x16x32_bf16 v[10:13], v[144:147], v[204:207], v[10:13]
	v_mfma_f32_16x16x32_bf16 v[62:65], v[140:143], v[176:179], v[62:65]
	v_mfma_f32_16x16x32_bf16 v[58:61], v[148:151], v[176:179], v[58:61]
	v_mfma_f32_16x16x32_bf16 v[46:49], v[140:143], v[186:189], v[46:49]
	v_mfma_f32_16x16x32_bf16 v[42:45], v[148:151], v[186:189], v[42:45]
	v_mfma_f32_16x16x32_bf16 v[30:33], v[140:143], v[200:203], v[30:33]
	v_mfma_f32_16x16x32_bf16 v[26:29], v[148:151], v[200:203], v[26:29]
	v_mfma_f32_16x16x32_bf16 v[14:17], v[140:143], v[208:211], v[14:17]
	v_mfma_f32_16x16x32_bf16 v[10:13], v[148:151], v[208:211], v[10:13]
	v_mfma_f32_16x16x32_bf16 v[54:57], v[152:155], v[168:171], v[54:57]
	v_mfma_f32_16x16x32_bf16 v[50:53], v[160:163], v[168:171], v[50:53]
	v_mfma_f32_16x16x32_bf16 v[38:41], v[152:155], v[180:183], v[38:41]
	v_mfma_f32_16x16x32_bf16 v[34:37], v[160:163], v[180:183], v[34:37]
	v_mfma_f32_16x16x32_bf16 v[22:25], v[152:155], v[196:199], v[22:25]
	v_mfma_f32_16x16x32_bf16 v[18:21], v[160:163], v[196:199], v[18:21]
	v_mfma_f32_16x16x32_bf16 v[6:9], v[152:155], v[204:207], v[6:9]
	v_mfma_f32_16x16x32_bf16 v[2:5], v[160:163], v[204:207], v[2:5]
	v_mfma_f32_16x16x32_bf16 v[54:57], v[156:159], v[176:179], v[54:57]
	v_mfma_f32_16x16x32_bf16 v[50:53], v[164:167], v[176:179], v[50:53]
	v_mfma_f32_16x16x32_bf16 v[38:41], v[156:159], v[186:189], v[38:41]
	v_mfma_f32_16x16x32_bf16 v[34:37], v[164:167], v[186:189], v[34:37]
	v_mfma_f32_16x16x32_bf16 v[22:25], v[156:159], v[200:203], v[22:25]
	v_mfma_f32_16x16x32_bf16 v[18:21], v[164:167], v[200:203], v[18:21]
	v_mfma_f32_16x16x32_bf16 v[6:9], v[156:159], v[208:211], v[6:9]
	v_mfma_f32_16x16x32_bf16 v[2:5], v[164:167], v[208:211], v[2:5]
	s_setprio 0
	s_barrier
	s_add_i32 s12, 0, 0x18000
	s_add_i32 s67, 0, 0x1c000
	v_add_u32_e32 v148, s12, v173
	v_add_u32_e32 v164, s67, v173
	ds_read_b128 v[136:139], v148
	ds_read_b128 v[140:143], v148 offset:1024
	ds_read_b128 v[144:147], v148 offset:2048
	ds_read_b128 v[148:151], v148 offset:3072
	ds_read_b128 v[152:155], v164
	ds_read_b128 v[156:159], v164 offset:1024
	ds_read_b128 v[160:163], v164 offset:2048
	ds_read_b128 v[164:167], v164 offset:3072
	s_add_u32 s48, s48, 0x40000
	s_addc_u32 s49, s49, 0
	s_mov_b32 m0, s55
	v_lshl_add_u64 v[228:229], s[48:49], 0, v[0:1]
	ds_read_b128 v[168:171], v175 offset:32768
	ds_read_b128 v[176:179], v175 offset:33792
	ds_read_b128 v[180:183], v175 offset:34816
	ds_read_b128 v[186:189], v175 offset:35840
	ds_read_b128 v[196:199], v175 offset:36864
	ds_read_b128 v[200:203], v175 offset:37888
	ds_read_b128 v[204:207], v175 offset:38912
	ds_read_b128 v[208:211], v175 offset:39936
	global_load_lds_dwordx4 v[228:229], off
	v_lshl_add_u64 v[228:229], s[48:49], 0, v[130:131]
	s_mov_b32 m0, s56
	s_nop 0
	global_load_lds_dwordx4 v[228:229], off
	s_waitcnt vmcnt(8)
	s_waitcnt lgkmcnt(0)
	s_barrier
	s_setprio 1
	v_mfma_f32_16x16x32_bf16 v[126:129], v[136:139], v[168:171], v[126:129]
	v_mfma_f32_16x16x32_bf16 v[122:125], v[144:147], v[168:171], v[122:125]
	v_mfma_f32_16x16x32_bf16 v[110:113], v[136:139], v[180:183], v[110:113]
	v_mfma_f32_16x16x32_bf16 v[106:109], v[144:147], v[180:183], v[106:109]
	v_mfma_f32_16x16x32_bf16 v[94:97], v[136:139], v[196:199], v[94:97]
	v_mfma_f32_16x16x32_bf16 v[90:93], v[144:147], v[196:199], v[90:93]
	v_mfma_f32_16x16x32_bf16 v[78:81], v[136:139], v[204:207], v[78:81]
	v_mfma_f32_16x16x32_bf16 v[74:77], v[144:147], v[204:207], v[74:77]
	v_mfma_f32_16x16x32_bf16 v[126:129], v[140:143], v[176:179], v[126:129]
	v_mfma_f32_16x16x32_bf16 v[122:125], v[148:151], v[176:179], v[122:125]
	v_mfma_f32_16x16x32_bf16 v[110:113], v[140:143], v[186:189], v[110:113]
	v_mfma_f32_16x16x32_bf16 v[106:109], v[148:151], v[186:189], v[106:109]
	v_mfma_f32_16x16x32_bf16 v[94:97], v[140:143], v[200:203], v[94:97]
	v_mfma_f32_16x16x32_bf16 v[90:93], v[148:151], v[200:203], v[90:93]
	v_mfma_f32_16x16x32_bf16 v[78:81], v[140:143], v[208:211], v[78:81]
	v_mfma_f32_16x16x32_bf16 v[74:77], v[148:151], v[208:211], v[74:77]
	v_mfma_f32_16x16x32_bf16 v[118:121], v[152:155], v[168:171], v[118:121]
	v_mfma_f32_16x16x32_bf16 v[114:117], v[160:163], v[168:171], v[114:117]
	v_mfma_f32_16x16x32_bf16 v[102:105], v[152:155], v[180:183], v[102:105]
	v_mfma_f32_16x16x32_bf16 v[98:101], v[160:163], v[180:183], v[98:101]
	v_mfma_f32_16x16x32_bf16 v[86:89], v[152:155], v[196:199], v[86:89]
	v_mfma_f32_16x16x32_bf16 v[82:85], v[160:163], v[196:199], v[82:85]
	v_mfma_f32_16x16x32_bf16 v[70:73], v[152:155], v[204:207], v[70:73]
	v_mfma_f32_16x16x32_bf16 v[66:69], v[160:163], v[204:207], v[66:69]
	v_mfma_f32_16x16x32_bf16 v[118:121], v[156:159], v[176:179], v[118:121]
	v_mfma_f32_16x16x32_bf16 v[114:117], v[164:167], v[176:179], v[114:117]
	v_mfma_f32_16x16x32_bf16 v[102:105], v[156:159], v[186:189], v[102:105]
	v_mfma_f32_16x16x32_bf16 v[98:101], v[164:167], v[186:189], v[98:101]
	v_mfma_f32_16x16x32_bf16 v[86:89], v[156:159], v[200:203], v[86:89]
	v_mfma_f32_16x16x32_bf16 v[82:85], v[164:167], v[200:203], v[82:85]
	v_mfma_f32_16x16x32_bf16 v[70:73], v[156:159], v[208:211], v[70:73]
	v_mfma_f32_16x16x32_bf16 v[66:69], v[164:167], v[208:211], v[66:69]
	s_setprio 0
	s_barrier
; #define PG8_STAGE(bufoff, gbase, voff) do { _Pragma("unroll") for (int _i = 0; _i < 2; ++_i) \
;         __builtin_amdgcn_global_load_lds((const unsigned*)((const char*)(gbase) + (voff)[_i]), (LAS unsigned*)(lds + (bufoff) + ldsw + _i * 8192), 16, 0, 0); } while (0)
; #define PG8_LDA(dst, b, h) do { _Pragma("unroll") for (int m = 0; m < 4; ++m) _Pragma("unroll") for (int k = 0; k < 2; ++k) dst[m][k] = *(const LAS bf16x8*)(lds + PG8_SA(b, h) + aoff + m * 2048 + k * 1024); } while (0)
; #define PG8_MMA(ai, bj, At, Bt) do { __builtin_amdgcn_s_setprio(1); _Pragma("unroll") for (int m = 0; m < 4; ++m) _Pragma("unroll") for (int n = 0; n < 2; ++n) _Pragma("unroll") for (int k = 0; k < 2; ++k) \
;         acc[ai][bj][m][n] = __builtin_amdgcn_mfma_f32_16x16x32_bf16(Bt[n][k], At[m][k], acc[ai][bj][m][n], 0, 0, 0); __builtin_amdgcn_s_setprio(0); } while (0)
; #define PG8_WAIT_V(n) asm volatile("s_waitcnt vmcnt(" #n ")" ::: "memory")
; #define PG8_WAIT_L(n) asm volatile("s_waitcnt lgkmcnt(" #n ")" ::: "memory")
; #define PG8_BAR __builtin_amdgcn_s_barrier()
; #define PG8_SCHED __builtin_amdgcn_sched_barrier(0)
; template <class Epi>
; DI void gemm_phase(LAS unsigned char* lds, const Gemm g, const Epi& E, const int tid) {
;     ...
;             PG8_LDA(At, 1, 1); PG8_STAGE(PG8_SB(1, 0), b3, voffB); PG8_STAGE(PG8_SB(1, 1), b3 + hstepB, voffB); PG8_STAGE(PG8_SA(1, 0), a3, voffA);
;             PG8_WAIT_V(8); PG8_WAIT_L(0); PG8_BAR; PG8_MMA(1, 0, At, B0); PG8_MMA(1, 1, At, B1); PG8_BAR; PG8_SCHED;
	s_add_i32 s12, s12, s52
	v_lshl_add_u64 v[192:193], v[192:193], 0, s[8:9]
	s_mov_b32 m0, s12
	ds_read_b128 v[168:171], v175 offset:49152
	ds_read_b128 v[176:179], v175 offset:50176
	ds_read_b128 v[180:183], v175 offset:51200
	ds_read_b128 v[186:189], v175 offset:52224
	ds_read_b128 v[196:199], v175 offset:53248
	ds_read_b128 v[200:203], v175 offset:54272
	ds_read_b128 v[204:207], v175 offset:55296
	ds_read_b128 v[208:211], v175 offset:56320
	global_load_lds_dwordx4 v[192:193], off
	s_add_i32 m0, s12, 0x2000
	s_add_u32 s46, s46, 0x40080
	v_lshl_add_u64 v[192:193], v[212:213], 0, s[8:9]
	s_addc_u32 s47, s47, 0
	s_add_i32 s12, s67, s52
	global_load_lds_dwordx4 v[192:193], off
	v_lshl_add_u64 v[192:193], s[46:47], 0, v[0:1]
	s_mov_b32 m0, s12
	s_nop 0
	global_load_lds_dwordx4 v[192:193], off
	v_lshl_add_u64 v[192:193], s[46:47], 0, v[130:131]
	s_add_i32 m0, s12, 0x2000
	s_nop 0
	global_load_lds_dwordx4 v[192:193], off
	v_lshl_add_u64 v[192:193], v[214:215], 0, s[8:9]
	s_mov_b32 m0, s57
	s_nop 0
	global_load_lds_dwordx4 v[192:193], off
	v_lshl_add_u64 v[192:193], v[216:217], 0, s[8:9]
	s_mov_b32 m0, s58
	s_nop 0
	global_load_lds_dwordx4 v[192:193], off
	s_waitcnt vmcnt(8)
	s_waitcnt lgkmcnt(0)
	s_barrier
	s_setprio 1
	v_mfma_f32_16x16x32_bf16 v[62:65], v[136:139], v[168:171], v[62:65]
	v_mfma_f32_16x16x32_bf16 v[58:61], v[144:147], v[168:171], v[58:61]
	v_mfma_f32_16x16x32_bf16 v[46:49], v[136:139], v[180:183], v[46:49]
	v_mfma_f32_16x16x32_bf16 v[42:45], v[144:147], v[180:183], v[42:45]
	v_mfma_f32_16x16x32_bf16 v[30:33], v[136:139], v[196:199], v[30:33]
	v_mfma_f32_16x16x32_bf16 v[26:29], v[144:147], v[196:199], v[26:29]
	v_mfma_f32_16x16x32_bf16 v[14:17], v[136:139], v[204:207], v[14:17]
	v_mfma_f32_16x16x32_bf16 v[10:13], v[144:147], v[204:207], v[10:13]
	v_mfma_f32_16x16x32_bf16 v[62:65], v[140:143], v[176:179], v[62:65]
	v_mfma_f32_16x16x32_bf16 v[58:61], v[148:151], v[176:179], v[58:61]
	v_mfma_f32_16x16x32_bf16 v[46:49], v[140:143], v[186:189], v[46:49]
	v_mfma_f32_16x16x32_bf16 v[42:45], v[148:151], v[186:189], v[42:45]
	v_mfma_f32_16x16x32_bf16 v[30:33], v[140:143], v[200:203], v[30:33]
	v_mfma_f32_16x16x32_bf16 v[26:29], v[148:151], v[200:203], v[26:29]
	v_mfma_f32_16x16x32_bf16 v[14:17], v[140:143], v[208:211], v[14:17]
	v_mfma_f32_16x16x32_bf16 v[10:13], v[148:151], v[208:211], v[10:13]
	v_mfma_f32_16x16x32_bf16 v[54:57], v[152:155], v[168:171], v[54:57]
	v_mfma_f32_16x16x32_bf16 v[50:53], v[160:163], v[168:171], v[50:53]
	v_mfma_f32_16x16x32_bf16 v[38:41], v[152:155], v[180:183], v[38:41]
	v_mfma_f32_16x16x32_bf16 v[34:37], v[160:163], v[180:183], v[34:37]
	v_mfma_f32_16x16x32_bf16 v[22:25], v[152:155], v[196:199], v[22:25]
	v_mfma_f32_16x16x32_bf16 v[18:21], v[160:163], v[196:199], v[18:21]
	v_mfma_f32_16x16x32_bf16 v[6:9], v[152:155], v[204:207], v[6:9]
	v_mfma_f32_16x16x32_bf16 v[2:5], v[160:163], v[204:207], v[2:5]
	v_mfma_f32_16x16x32_bf16 v[54:57], v[156:159], v[176:179], v[54:57]
	v_mfma_f32_16x16x32_bf16 v[50:53], v[164:167], v[176:179], v[50:53]
	v_mfma_f32_16x16x32_bf16 v[38:41], v[156:159], v[186:189], v[38:41]
	v_mfma_f32_16x16x32_bf16 v[34:37], v[164:167], v[186:189], v[34:37]
	v_mfma_f32_16x16x32_bf16 v[22:25], v[156:159], v[200:203], v[22:25]
	v_mfma_f32_16x16x32_bf16 v[18:21], v[164:167], v[200:203], v[18:21]
	v_mfma_f32_16x16x32_bf16 v[6:9], v[156:159], v[208:211], v[6:9]
	v_mfma_f32_16x16x32_bf16 v[2:5], v[164:167], v[208:211], v[2:5]
	s_setprio 0
	s_barrier
	s_add_i32 s66, s66, 2
	s_add_u32 s44, s44, 0x100
	s_addc_u32 s45, s45, 0
	s_add_u32 s64, s64, 0x100
	s_addc_u32 s65, s65, 0
	s_cmp_gt_u32 s66, 13
	s_cbranch_scc0 .LBB0_172
	s_and_b64 vcc, exec, s[14:15]
	s_cbranch_vccz .LBB0_175
	s_barrier

; #define PG8_STAGE(bufoff, gbase, voff) do { _Pragma("unroll") for (int _i = 0; _i < 2; ++_i) \
;         __builtin_amdgcn_global_load_lds((const unsigned*)((const char*)(gbase) + (voff)[_i]), (LAS unsigned*)(lds + (bufoff) + ldsw + _i * 8192), 16, 0, 0); } while (0)
; #define PG8_LDA(dst, b, h) do { _Pragma("unroll") for (int m = 0; m < 4; ++m) _Pragma("unroll") for (int k = 0; k < 2; ++k) dst[m][k] = *(const LAS bf16x8*)(lds + PG8_SA(b, h) + aoff + m * 2048 + k * 1024); } while (0)
; #define PG8_LDB(dst, b, h) do { _Pragma("unroll") for (int n = 0; n < 2; ++n) _Pragma("unroll") for (int k = 0; k < 2; ++k) dst[n][k] = *(const LAS bf16x8*)(lds + PG8_SB(b, h) + boff + n * 2048 + k * 1024); } while (0)
; #define PG8_MMA(ai, bj, At, Bt) do { __builtin_amdgcn_s_setprio(1); _Pragma("unroll") for (int m = 0; m < 4; ++m) _Pragma("unroll") for (int n = 0; n < 2; ++n) _Pragma("unroll") for (int k = 0; k < 2; ++k) \
;         acc[ai][bj][m][n] = __builtin_amdgcn_mfma_f32_16x16x32_bf16(Bt[n][k], At[m][k], acc[ai][bj][m][n], 0, 0, 0); __builtin_amdgcn_s_setprio(0); } while (0)
; #define PG8_WAIT_V(n) asm volatile("s_waitcnt vmcnt(" #n ")" ::: "memory")
; #define PG8_WAIT_L(n) asm volatile("s_waitcnt lgkmcnt(" #n ")" ::: "memory")
; #define PG8_BAR __builtin_amdgcn_s_barrier()
; #define PG8_SCHED __builtin_amdgcn_sched_barrier(0)
; template <class Epi>
; DI void gemm_phase(LAS unsigned char* lds, const Gemm g, const Epi& E, const int tid) {
;     ...
;             PG8_LDB(B0, 0, 0); PG8_LDB(B1, 0, 1); PG8_SCHED; PG8_LDA(At, 0, 0); PG8_STAGE(PG8_SA(1, 1), a1 + hstepA, voffA);
;             PG8_WAIT_V(8); PG8_WAIT_L(0); PG8_BAR; PG8_MMA(0, 0, At, B0); PG8_MMA(0, 1, At, B1); PG8_BAR; PG8_SCHED;
;             PG8_LDA(At, 0, 1); PG8_STAGE(PG8_SB(0, 0), b2, voffB); PG8_STAGE(PG8_SB(0, 1), b2 + hstepB, voffB); PG8_STAGE(PG8_SA(0, 0), a2, voffA);
;             PG8_WAIT_V(8); PG8_WAIT_L(0); PG8_BAR; PG8_MMA(1, 0, At, B0); PG8_MMA(1, 1, At, B1); PG8_BAR; PG8_SCHED;
.LBB0_195:
	s_add_u32 s12, s46, 0xfff80080
	s_addc_u32 s48, s47, -1
	s_add_i32 s66, 0, 0x10000
	s_cmp_eq_u32 s65, 4
	s_cselect_b32 s51, s35, s48
	s_cselect_b32 s50, s62, s12
	s_cselect_b32 s49, s25, s64
	s_cselect_b32 s48, s41, s63
	s_add_i32 s12, 0, 0x14000
	v_add_u32_e32 v156, s66, v141
	v_add_u32_e32 v172, s12, v141
	ds_read_b128 v[144:147], v156
	ds_read_b128 v[148:151], v156 offset:1024
	ds_read_b128 v[152:155], v156 offset:2048
	ds_read_b128 v[156:159], v156 offset:3072
	ds_read_b128 v[160:163], v172
	ds_read_b128 v[164:167], v172 offset:1024
	ds_read_b128 v[168:171], v172 offset:2048
	ds_read_b128 v[172:175], v172 offset:3072
	v_lshl_add_u64 v[192:193], s[46:47], 0, v[136:137]
	s_add_i32 m0, s52, 0xc000
	ds_read_b128 v[176:179], v143
	ds_read_b128 v[180:183], v143 offset:1024
	ds_read_b128 v[186:189], v143 offset:2048
	ds_read_b128 v[196:199], v143 offset:3072
	ds_read_b128 v[200:203], v143 offset:4096
	ds_read_b128 v[204:207], v143 offset:5120
	ds_read_b128 v[208:211], v143 offset:6144
	ds_read_b128 v[212:215], v143 offset:7168
	global_load_lds_dwordx4 v[192:193], off
	v_lshl_add_u64 v[192:193], s[46:47], 0, v[138:139]
	s_add_i32 m0, s52, 0xe000
	s_nop 0
	global_load_lds_dwordx4 v[192:193], off
	s_waitcnt vmcnt(8)
	s_waitcnt lgkmcnt(0)
	s_barrier
	s_setprio 1
	v_mfma_f32_16x16x32_bf16 v[126:129], v[144:147], v[176:179], v[126:129]
	v_mfma_f32_16x16x32_bf16 v[122:125], v[152:155], v[176:179], v[122:125]
	v_mfma_f32_16x16x32_bf16 v[118:121], v[144:147], v[186:189], v[118:121]
	v_mfma_f32_16x16x32_bf16 v[114:117], v[152:155], v[186:189], v[114:117]
	v_mfma_f32_16x16x32_bf16 v[102:105], v[144:147], v[200:203], v[102:105]
	v_mfma_f32_16x16x32_bf16 v[98:101], v[152:155], v[200:203], v[98:101]
	v_mfma_f32_16x16x32_bf16 v[86:89], v[144:147], v[208:211], v[86:89]
	v_mfma_f32_16x16x32_bf16 v[82:85], v[152:155], v[208:211], v[82:85]
	v_mfma_f32_16x16x32_bf16 v[126:129], v[148:151], v[180:183], v[126:129]
	v_mfma_f32_16x16x32_bf16 v[122:125], v[156:159], v[180:183], v[122:125]
	v_mfma_f32_16x16x32_bf16 v[118:121], v[148:151], v[196:199], v[118:121]
	v_mfma_f32_16x16x32_bf16 v[114:117], v[156:159], v[196:199], v[114:117]
	v_mfma_f32_16x16x32_bf16 v[102:105], v[148:151], v[204:207], v[102:105]
	v_mfma_f32_16x16x32_bf16 v[98:101], v[156:159], v[204:207], v[98:101]
	v_mfma_f32_16x16x32_bf16 v[86:89], v[148:151], v[212:215], v[86:89]
	v_mfma_f32_16x16x32_bf16 v[82:85], v[156:159], v[212:215], v[82:85]
	v_mfma_f32_16x16x32_bf16 v[110:113], v[160:163], v[176:179], v[110:113]
	v_mfma_f32_16x16x32_bf16 v[106:109], v[168:171], v[176:179], v[106:109]
	v_mfma_f32_16x16x32_bf16 v[94:97], v[160:163], v[186:189], v[94:97]
	v_mfma_f32_16x16x32_bf16 v[90:93], v[168:171], v[186:189], v[90:93]
	v_mfma_f32_16x16x32_bf16 v[78:81], v[160:163], v[200:203], v[78:81]
	v_mfma_f32_16x16x32_bf16 v[74:77], v[168:171], v[200:203], v[74:77]
	v_mfma_f32_16x16x32_bf16 v[70:73], v[160:163], v[208:211], v[70:73]
	v_mfma_f32_16x16x32_bf16 v[66:69], v[168:171], v[208:211], v[66:69]
	v_mfma_f32_16x16x32_bf16 v[110:113], v[164:167], v[180:183], v[110:113]
	v_mfma_f32_16x16x32_bf16 v[106:109], v[172:175], v[180:183], v[106:109]
	v_mfma_f32_16x16x32_bf16 v[94:97], v[164:167], v[196:199], v[94:97]
	v_mfma_f32_16x16x32_bf16 v[90:93], v[172:175], v[196:199], v[90:93]
	v_mfma_f32_16x16x32_bf16 v[78:81], v[164:167], v[204:207], v[78:81]
	v_mfma_f32_16x16x32_bf16 v[74:77], v[172:175], v[204:207], v[74:77]
	v_mfma_f32_16x16x32_bf16 v[70:73], v[164:167], v[212:215], v[70:73]
	v_mfma_f32_16x16x32_bf16 v[66:69], v[172:175], v[212:215], v[66:69]
	s_setprio 0
	s_barrier
	s_add_i32 s66, s66, s4
	v_lshl_add_u64 v[192:193], s[48:49], 0, v[0:1]
	s_mov_b32 m0, s66
	ds_read_b128 v[176:179], v143 offset:16384
	ds_read_b128 v[180:183], v143 offset:17408
	ds_read_b128 v[186:189], v143 offset:18432
	ds_read_b128 v[196:199], v143 offset:19456
	ds_read_b128 v[200:203], v143 offset:20480
	ds_read_b128 v[204:207], v143 offset:21504
	ds_read_b128 v[208:211], v143 offset:22528
	ds_read_b128 v[212:215], v143 offset:23552
	global_load_lds_dwordx4 v[192:193], off
	s_add_i32 m0, s66, 0x2000
	s_add_u32 s66, s48, 0x20000
	v_lshl_add_u64 v[216:217], s[48:49], 0, v[130:131]
	s_addc_u32 s67, s49, 0
	s_add_i32 s12, s12, s4
	global_load_lds_dwordx4 v[216:217], off
	v_lshl_add_u64 v[228:229], s[66:67], 0, v[0:1]
	s_mov_b32 m0, s12
	v_lshl_add_u64 v[230:231], s[50:51], 0, v[132:133]
	global_load_lds_dwordx4 v[228:229], off
	v_lshl_add_u64 v[228:229], s[66:67], 0, v[130:131]
	s_add_i32 m0, s12, 0x2000
	s_nop 0
	global_load_lds_dwordx4 v[228:229], off
	v_lshl_add_u64 v[228:229], s[50:51], 0, v[134:135]
	s_mov_b32 m0, s52
	s_nop 0
	global_load_lds_dwordx4 v[228:229], off
	s_mov_b32 m0, s53
	s_nop 0
	global_load_lds_dwordx4 v[230:231], off
	s_waitcnt vmcnt(8)
	s_waitcnt lgkmcnt(0)
	s_barrier
; #define PG8_STAGE(bufoff, gbase, voff) do { _Pragma("unroll") for (int _i = 0; _i < 2; ++_i) \
;         __builtin_amdgcn_global_load_lds((const unsigned*)((const char*)(gbase) + (voff)[_i]), (LAS unsigned*)(lds + (bufoff) + ldsw + _i * 8192), 16, 0, 0); } while (0)
; #define PG8_LDA(dst, b, h) do { _Pragma("unroll") for (int m = 0; m < 4; ++m) _Pragma("unroll") for (int k = 0; k < 2; ++k) dst[m][k] = *(const LAS bf16x8*)(lds + PG8_SA(b, h) + aoff + m * 2048 + k * 1024); } while (0)
; #define PG8_LDB(dst, b, h) do { _Pragma("unroll") for (int n = 0; n < 2; ++n) _Pragma("unroll") for (int k = 0; k < 2; ++k) dst[n][k] = *(const LAS bf16x8*)(lds + PG8_SB(b, h) + boff + n * 2048 + k * 1024); } while (0)
; #define PG8_MMA(ai, bj, At, Bt) do { __builtin_amdgcn_s_setprio(1); _Pragma("unroll") for (int m = 0; m < 4; ++m) _Pragma("unroll") for (int n = 0; n < 2; ++n) _Pragma("unroll") for (int k = 0; k < 2; ++k) \
;         acc[ai][bj][m][n] = __builtin_amdgcn_mfma_f32_16x16x32_bf16(Bt[n][k], At[m][k], acc[ai][bj][m][n], 0, 0, 0); __builtin_amdgcn_s_setprio(0); } while (0)
; #define PG8_WAIT_V(n) asm volatile("s_waitcnt vmcnt(" #n ")" ::: "memory")
; #define PG8_WAIT_L(n) asm volatile("s_waitcnt lgkmcnt(" #n ")" ::: "memory")
; #define PG8_BAR __builtin_amdgcn_s_barrier()
; #define PG8_SCHED __builtin_amdgcn_sched_barrier(0)
; template <class Epi>
; DI void gemm_phase(LAS unsigned char* lds, const Gemm g, const Epi& E, const int tid) {
;     ...
;             PG8_WAIT_V(8); PG8_WAIT_L(0); PG8_BAR; PG8_MMA(1, 0, At, B0); PG8_MMA(1, 1, At, B1); PG8_BAR; PG8_SCHED;
;             PG8_LDB(B0, 1, 0); PG8_LDB(B1, 1, 1); PG8_SCHED; PG8_LDA(At, 1, 0); PG8_STAGE(PG8_SA(0, 1), a2 + hstepA, voffA);
;             PG8_WAIT_V(8); PG8_WAIT_L(0); PG8_BAR; PG8_MMA(0, 0, At, B0); PG8_MMA(0, 1, At, B1); PG8_BAR; PG8_SCHED;
	s_setprio 1
	v_mfma_f32_16x16x32_bf16 v[62:65], v[144:147], v[176:179], v[62:65]
	v_mfma_f32_16x16x32_bf16 v[58:61], v[152:155], v[176:179], v[58:61]
	v_mfma_f32_16x16x32_bf16 v[54:57], v[144:147], v[186:189], v[54:57]
	v_mfma_f32_16x16x32_bf16 v[50:53], v[152:155], v[186:189], v[50:53]
	v_mfma_f32_16x16x32_bf16 v[38:41], v[144:147], v[200:203], v[38:41]
	v_mfma_f32_16x16x32_bf16 v[34:37], v[152:155], v[200:203], v[34:37]
	v_mfma_f32_16x16x32_bf16 v[22:25], v[144:147], v[208:211], v[22:25]
	v_mfma_f32_16x16x32_bf16 v[18:21], v[152:155], v[208:211], v[18:21]
	v_mfma_f32_16x16x32_bf16 v[62:65], v[148:151], v[180:183], v[62:65]
	v_mfma_f32_16x16x32_bf16 v[58:61], v[156:159], v[180:183], v[58:61]
	v_mfma_f32_16x16x32_bf16 v[54:57], v[148:151], v[196:199], v[54:57]
	v_mfma_f32_16x16x32_bf16 v[50:53], v[156:159], v[196:199], v[50:53]
	v_mfma_f32_16x16x32_bf16 v[38:41], v[148:151], v[204:207], v[38:41]
	v_mfma_f32_16x16x32_bf16 v[34:37], v[156:159], v[204:207], v[34:37]
	v_mfma_f32_16x16x32_bf16 v[22:25], v[148:151], v[212:215], v[22:25]
	v_mfma_f32_16x16x32_bf16 v[18:21], v[156:159], v[212:215], v[18:21]
	v_mfma_f32_16x16x32_bf16 v[46:49], v[160:163], v[176:179], v[46:49]
	v_mfma_f32_16x16x32_bf16 v[42:45], v[168:171], v[176:179], v[42:45]
	v_mfma_f32_16x16x32_bf16 v[30:33], v[160:163], v[186:189], v[30:33]
	v_mfma_f32_16x16x32_bf16 v[26:29], v[168:171], v[186:189], v[26:29]
	v_mfma_f32_16x16x32_bf16 v[14:17], v[160:163], v[200:203], v[14:17]
	v_mfma_f32_16x16x32_bf16 v[10:13], v[168:171], v[200:203], v[10:13]
	v_mfma_f32_16x16x32_bf16 v[6:9], v[160:163], v[208:211], v[6:9]
	v_mfma_f32_16x16x32_bf16 v[2:5], v[168:171], v[208:211], v[2:5]
	v_mfma_f32_16x16x32_bf16 v[46:49], v[164:167], v[180:183], v[46:49]
	v_mfma_f32_16x16x32_bf16 v[42:45], v[172:175], v[180:183], v[42:45]
	v_mfma_f32_16x16x32_bf16 v[30:33], v[164:167], v[196:199], v[30:33]
	v_mfma_f32_16x16x32_bf16 v[26:29], v[172:175], v[196:199], v[26:29]
	v_mfma_f32_16x16x32_bf16 v[14:17], v[164:167], v[204:207], v[14:17]
	v_mfma_f32_16x16x32_bf16 v[10:13], v[172:175], v[204:207], v[10:13]
	v_mfma_f32_16x16x32_bf16 v[6:9], v[164:167], v[212:215], v[6:9]
	v_mfma_f32_16x16x32_bf16 v[2:5], v[172:175], v[212:215], v[2:5]
	s_setprio 0
	s_barrier
	s_add_i32 s12, 0, 0x18000
	s_add_i32 s66, 0, 0x1c000
	v_add_u32_e32 v156, s12, v141
	v_add_u32_e32 v172, s66, v141
	ds_read_b128 v[144:147], v156
	ds_read_b128 v[148:151], v156 offset:1024
	ds_read_b128 v[152:155], v156 offset:2048
	ds_read_b128 v[156:159], v156 offset:3072
	ds_read_b128 v[160:163], v172
	ds_read_b128 v[164:167], v172 offset:1024
	ds_read_b128 v[168:171], v172 offset:2048
	ds_read_b128 v[172:175], v172 offset:3072
	s_add_u32 s50, s50, 0x80000
	s_addc_u32 s51, s51, 0
	s_mov_b32 m0, s54
	v_lshl_add_u64 v[232:233], s[50:51], 0, v[134:135]
	ds_read_b128 v[176:179], v143 offset:32768
	ds_read_b128 v[180:183], v143 offset:33792
	ds_read_b128 v[186:189], v143 offset:34816
	ds_read_b128 v[196:199], v143 offset:35840
	ds_read_b128 v[200:203], v143 offset:36864
	ds_read_b128 v[204:207], v143 offset:37888
	ds_read_b128 v[208:211], v143 offset:38912
	ds_read_b128 v[212:215], v143 offset:39936
	global_load_lds_dwordx4 v[232:233], off
	v_lshl_add_u64 v[232:233], s[50:51], 0, v[132:133]
	s_mov_b32 m0, s55
	s_nop 0
	global_load_lds_dwordx4 v[232:233], off
	s_waitcnt vmcnt(8)
	s_waitcnt lgkmcnt(0)
	s_barrier
	s_setprio 1
	v_mfma_f32_16x16x32_bf16 v[126:129], v[144:147], v[176:179], v[126:129]
	v_mfma_f32_16x16x32_bf16 v[122:125], v[152:155], v[176:179], v[122:125]
	v_mfma_f32_16x16x32_bf16 v[118:121], v[144:147], v[186:189], v[118:121]
	v_mfma_f32_16x16x32_bf16 v[114:117], v[152:155], v[186:189], v[114:117]
	v_mfma_f32_16x16x32_bf16 v[102:105], v[144:147], v[200:203], v[102:105]
	v_mfma_f32_16x16x32_bf16 v[98:101], v[152:155], v[200:203], v[98:101]
	v_mfma_f32_16x16x32_bf16 v[86:89], v[144:147], v[208:211], v[86:89]
	v_mfma_f32_16x16x32_bf16 v[82:85], v[152:155], v[208:211], v[82:85]
	v_mfma_f32_16x16x32_bf16 v[126:129], v[148:151], v[180:183], v[126:129]
	v_mfma_f32_16x16x32_bf16 v[122:125], v[156:159], v[180:183], v[122:125]
	v_mfma_f32_16x16x32_bf16 v[118:121], v[148:151], v[196:199], v[118:121]
	v_mfma_f32_16x16x32_bf16 v[114:117], v[156:159], v[196:199], v[114:117]
	v_mfma_f32_16x16x32_bf16 v[102:105], v[148:151], v[204:207], v[102:105]
	v_mfma_f32_16x16x32_bf16 v[98:101], v[156:159], v[204:207], v[98:101]
	v_mfma_f32_16x16x32_bf16 v[86:89], v[148:151], v[212:215], v[86:89]
	v_mfma_f32_16x16x32_bf16 v[82:85], v[156:159], v[212:215], v[82:85]
	v_mfma_f32_16x16x32_bf16 v[110:113], v[160:163], v[176:179], v[110:113]
	v_mfma_f32_16x16x32_bf16 v[106:109], v[168:171], v[176:179], v[106:109]
	v_mfma_f32_16x16x32_bf16 v[94:97], v[160:163], v[186:189], v[94:97]
	v_mfma_f32_16x16x32_bf16 v[90:93], v[168:171], v[186:189], v[90:93]
	v_mfma_f32_16x16x32_bf16 v[78:81], v[160:163], v[200:203], v[78:81]
	v_mfma_f32_16x16x32_bf16 v[74:77], v[168:171], v[200:203], v[74:77]
	v_mfma_f32_16x16x32_bf16 v[70:73], v[160:163], v[208:211], v[70:73]
	v_mfma_f32_16x16x32_bf16 v[66:69], v[168:171], v[208:211], v[66:69]
	v_mfma_f32_16x16x32_bf16 v[110:113], v[164:167], v[180:183], v[110:113]
	v_mfma_f32_16x16x32_bf16 v[106:109], v[172:175], v[180:183], v[106:109]
	v_mfma_f32_16x16x32_bf16 v[94:97], v[164:167], v[196:199], v[94:97]
	v_mfma_f32_16x16x32_bf16 v[90:93], v[172:175], v[196:199], v[90:93]
	v_mfma_f32_16x16x32_bf16 v[78:81], v[164:167], v[204:207], v[78:81]
	v_mfma_f32_16x16x32_bf16 v[74:77], v[172:175], v[204:207], v[74:77]
	v_mfma_f32_16x16x32_bf16 v[70:73], v[164:167], v[212:215], v[70:73]
	v_mfma_f32_16x16x32_bf16 v[66:69], v[172:175], v[212:215], v[66:69]
	s_setprio 0
	s_barrier
; #define PG8_STAGE(bufoff, gbase, voff) do { _Pragma("unroll") for (int _i = 0; _i < 2; ++_i) \
;         __builtin_amdgcn_global_load_lds((const unsigned*)((const char*)(gbase) + (voff)[_i]), (LAS unsigned*)(lds + (bufoff) + ldsw + _i * 8192), 16, 0, 0); } while (0)
; #define PG8_LDA(dst, b, h) do { _Pragma("unroll") for (int m = 0; m < 4; ++m) _Pragma("unroll") for (int k = 0; k < 2; ++k) dst[m][k] = *(const LAS bf16x8*)(lds + PG8_SA(b, h) + aoff + m * 2048 + k * 1024); } while (0)
; #define PG8_MMA(ai, bj, At, Bt) do { __builtin_amdgcn_s_setprio(1); _Pragma("unroll") for (int m = 0; m < 4; ++m) _Pragma("unroll") for (int n = 0; n < 2; ++n) _Pragma("unroll") for (int k = 0; k < 2; ++k) \
;         acc[ai][bj][m][n] = __builtin_amdgcn_mfma_f32_16x16x32_bf16(Bt[n][k], At[m][k], acc[ai][bj][m][n], 0, 0, 0); __builtin_amdgcn_s_setprio(0); } while (0)
; #define PG8_WAIT_V(n) asm volatile("s_waitcnt vmcnt(" #n ")" ::: "memory")
; #define PG8_WAIT_L(n) asm volatile("s_waitcnt lgkmcnt(" #n ")" ::: "memory")
; #define PG8_BAR __builtin_amdgcn_s_barrier()
; #define PG8_SCHED __builtin_amdgcn_sched_barrier(0)
; template <class Epi>
; DI void gemm_phase(LAS unsigned char* lds, const Gemm g, const Epi& E, const int tid) {
;     ...
;             PG8_LDA(At, 1, 1); PG8_STAGE(PG8_SB(1, 0), b3, voffB); PG8_STAGE(PG8_SB(1, 1), b3 + hstepB, voffB); PG8_STAGE(PG8_SA(1, 0), a3, voffA);
;             PG8_WAIT_V(8); PG8_WAIT_L(0); PG8_BAR; PG8_MMA(1, 0, At, B0); PG8_MMA(1, 1, At, B1); PG8_BAR; PG8_SCHED;
;         }
;         if (wr == 0) PG8_BAR;
	s_add_i32 s12, s12, s4
	v_lshl_add_u64 v[192:193], v[192:193], 0, s[8:9]
	s_mov_b32 m0, s12
	ds_read_b128 v[176:179], v143 offset:49152
	ds_read_b128 v[180:183], v143 offset:50176
	ds_read_b128 v[186:189], v143 offset:51200
	ds_read_b128 v[196:199], v143 offset:52224
	ds_read_b128 v[200:203], v143 offset:53248
	ds_read_b128 v[204:207], v143 offset:54272
	ds_read_b128 v[208:211], v143 offset:55296
	ds_read_b128 v[212:215], v143 offset:56320
	global_load_lds_dwordx4 v[192:193], off
	s_add_i32 m0, s12, 0x2000
	s_add_u32 s48, s48, 0x20080
	v_lshl_add_u64 v[192:193], v[216:217], 0, s[8:9]
	s_addc_u32 s49, s49, 0
	s_add_i32 s12, s66, s4
	global_load_lds_dwordx4 v[192:193], off
	v_lshl_add_u64 v[192:193], s[48:49], 0, v[0:1]
	s_mov_b32 m0, s12
	s_nop 0
	global_load_lds_dwordx4 v[192:193], off
	v_lshl_add_u64 v[192:193], s[48:49], 0, v[130:131]
	s_add_i32 m0, s12, 0x2000
	s_nop 0
	global_load_lds_dwordx4 v[192:193], off
	v_lshl_add_u64 v[192:193], v[228:229], 0, s[8:9]
	s_mov_b32 m0, s56
	s_nop 0
	global_load_lds_dwordx4 v[192:193], off
	v_lshl_add_u64 v[192:193], v[230:231], 0, s[8:9]
	s_mov_b32 m0, s57
	s_nop 0
	global_load_lds_dwordx4 v[192:193], off
	s_waitcnt vmcnt(8)
	s_waitcnt lgkmcnt(0)
	s_barrier
	s_setprio 1
	v_mfma_f32_16x16x32_bf16 v[62:65], v[144:147], v[176:179], v[62:65]
	v_mfma_f32_16x16x32_bf16 v[58:61], v[152:155], v[176:179], v[58:61]
	v_mfma_f32_16x16x32_bf16 v[54:57], v[144:147], v[186:189], v[54:57]
	v_mfma_f32_16x16x32_bf16 v[50:53], v[152:155], v[186:189], v[50:53]
	v_mfma_f32_16x16x32_bf16 v[38:41], v[144:147], v[200:203], v[38:41]
	v_mfma_f32_16x16x32_bf16 v[34:37], v[152:155], v[200:203], v[34:37]
	v_mfma_f32_16x16x32_bf16 v[22:25], v[144:147], v[208:211], v[22:25]
	v_mfma_f32_16x16x32_bf16 v[18:21], v[152:155], v[208:211], v[18:21]
	v_mfma_f32_16x16x32_bf16 v[62:65], v[148:151], v[180:183], v[62:65]
	v_mfma_f32_16x16x32_bf16 v[58:61], v[156:159], v[180:183], v[58:61]
	v_mfma_f32_16x16x32_bf16 v[54:57], v[148:151], v[196:199], v[54:57]
	v_mfma_f32_16x16x32_bf16 v[50:53], v[156:159], v[196:199], v[50:53]
	v_mfma_f32_16x16x32_bf16 v[38:41], v[148:151], v[204:207], v[38:41]
	v_mfma_f32_16x16x32_bf16 v[34:37], v[156:159], v[204:207], v[34:37]
	v_mfma_f32_16x16x32_bf16 v[22:25], v[148:151], v[212:215], v[22:25]
	v_mfma_f32_16x16x32_bf16 v[18:21], v[156:159], v[212:215], v[18:21]
	v_mfma_f32_16x16x32_bf16 v[46:49], v[160:163], v[176:179], v[46:49]
	v_mfma_f32_16x16x32_bf16 v[42:45], v[168:171], v[176:179], v[42:45]
	v_mfma_f32_16x16x32_bf16 v[30:33], v[160:163], v[186:189], v[30:33]
	v_mfma_f32_16x16x32_bf16 v[26:29], v[168:171], v[186:189], v[26:29]
	v_mfma_f32_16x16x32_bf16 v[14:17], v[160:163], v[200:203], v[14:17]
	v_mfma_f32_16x16x32_bf16 v[10:13], v[168:171], v[200:203], v[10:13]
	v_mfma_f32_16x16x32_bf16 v[6:9], v[160:163], v[208:211], v[6:9]
	v_mfma_f32_16x16x32_bf16 v[2:5], v[168:171], v[208:211], v[2:5]
	v_mfma_f32_16x16x32_bf16 v[46:49], v[164:167], v[180:183], v[46:49]
	v_mfma_f32_16x16x32_bf16 v[42:45], v[172:175], v[180:183], v[42:45]
	v_mfma_f32_16x16x32_bf16 v[30:33], v[164:167], v[196:199], v[30:33]
	v_mfma_f32_16x16x32_bf16 v[26:29], v[172:175], v[196:199], v[26:29]
	v_mfma_f32_16x16x32_bf16 v[14:17], v[164:167], v[204:207], v[14:17]
	v_mfma_f32_16x16x32_bf16 v[10:13], v[172:175], v[204:207], v[10:13]
	v_mfma_f32_16x16x32_bf16 v[6:9], v[164:167], v[212:215], v[6:9]
	v_mfma_f32_16x16x32_bf16 v[2:5], v[172:175], v[212:215], v[2:5]
	s_setprio 0
	s_barrier
	s_add_i32 s65, s65, 2
	s_add_u32 s46, s46, 0x100
	s_addc_u32 s47, s47, 0
	s_add_u32 s63, s63, 0x100
	s_addc_u32 s64, s64, 0
	s_cmp_gt_u32 s65, 5
	s_cbranch_scc0 .LBB0_195
	s_and_b64 vcc, exec, s[14:15]
	s_cbranch_vccz .LBB0_198
	s_barrier

; #define PG8_STAGE(bufoff, gbase, voff) do { _Pragma("unroll") for (int _i = 0; _i < 2; ++_i) \
;         __builtin_amdgcn_global_load_lds((const unsigned*)((const char*)(gbase) + (voff)[_i]), (LAS unsigned*)(lds + (bufoff) + ldsw + _i * 8192), 16, 0, 0); } while (0)
; #define PG8_LDA(dst, b, h) do { _Pragma("unroll") for (int m = 0; m < 4; ++m) _Pragma("unroll") for (int k = 0; k < 2; ++k) dst[m][k] = *(const LAS bf16x8*)(lds + PG8_SA(b, h) + aoff + m * 2048 + k * 1024); } while (0)
; #define PG8_LDB(dst, b, h) do { _Pragma("unroll") for (int n = 0; n < 2; ++n) _Pragma("unroll") for (int k = 0; k < 2; ++k) dst[n][k] = *(const LAS bf16x8*)(lds + PG8_SB(b, h) + boff + n * 2048 + k * 1024); } while (0)
; #define PG8_MMA(ai, bj, At, Bt) do { __builtin_amdgcn_s_setprio(1); _Pragma("unroll") for (int m = 0; m < 4; ++m) _Pragma("unroll") for (int n = 0; n < 2; ++n) _Pragma("unroll") for (int k = 0; k < 2; ++k) \
;         acc[ai][bj][m][n] = __builtin_amdgcn_mfma_f32_16x16x32_bf16(Bt[n][k], At[m][k], acc[ai][bj][m][n], 0, 0, 0); __builtin_amdgcn_s_setprio(0); } while (0)
; #define PG8_WAIT_V(n) asm volatile("s_waitcnt vmcnt(" #n ")" ::: "memory")
; #define PG8_WAIT_L(n) asm volatile("s_waitcnt lgkmcnt(" #n ")" ::: "memory")
; #define PG8_BAR __builtin_amdgcn_s_barrier()
; #define PG8_SCHED __builtin_amdgcn_sched_barrier(0)
; template <class Epi>
; DI void gemm_phase(LAS unsigned char* lds, const Gemm g, const Epi& E, const int tid) {
;     ...
;         for (int t = 0; t < nt; t += 2) {
;             const bool last = (t == nt - 2);
;             const char* a1 = cA + (size_t)(t + 1) * kstepA;
;             const char* a2 = last ? nA : cA + (size_t)(t + 2) * kstepA; const char* b2 = last ? nB : cB + (size_t)(t + 2) * kstep;
;             const char* a3 = a2 + kstepA; const char* b3 = b2 + kstep;
;             PG8_LDB(B0, 0, 0); PG8_LDB(B1, 0, 1); PG8_SCHED; PG8_LDA(At, 0, 0); PG8_STAGE(PG8_SA(1, 1), a1 + hstepA, voffA);
;             PG8_WAIT_V(8); PG8_WAIT_L(0); PG8_BAR; PG8_MMA(0, 0, At, B0); PG8_MMA(0, 1, At, B1); PG8_BAR; PG8_SCHED;
;             PG8_LDA(At, 0, 1); PG8_STAGE(PG8_SB(0, 0), b2, voffB); PG8_STAGE(PG8_SB(0, 1), b2 + hstepB, voffB); PG8_STAGE(PG8_SA(0, 0), a2, voffA);
.LBB0_360:
	s_add_u32 s12, s46, s50
	s_addc_u32 s51, s47, 0
	s_add_u32 s54, s12, 0x100
	s_addc_u32 s55, s51, 0
	s_and_b64 s[52:53], s[48:49], exec
	s_cselect_b32 s53, s41, s55
	s_cselect_b32 s52, s40, s54
	s_add_u32 s50, s44, s50
	s_addc_u32 s54, s45, 0
	s_add_u32 s50, s50, 0x100
	s_addc_u32 s54, s54, 0
	s_add_i32 s81, 0, 0x10000
	s_and_b64 s[48:49], s[48:49], exec
	s_cselect_b32 s55, s35, s54
	s_cselect_b32 s54, s70, s50
	s_add_i32 s49, 0, 0x14000
	s_add_u32 s58, s12, 0x18080
	s_addc_u32 s59, s51, 0
	s_add_i32 s80, s81, s4
	s_add_i32 m0, s60, 0xc000
	s_add_i32 s12, s60, 0xe000
	s_add_i32 s75, s80, 0x2000
	s_add_u32 s56, s54, 0x10000
	v_add_u32_e32 v152, s81, v137
	v_add_u32_e32 v168, s49, v137
	s_addc_u32 s57, s55, 0
	s_add_i32 s79, s49, s4
	ds_read_b128 v[140:143], v152
	ds_read_b128 v[144:147], v152 offset:1024
	ds_read_b128 v[148:151], v152 offset:2048
	ds_read_b128 v[152:155], v152 offset:3072
	ds_read_b128 v[156:159], v168
	ds_read_b128 v[160:163], v168 offset:1024
	ds_read_b128 v[164:167], v168 offset:2048
	ds_read_b128 v[168:171], v168 offset:3072
	s_add_i32 s78, s79, 0x2000
	s_add_i32 s74, 0, 0x18000
	s_add_i32 s73, 0, 0x1c000
	s_add_u32 s50, s52, 0x18000
	s_addc_u32 s51, s53, 0
	s_add_i32 s72, s74, s4
	s_add_i32 s71, s72, 0x2000
	s_add_u32 s48, s54, 0x10080
	s_addc_u32 s49, s55, 0
	s_add_i32 s82, s73, s4
	s_add_i32 s81, s82, 0x2000
	v_lshl_add_u64 v[186:187], s[58:59], 0, v[134:135]
	ds_read_b128 v[172:175], v139
	ds_read_b128 v[176:179], v139 offset:1024
	ds_read_b128 v[180:183], v139 offset:2048
	ds_read_b128 v[196:199], v139 offset:3072
	ds_read_b128 v[200:203], v139 offset:4096
	ds_read_b128 v[204:207], v139 offset:5120
	ds_read_b128 v[208:211], v139 offset:6144
	ds_read_b128 v[228:231], v139 offset:7168
	global_load_lds_dwordx4 v[186:187], off
	v_lshl_add_u64 v[186:187], s[58:59], 0, v[132:133]
	s_mov_b32 m0, s12
	s_nop 0
	global_load_lds_dwordx4 v[186:187], off
	s_waitcnt vmcnt(8)
	s_waitcnt lgkmcnt(0)
	s_barrier
	s_setprio 1
	v_mfma_f32_16x16x32_bf16 v[126:129], v[140:143], v[172:175], v[126:129]
	v_mfma_f32_16x16x32_bf16 v[122:125], v[148:151], v[172:175], v[122:125]
	v_mfma_f32_16x16x32_bf16 v[118:121], v[140:143], v[180:183], v[118:121]
	v_mfma_f32_16x16x32_bf16 v[114:117], v[148:151], v[180:183], v[114:117]
	v_mfma_f32_16x16x32_bf16 v[102:105], v[140:143], v[200:203], v[102:105]
	v_mfma_f32_16x16x32_bf16 v[98:101], v[148:151], v[200:203], v[98:101]
	v_mfma_f32_16x16x32_bf16 v[86:89], v[140:143], v[208:211], v[86:89]
	v_mfma_f32_16x16x32_bf16 v[82:85], v[148:151], v[208:211], v[82:85]
	v_mfma_f32_16x16x32_bf16 v[126:129], v[144:147], v[176:179], v[126:129]
	v_mfma_f32_16x16x32_bf16 v[122:125], v[152:155], v[176:179], v[122:125]
	v_mfma_f32_16x16x32_bf16 v[118:121], v[144:147], v[196:199], v[118:121]
	v_mfma_f32_16x16x32_bf16 v[114:117], v[152:155], v[196:199], v[114:117]
	v_mfma_f32_16x16x32_bf16 v[102:105], v[144:147], v[204:207], v[102:105]
	v_mfma_f32_16x16x32_bf16 v[98:101], v[152:155], v[204:207], v[98:101]
	v_mfma_f32_16x16x32_bf16 v[86:89], v[144:147], v[228:231], v[86:89]
	v_mfma_f32_16x16x32_bf16 v[82:85], v[152:155], v[228:231], v[82:85]
	v_mfma_f32_16x16x32_bf16 v[110:113], v[156:159], v[172:175], v[110:113]
	v_mfma_f32_16x16x32_bf16 v[106:109], v[164:167], v[172:175], v[106:109]
	v_mfma_f32_16x16x32_bf16 v[94:97], v[156:159], v[180:183], v[94:97]
	v_mfma_f32_16x16x32_bf16 v[90:93], v[164:167], v[180:183], v[90:93]
	v_mfma_f32_16x16x32_bf16 v[78:81], v[156:159], v[200:203], v[78:81]
	v_mfma_f32_16x16x32_bf16 v[74:77], v[164:167], v[200:203], v[74:77]
	v_mfma_f32_16x16x32_bf16 v[70:73], v[156:159], v[208:211], v[70:73]
	v_mfma_f32_16x16x32_bf16 v[66:69], v[164:167], v[208:211], v[66:69]
	v_mfma_f32_16x16x32_bf16 v[110:113], v[160:163], v[176:179], v[110:113]
	v_mfma_f32_16x16x32_bf16 v[106:109], v[168:171], v[176:179], v[106:109]
	v_mfma_f32_16x16x32_bf16 v[94:97], v[160:163], v[196:199], v[94:97]
	v_mfma_f32_16x16x32_bf16 v[90:93], v[168:171], v[196:199], v[90:93]
	v_mfma_f32_16x16x32_bf16 v[78:81], v[160:163], v[204:207], v[78:81]
	v_mfma_f32_16x16x32_bf16 v[74:77], v[168:171], v[204:207], v[74:77]
	v_mfma_f32_16x16x32_bf16 v[70:73], v[160:163], v[228:231], v[70:73]
	v_mfma_f32_16x16x32_bf16 v[66:69], v[168:171], v[228:231], v[66:69]
	s_setprio 0
	s_barrier
	s_mov_b32 m0, s80
	v_lshl_add_u64 v[186:187], s[54:55], 0, v[0:1]
	ds_read_b128 v[172:175], v139 offset:16384
	ds_read_b128 v[176:179], v139 offset:17408
	ds_read_b128 v[180:183], v139 offset:18432
	ds_read_b128 v[196:199], v139 offset:19456
	ds_read_b128 v[200:203], v139 offset:20480
	ds_read_b128 v[204:207], v139 offset:21504
	ds_read_b128 v[208:211], v139 offset:22528
	ds_read_b128 v[228:231], v139 offset:23552
	global_load_lds_dwordx4 v[186:187], off
	v_lshl_add_u64 v[188:189], s[54:55], 0, v[130:131]
	s_mov_b32 m0, s75
	v_lshl_add_u64 v[212:213], s[56:57], 0, v[0:1]
	global_load_lds_dwordx4 v[188:189], off
	s_mov_b32 m0, s79
	v_lshl_add_u64 v[214:215], s[52:53], 0, v[132:133]
	global_load_lds_dwordx4 v[212:213], off
	v_lshl_add_u64 v[212:213], s[56:57], 0, v[130:131]
	s_mov_b32 m0, s78
	s_nop 0
	global_load_lds_dwordx4 v[212:213], off
	v_lshl_add_u64 v[212:213], s[52:53], 0, v[134:135]
	s_mov_b32 m0, s60
	s_nop 0
	global_load_lds_dwordx4 v[212:213], off
	s_mov_b32 m0, s61
	s_nop 0
	global_load_lds_dwordx4 v[214:215], off
	s_waitcnt vmcnt(8)
	s_waitcnt lgkmcnt(0)
	s_barrier
; #define PG8_STAGE(bufoff, gbase, voff) do { _Pragma("unroll") for (int _i = 0; _i < 2; ++_i) \
;         __builtin_amdgcn_global_load_lds((const unsigned*)((const char*)(gbase) + (voff)[_i]), (LAS unsigned*)(lds + (bufoff) + ldsw + _i * 8192), 16, 0, 0); } while (0)
; #define PG8_LDA(dst, b, h) do { _Pragma("unroll") for (int m = 0; m < 4; ++m) _Pragma("unroll") for (int k = 0; k < 2; ++k) dst[m][k] = *(const LAS bf16x8*)(lds + PG8_SA(b, h) + aoff + m * 2048 + k * 1024); } while (0)
; #define PG8_LDB(dst, b, h) do { _Pragma("unroll") for (int n = 0; n < 2; ++n) _Pragma("unroll") for (int k = 0; k < 2; ++k) dst[n][k] = *(const LAS bf16x8*)(lds + PG8_SB(b, h) + boff + n * 2048 + k * 1024); } while (0)
; #define PG8_MMA(ai, bj, At, Bt) do { __builtin_amdgcn_s_setprio(1); _Pragma("unroll") for (int m = 0; m < 4; ++m) _Pragma("unroll") for (int n = 0; n < 2; ++n) _Pragma("unroll") for (int k = 0; k < 2; ++k) \
;         acc[ai][bj][m][n] = __builtin_amdgcn_mfma_f32_16x16x32_bf16(Bt[n][k], At[m][k], acc[ai][bj][m][n], 0, 0, 0); __builtin_amdgcn_s_setprio(0); } while (0)
; #define PG8_WAIT_V(n) asm volatile("s_waitcnt vmcnt(" #n ")" ::: "memory")
; #define PG8_WAIT_L(n) asm volatile("s_waitcnt lgkmcnt(" #n ")" ::: "memory")
; #define PG8_BAR __builtin_amdgcn_s_barrier()
; #define PG8_SCHED __builtin_amdgcn_sched_barrier(0)
; template <class Epi>
; DI void gemm_phase(LAS unsigned char* lds, const Gemm g, const Epi& E, const int tid) {
;     ...
;             PG8_WAIT_V(8); PG8_WAIT_L(0); PG8_BAR; PG8_MMA(1, 0, At, B0); PG8_MMA(1, 1, At, B1); PG8_BAR; PG8_SCHED;
;             PG8_LDB(B0, 1, 0); PG8_LDB(B1, 1, 1); PG8_SCHED; PG8_LDA(At, 1, 0); PG8_STAGE(PG8_SA(0, 1), a2 + hstepA, voffA);
;             PG8_WAIT_V(8); PG8_WAIT_L(0); PG8_BAR; PG8_MMA(0, 0, At, B0); PG8_MMA(0, 1, At, B1); PG8_BAR; PG8_SCHED;
	s_setprio 1
	v_mfma_f32_16x16x32_bf16 v[62:65], v[140:143], v[172:175], v[62:65]
	v_mfma_f32_16x16x32_bf16 v[58:61], v[148:151], v[172:175], v[58:61]
	v_mfma_f32_16x16x32_bf16 v[54:57], v[140:143], v[180:183], v[54:57]
	v_mfma_f32_16x16x32_bf16 v[50:53], v[148:151], v[180:183], v[50:53]
	v_mfma_f32_16x16x32_bf16 v[38:41], v[140:143], v[200:203], v[38:41]
	v_mfma_f32_16x16x32_bf16 v[34:37], v[148:151], v[200:203], v[34:37]
	v_mfma_f32_16x16x32_bf16 v[22:25], v[140:143], v[208:211], v[22:25]
	v_mfma_f32_16x16x32_bf16 v[18:21], v[148:151], v[208:211], v[18:21]
	v_mfma_f32_16x16x32_bf16 v[62:65], v[144:147], v[176:179], v[62:65]
	v_mfma_f32_16x16x32_bf16 v[58:61], v[152:155], v[176:179], v[58:61]
	v_mfma_f32_16x16x32_bf16 v[54:57], v[144:147], v[196:199], v[54:57]
	v_mfma_f32_16x16x32_bf16 v[50:53], v[152:155], v[196:199], v[50:53]
	v_mfma_f32_16x16x32_bf16 v[38:41], v[144:147], v[204:207], v[38:41]
	v_mfma_f32_16x16x32_bf16 v[34:37], v[152:155], v[204:207], v[34:37]
	v_mfma_f32_16x16x32_bf16 v[22:25], v[144:147], v[228:231], v[22:25]
	v_mfma_f32_16x16x32_bf16 v[18:21], v[152:155], v[228:231], v[18:21]
	v_mfma_f32_16x16x32_bf16 v[46:49], v[156:159], v[172:175], v[46:49]
	v_mfma_f32_16x16x32_bf16 v[42:45], v[164:167], v[172:175], v[42:45]
	v_mfma_f32_16x16x32_bf16 v[30:33], v[156:159], v[180:183], v[30:33]
	v_mfma_f32_16x16x32_bf16 v[26:29], v[164:167], v[180:183], v[26:29]
	v_mfma_f32_16x16x32_bf16 v[14:17], v[156:159], v[200:203], v[14:17]
	v_mfma_f32_16x16x32_bf16 v[10:13], v[164:167], v[200:203], v[10:13]
	v_mfma_f32_16x16x32_bf16 v[6:9], v[156:159], v[208:211], v[6:9]
	v_mfma_f32_16x16x32_bf16 v[2:5], v[164:167], v[208:211], v[2:5]
	v_mfma_f32_16x16x32_bf16 v[46:49], v[160:163], v[176:179], v[46:49]
	v_mfma_f32_16x16x32_bf16 v[42:45], v[168:171], v[176:179], v[42:45]
	v_mfma_f32_16x16x32_bf16 v[30:33], v[160:163], v[196:199], v[30:33]
	v_mfma_f32_16x16x32_bf16 v[26:29], v[168:171], v[196:199], v[26:29]
	v_mfma_f32_16x16x32_bf16 v[14:17], v[160:163], v[204:207], v[14:17]
	v_mfma_f32_16x16x32_bf16 v[10:13], v[168:171], v[204:207], v[10:13]
	v_mfma_f32_16x16x32_bf16 v[6:9], v[160:163], v[228:231], v[6:9]
	v_mfma_f32_16x16x32_bf16 v[2:5], v[168:171], v[228:231], v[2:5]
	s_setprio 0
	s_barrier
	v_add_u32_e32 v152, s74, v137
	v_add_u32_e32 v168, s73, v137
	ds_read_b128 v[140:143], v152
	ds_read_b128 v[144:147], v152 offset:1024
	ds_read_b128 v[148:151], v152 offset:2048
	ds_read_b128 v[152:155], v152 offset:3072
	ds_read_b128 v[156:159], v168
	ds_read_b128 v[160:163], v168 offset:1024
	ds_read_b128 v[164:167], v168 offset:2048
	ds_read_b128 v[168:171], v168 offset:3072
	s_mov_b32 m0, s62
	v_lshl_add_u64 v[216:217], s[50:51], 0, v[134:135]
	ds_read_b128 v[172:175], v139 offset:32768
	ds_read_b128 v[176:179], v139 offset:33792
	ds_read_b128 v[180:183], v139 offset:34816
	ds_read_b128 v[196:199], v139 offset:35840
	ds_read_b128 v[200:203], v139 offset:36864
	ds_read_b128 v[204:207], v139 offset:37888
	ds_read_b128 v[208:211], v139 offset:38912
	ds_read_b128 v[228:231], v139 offset:39936
	global_load_lds_dwordx4 v[216:217], off
	v_lshl_add_u64 v[216:217], s[50:51], 0, v[132:133]
	s_mov_b32 m0, s63
	s_nop 0
	global_load_lds_dwordx4 v[216:217], off
	s_waitcnt vmcnt(8)
	s_waitcnt lgkmcnt(0)
	s_barrier
	s_setprio 1
	v_mfma_f32_16x16x32_bf16 v[126:129], v[140:143], v[172:175], v[126:129]
	v_mfma_f32_16x16x32_bf16 v[122:125], v[148:151], v[172:175], v[122:125]
	v_mfma_f32_16x16x32_bf16 v[118:121], v[140:143], v[180:183], v[118:121]
	v_mfma_f32_16x16x32_bf16 v[114:117], v[148:151], v[180:183], v[114:117]
	v_mfma_f32_16x16x32_bf16 v[102:105], v[140:143], v[200:203], v[102:105]
	v_mfma_f32_16x16x32_bf16 v[98:101], v[148:151], v[200:203], v[98:101]
	v_mfma_f32_16x16x32_bf16 v[86:89], v[140:143], v[208:211], v[86:89]
	v_mfma_f32_16x16x32_bf16 v[82:85], v[148:151], v[208:211], v[82:85]
	v_mfma_f32_16x16x32_bf16 v[126:129], v[144:147], v[176:179], v[126:129]
	v_mfma_f32_16x16x32_bf16 v[122:125], v[152:155], v[176:179], v[122:125]
	v_mfma_f32_16x16x32_bf16 v[118:121], v[144:147], v[196:199], v[118:121]
	v_mfma_f32_16x16x32_bf16 v[114:117], v[152:155], v[196:199], v[114:117]
	v_mfma_f32_16x16x32_bf16 v[102:105], v[144:147], v[204:207], v[102:105]
	v_mfma_f32_16x16x32_bf16 v[98:101], v[152:155], v[204:207], v[98:101]
	v_mfma_f32_16x16x32_bf16 v[86:89], v[144:147], v[228:231], v[86:89]
	v_mfma_f32_16x16x32_bf16 v[82:85], v[152:155], v[228:231], v[82:85]
	v_mfma_f32_16x16x32_bf16 v[110:113], v[156:159], v[172:175], v[110:113]
	v_mfma_f32_16x16x32_bf16 v[106:109], v[164:167], v[172:175], v[106:109]
	v_mfma_f32_16x16x32_bf16 v[94:97], v[156:159], v[180:183], v[94:97]
	v_mfma_f32_16x16x32_bf16 v[90:93], v[164:167], v[180:183], v[90:93]
	v_mfma_f32_16x16x32_bf16 v[78:81], v[156:159], v[200:203], v[78:81]
	v_mfma_f32_16x16x32_bf16 v[74:77], v[164:167], v[200:203], v[74:77]
	v_mfma_f32_16x16x32_bf16 v[70:73], v[156:159], v[208:211], v[70:73]
	v_mfma_f32_16x16x32_bf16 v[66:69], v[164:167], v[208:211], v[66:69]
	v_mfma_f32_16x16x32_bf16 v[110:113], v[160:163], v[176:179], v[110:113]
	v_mfma_f32_16x16x32_bf16 v[106:109], v[168:171], v[176:179], v[106:109]
	v_mfma_f32_16x16x32_bf16 v[94:97], v[160:163], v[196:199], v[94:97]
	v_mfma_f32_16x16x32_bf16 v[90:93], v[168:171], v[196:199], v[90:93]
	v_mfma_f32_16x16x32_bf16 v[78:81], v[160:163], v[204:207], v[78:81]
	v_mfma_f32_16x16x32_bf16 v[74:77], v[168:171], v[204:207], v[74:77]
	v_mfma_f32_16x16x32_bf16 v[70:73], v[160:163], v[228:231], v[70:73]
	v_mfma_f32_16x16x32_bf16 v[66:69], v[168:171], v[228:231], v[66:69]
	s_setprio 0
	s_barrier
; #define PG8_STAGE(bufoff, gbase, voff) do { _Pragma("unroll") for (int _i = 0; _i < 2; ++_i) \
;         __builtin_amdgcn_global_load_lds((const unsigned*)((const char*)(gbase) + (voff)[_i]), (LAS unsigned*)(lds + (bufoff) + ldsw + _i * 8192), 16, 0, 0); } while (0)
; #define PG8_LDA(dst, b, h) do { _Pragma("unroll") for (int m = 0; m < 4; ++m) _Pragma("unroll") for (int k = 0; k < 2; ++k) dst[m][k] = *(const LAS bf16x8*)(lds + PG8_SA(b, h) + aoff + m * 2048 + k * 1024); } while (0)
; #define PG8_MMA(ai, bj, At, Bt) do { __builtin_amdgcn_s_setprio(1); _Pragma("unroll") for (int m = 0; m < 4; ++m) _Pragma("unroll") for (int n = 0; n < 2; ++n) _Pragma("unroll") for (int k = 0; k < 2; ++k) \
;         acc[ai][bj][m][n] = __builtin_amdgcn_mfma_f32_16x16x32_bf16(Bt[n][k], At[m][k], acc[ai][bj][m][n], 0, 0, 0); __builtin_amdgcn_s_setprio(0); } while (0)
; #define PG8_WAIT_V(n) asm volatile("s_waitcnt vmcnt(" #n ")" ::: "memory")
; #define PG8_WAIT_L(n) asm volatile("s_waitcnt lgkmcnt(" #n ")" ::: "memory")
; #define PG8_BAR __builtin_amdgcn_s_barrier()
; #define PG8_SCHED __builtin_amdgcn_sched_barrier(0)
; template <class Epi>
; DI void gemm_phase(LAS unsigned char* lds, const Gemm g, const Epi& E, const int tid) {
;     ...
;             PG8_LDA(At, 1, 1); PG8_STAGE(PG8_SB(1, 0), b3, voffB); PG8_STAGE(PG8_SB(1, 1), b3 + hstepB, voffB); PG8_STAGE(PG8_SA(1, 0), a3, voffA);
;             PG8_WAIT_V(8); PG8_WAIT_L(0); PG8_BAR; PG8_MMA(1, 0, At, B0); PG8_MMA(1, 1, At, B1); PG8_BAR; PG8_SCHED;
;         }
;         if (wr == 0) PG8_BAR;
	s_mov_b32 m0, s72
	v_lshl_add_u64 v[186:187], v[186:187], 0, s[8:9]
	ds_read_b128 v[172:175], v139 offset:49152
	ds_read_b128 v[176:179], v139 offset:50176
	ds_read_b128 v[180:183], v139 offset:51200
	ds_read_b128 v[196:199], v139 offset:52224
	ds_read_b128 v[200:203], v139 offset:53248
	ds_read_b128 v[204:207], v139 offset:54272
	ds_read_b128 v[208:211], v139 offset:55296
	ds_read_b128 v[228:231], v139 offset:56320
	global_load_lds_dwordx4 v[186:187], off
	v_lshl_add_u64 v[186:187], v[188:189], 0, s[8:9]
	s_mov_b32 m0, s71
	s_nop 0
	global_load_lds_dwordx4 v[186:187], off
	v_lshl_add_u64 v[186:187], s[48:49], 0, v[0:1]
	s_mov_b32 m0, s82
	s_nop 0
	global_load_lds_dwordx4 v[186:187], off
	v_lshl_add_u64 v[186:187], s[48:49], 0, v[130:131]
	s_mov_b32 m0, s81
	s_nop 0
	global_load_lds_dwordx4 v[186:187], off
	v_lshl_add_u64 v[186:187], v[212:213], 0, s[8:9]
	s_mov_b32 m0, s64
	s_nop 0
	global_load_lds_dwordx4 v[186:187], off
	v_lshl_add_u64 v[186:187], v[214:215], 0, s[8:9]
	s_mov_b32 m0, s65
	s_nop 0
	global_load_lds_dwordx4 v[186:187], off
	s_waitcnt vmcnt(8)
	s_waitcnt lgkmcnt(0)
	s_barrier
	s_setprio 1
	v_mfma_f32_16x16x32_bf16 v[62:65], v[140:143], v[172:175], v[62:65]
	v_mfma_f32_16x16x32_bf16 v[58:61], v[148:151], v[172:175], v[58:61]
	v_mfma_f32_16x16x32_bf16 v[54:57], v[140:143], v[180:183], v[54:57]
	v_mfma_f32_16x16x32_bf16 v[50:53], v[148:151], v[180:183], v[50:53]
	v_mfma_f32_16x16x32_bf16 v[38:41], v[140:143], v[200:203], v[38:41]
	v_mfma_f32_16x16x32_bf16 v[34:37], v[148:151], v[200:203], v[34:37]
	v_mfma_f32_16x16x32_bf16 v[22:25], v[140:143], v[208:211], v[22:25]
	v_mfma_f32_16x16x32_bf16 v[18:21], v[148:151], v[208:211], v[18:21]
	v_mfma_f32_16x16x32_bf16 v[62:65], v[144:147], v[176:179], v[62:65]
	v_mfma_f32_16x16x32_bf16 v[58:61], v[152:155], v[176:179], v[58:61]
	v_mfma_f32_16x16x32_bf16 v[54:57], v[144:147], v[196:199], v[54:57]
	v_mfma_f32_16x16x32_bf16 v[50:53], v[152:155], v[196:199], v[50:53]
	v_mfma_f32_16x16x32_bf16 v[38:41], v[144:147], v[204:207], v[38:41]
	v_mfma_f32_16x16x32_bf16 v[34:37], v[152:155], v[204:207], v[34:37]
	v_mfma_f32_16x16x32_bf16 v[22:25], v[144:147], v[228:231], v[22:25]
	v_mfma_f32_16x16x32_bf16 v[18:21], v[152:155], v[228:231], v[18:21]
	v_mfma_f32_16x16x32_bf16 v[46:49], v[156:159], v[172:175], v[46:49]
	v_mfma_f32_16x16x32_bf16 v[42:45], v[164:167], v[172:175], v[42:45]
	v_mfma_f32_16x16x32_bf16 v[30:33], v[156:159], v[180:183], v[30:33]
	v_mfma_f32_16x16x32_bf16 v[26:29], v[164:167], v[180:183], v[26:29]
	v_mfma_f32_16x16x32_bf16 v[14:17], v[156:159], v[200:203], v[14:17]
	v_mfma_f32_16x16x32_bf16 v[10:13], v[164:167], v[200:203], v[10:13]
	v_mfma_f32_16x16x32_bf16 v[6:9], v[156:159], v[208:211], v[6:9]
	v_mfma_f32_16x16x32_bf16 v[2:5], v[164:167], v[208:211], v[2:5]
	v_mfma_f32_16x16x32_bf16 v[46:49], v[160:163], v[176:179], v[46:49]
	v_mfma_f32_16x16x32_bf16 v[42:45], v[168:171], v[176:179], v[42:45]
	v_mfma_f32_16x16x32_bf16 v[30:33], v[160:163], v[196:199], v[30:33]
	v_mfma_f32_16x16x32_bf16 v[26:29], v[168:171], v[196:199], v[26:29]
	v_mfma_f32_16x16x32_bf16 v[14:17], v[160:163], v[204:207], v[14:17]
	v_mfma_f32_16x16x32_bf16 v[10:13], v[168:171], v[204:207], v[10:13]
	v_mfma_f32_16x16x32_bf16 v[6:9], v[160:163], v[228:231], v[6:9]
	v_mfma_f32_16x16x32_bf16 v[2:5], v[168:171], v[228:231], v[2:5]
	s_setprio 0
	s_barrier
	s_movk_i32 s50, 0x100
	s_andn2_b64 vcc, exec, s[38:39]
	s_mov_b64 s[48:49], -1
	s_mov_b64 s[38:39], 0
	s_cbranch_vccz .LBB0_360
	s_and_b64 vcc, exec, s[24:25]
	s_cbranch_vccz .LBB0_363
	s_barrier

; #define PG8_STAGE(bufoff, gbase, voff) do { _Pragma("unroll") for (int _i = 0; _i < 2; ++_i) \
;         __builtin_amdgcn_global_load_lds((const unsigned*)((const char*)(gbase) + (voff)[_i]), (LAS unsigned*)(lds + (bufoff) + ldsw + _i * 8192), 16, 0, 0); } while (0)
; #define PG8_LDA(dst, b, h) do { _Pragma("unroll") for (int m = 0; m < 4; ++m) _Pragma("unroll") for (int k = 0; k < 2; ++k) dst[m][k] = *(const LAS bf16x8*)(lds + PG8_SA(b, h) + aoff + m * 2048 + k * 1024); } while (0)
; #define PG8_LDB(dst, b, h) do { _Pragma("unroll") for (int n = 0; n < 2; ++n) _Pragma("unroll") for (int k = 0; k < 2; ++k) dst[n][k] = *(const LAS bf16x8*)(lds + PG8_SB(b, h) + boff + n * 2048 + k * 1024); } while (0)
; #define PG8_MMA(ai, bj, At, Bt) do { __builtin_amdgcn_s_setprio(1); _Pragma("unroll") for (int m = 0; m < 4; ++m) _Pragma("unroll") for (int n = 0; n < 2; ++n) _Pragma("unroll") for (int k = 0; k < 2; ++k) \
;         acc[ai][bj][m][n] = __builtin_amdgcn_mfma_f32_16x16x32_bf16(Bt[n][k], At[m][k], acc[ai][bj][m][n], 0, 0, 0); __builtin_amdgcn_s_setprio(0); } while (0)
; #define PG8_WAIT_V(n) asm volatile("s_waitcnt vmcnt(" #n ")" ::: "memory")
; #define PG8_WAIT_L(n) asm volatile("s_waitcnt lgkmcnt(" #n ")" ::: "memory")
; #define PG8_BAR __builtin_amdgcn_s_barrier()
; #define PG8_SCHED __builtin_amdgcn_sched_barrier(0)
; template <class Epi>
; DI void gemm_phase(LAS unsigned char* lds, const Gemm g, const Epi& E, const int tid) {
;     ...
;         for (int t = 0; t < nt; t += 2) {
;             const bool last = (t == nt - 2);
;             const char* a1 = cA + (size_t)(t + 1) * kstepA;
;             const char* a2 = last ? nA : cA + (size_t)(t + 2) * kstepA; const char* b2 = last ? nB : cB + (size_t)(t + 2) * kstep;
;             const char* a3 = a2 + kstepA; const char* b3 = b2 + kstep;
;             PG8_LDB(B0, 0, 0); PG8_LDB(B1, 0, 1); PG8_SCHED; PG8_LDA(At, 0, 0); PG8_STAGE(PG8_SA(1, 1), a1 + hstepA, voffA);
;             PG8_WAIT_V(8); PG8_WAIT_L(0); PG8_BAR; PG8_MMA(0, 0, At, B0); PG8_MMA(0, 1, At, B1); PG8_BAR; PG8_SCHED;
;             PG8_LDA(At, 0, 1); PG8_STAGE(PG8_SB(0, 0), b2, voffB); PG8_STAGE(PG8_SB(0, 1), b2 + hstepB, voffB); PG8_STAGE(PG8_SA(0, 0), a2, voffA);
.LBB0_523:
	s_add_u32 s12, s0, 0xfffc0080
	s_addc_u32 s40, s1, -1
	s_add_i32 s65, 0, 0x10000
	s_cmp_eq_u32 s64, 12
	s_cselect_b32 s49, s35, s40
	s_cselect_b32 s48, s60, s12
	v_add_u32_e32 v0, s65, v151
	s_cselect_b32 s41, s43, s63
	s_cselect_b32 s40, s61, s62
	s_add_i32 s12, 0, 0x14000
	ds_read_b128 v[142:145], v0
	ds_read_b128 v[146:149], v0 offset:1024
	ds_read_b128 v[154:157], v0 offset:2048
	ds_read_b128 v[158:161], v0 offset:3072
	v_add_u32_e32 v0, s12, v151
	ds_read_b128 v[162:165], v0
	ds_read_b128 v[166:169], v0 offset:1024
	ds_read_b128 v[170:173], v0 offset:2048
	ds_read_b128 v[174:177], v0 offset:3072
	v_lshl_add_u64 v[182:183], s[0:1], 0, v[138:139]
	s_add_i32 m0, s53, 0xc000
	ds_read_b128 v[178:181], v153
	ds_read_b128 v[196:199], v153 offset:1024
	ds_read_b128 v[200:203], v153 offset:2048
	ds_read_b128 v[204:207], v153 offset:3072
	ds_read_b128 v[208:211], v153 offset:4096
	ds_read_b128 v[228:231], v153 offset:5120
	ds_read_b128 v[232:235], v153 offset:6144
	ds_read_b128 v[236:239], v153 offset:7168
	global_load_lds_dwordx4 v[182:183], off
	v_lshl_add_u64 v[182:183], s[0:1], 0, v[140:141]
	s_add_i32 m0, s53, 0xe000
	s_nop 0
	global_load_lds_dwordx4 v[182:183], off
	s_waitcnt vmcnt(8)
	s_waitcnt lgkmcnt(0)
	s_barrier
	s_setprio 1
	v_mfma_f32_16x16x32_bf16 v[126:129], v[142:145], v[178:181], v[126:129]
	v_mfma_f32_16x16x32_bf16 v[122:125], v[154:157], v[178:181], v[122:125]
	v_mfma_f32_16x16x32_bf16 v[110:113], v[142:145], v[200:203], v[110:113]
	v_mfma_f32_16x16x32_bf16 v[106:109], v[154:157], v[200:203], v[106:109]
	v_mfma_f32_16x16x32_bf16 v[94:97], v[142:145], v[208:211], v[94:97]
	v_mfma_f32_16x16x32_bf16 v[90:93], v[154:157], v[208:211], v[90:93]
	v_mfma_f32_16x16x32_bf16 v[78:81], v[142:145], v[232:235], v[78:81]
	v_mfma_f32_16x16x32_bf16 v[74:77], v[154:157], v[232:235], v[74:77]
	v_mfma_f32_16x16x32_bf16 v[126:129], v[146:149], v[196:199], v[126:129]
	v_mfma_f32_16x16x32_bf16 v[122:125], v[158:161], v[196:199], v[122:125]
	v_mfma_f32_16x16x32_bf16 v[110:113], v[146:149], v[204:207], v[110:113]
	v_mfma_f32_16x16x32_bf16 v[106:109], v[158:161], v[204:207], v[106:109]
	v_mfma_f32_16x16x32_bf16 v[94:97], v[146:149], v[228:231], v[94:97]
	v_mfma_f32_16x16x32_bf16 v[90:93], v[158:161], v[228:231], v[90:93]
	v_mfma_f32_16x16x32_bf16 v[78:81], v[146:149], v[236:239], v[78:81]
	v_mfma_f32_16x16x32_bf16 v[74:77], v[158:161], v[236:239], v[74:77]
	v_mfma_f32_16x16x32_bf16 v[118:121], v[162:165], v[178:181], v[118:121]
	v_mfma_f32_16x16x32_bf16 v[114:117], v[170:173], v[178:181], v[114:117]
	v_mfma_f32_16x16x32_bf16 v[102:105], v[162:165], v[200:203], v[102:105]
	v_mfma_f32_16x16x32_bf16 v[98:101], v[170:173], v[200:203], v[98:101]
	v_mfma_f32_16x16x32_bf16 v[86:89], v[162:165], v[208:211], v[86:89]
	v_mfma_f32_16x16x32_bf16 v[82:85], v[170:173], v[208:211], v[82:85]
	v_mfma_f32_16x16x32_bf16 v[70:73], v[162:165], v[232:235], v[70:73]
	v_mfma_f32_16x16x32_bf16 v[66:69], v[170:173], v[232:235], v[66:69]
	v_mfma_f32_16x16x32_bf16 v[118:121], v[166:169], v[196:199], v[118:121]
	v_mfma_f32_16x16x32_bf16 v[114:117], v[174:177], v[196:199], v[114:117]
	v_mfma_f32_16x16x32_bf16 v[102:105], v[166:169], v[204:207], v[102:105]
	v_mfma_f32_16x16x32_bf16 v[98:101], v[174:177], v[204:207], v[98:101]
	v_mfma_f32_16x16x32_bf16 v[86:89], v[166:169], v[228:231], v[86:89]
	v_mfma_f32_16x16x32_bf16 v[82:85], v[174:177], v[228:231], v[82:85]
	v_mfma_f32_16x16x32_bf16 v[70:73], v[166:169], v[236:239], v[70:73]
	v_mfma_f32_16x16x32_bf16 v[66:69], v[174:177], v[236:239], v[66:69]
	s_setprio 0
	s_barrier
	s_add_i32 s65, s65, s52
	v_lshl_add_u64 v[182:183], s[40:41], 0, v[134:135]
	s_mov_b32 m0, s65
	ds_read_b128 v[178:181], v153 offset:16384
	ds_read_b128 v[196:199], v153 offset:17408
	ds_read_b128 v[200:203], v153 offset:18432
	ds_read_b128 v[204:207], v153 offset:19456
	ds_read_b128 v[208:211], v153 offset:20480
	ds_read_b128 v[228:231], v153 offset:21504
	ds_read_b128 v[232:235], v153 offset:22528
	ds_read_b128 v[236:239], v153 offset:23552
	global_load_lds_dwordx4 v[182:183], off
	s_add_i32 m0, s65, 0x2000
	s_add_u32 s66, s40, 0x40000
	v_lshl_add_u64 v[186:187], s[40:41], 0, v[130:131]
	s_addc_u32 s67, s41, 0
	s_add_i32 s12, s12, s52
	global_load_lds_dwordx4 v[186:187], off
	v_lshl_add_u64 v[188:189], s[66:67], 0, v[134:135]
	s_mov_b32 m0, s12
	v_lshl_add_u64 v[212:213], s[48:49], 0, v[132:133]
	global_load_lds_dwordx4 v[188:189], off
	v_lshl_add_u64 v[188:189], s[66:67], 0, v[130:131]
	s_add_i32 m0, s12, 0x2000
	s_nop 0
	global_load_lds_dwordx4 v[188:189], off
	v_lshl_add_u64 v[188:189], s[48:49], 0, v[136:137]
	s_mov_b32 m0, s53
	s_nop 0
	global_load_lds_dwordx4 v[188:189], off
	s_mov_b32 m0, s54
	s_nop 0
	global_load_lds_dwordx4 v[212:213], off
	s_waitcnt vmcnt(8)
	s_waitcnt lgkmcnt(0)
	s_barrier
; #define PG8_STAGE(bufoff, gbase, voff) do { _Pragma("unroll") for (int _i = 0; _i < 2; ++_i) \
;         __builtin_amdgcn_global_load_lds((const unsigned*)((const char*)(gbase) + (voff)[_i]), (LAS unsigned*)(lds + (bufoff) + ldsw + _i * 8192), 16, 0, 0); } while (0)
; #define PG8_LDA(dst, b, h) do { _Pragma("unroll") for (int m = 0; m < 4; ++m) _Pragma("unroll") for (int k = 0; k < 2; ++k) dst[m][k] = *(const LAS bf16x8*)(lds + PG8_SA(b, h) + aoff + m * 2048 + k * 1024); } while (0)
; #define PG8_LDB(dst, b, h) do { _Pragma("unroll") for (int n = 0; n < 2; ++n) _Pragma("unroll") for (int k = 0; k < 2; ++k) dst[n][k] = *(const LAS bf16x8*)(lds + PG8_SB(b, h) + boff + n * 2048 + k * 1024); } while (0)
; #define PG8_MMA(ai, bj, At, Bt) do { __builtin_amdgcn_s_setprio(1); _Pragma("unroll") for (int m = 0; m < 4; ++m) _Pragma("unroll") for (int n = 0; n < 2; ++n) _Pragma("unroll") for (int k = 0; k < 2; ++k) \
;         acc[ai][bj][m][n] = __builtin_amdgcn_mfma_f32_16x16x32_bf16(Bt[n][k], At[m][k], acc[ai][bj][m][n], 0, 0, 0); __builtin_amdgcn_s_setprio(0); } while (0)
; #define PG8_WAIT_V(n) asm volatile("s_waitcnt vmcnt(" #n ")" ::: "memory")
; #define PG8_WAIT_L(n) asm volatile("s_waitcnt lgkmcnt(" #n ")" ::: "memory")
; #define PG8_BAR __builtin_amdgcn_s_barrier()
; #define PG8_SCHED __builtin_amdgcn_sched_barrier(0)
; template <class Epi>
; DI void gemm_phase(LAS unsigned char* lds, const Gemm g, const Epi& E, const int tid) {
;     ...
;             PG8_WAIT_V(8); PG8_WAIT_L(0); PG8_BAR; PG8_MMA(1, 0, At, B0); PG8_MMA(1, 1, At, B1); PG8_BAR; PG8_SCHED;
;             PG8_LDB(B0, 1, 0); PG8_LDB(B1, 1, 1); PG8_SCHED; PG8_LDA(At, 1, 0); PG8_STAGE(PG8_SA(0, 1), a2 + hstepA, voffA);
;             PG8_WAIT_V(8); PG8_WAIT_L(0); PG8_BAR; PG8_MMA(0, 0, At, B0); PG8_MMA(0, 1, At, B1); PG8_BAR; PG8_SCHED;
	s_setprio 1
	v_mfma_f32_16x16x32_bf16 v[62:65], v[142:145], v[178:181], v[62:65]
	v_mfma_f32_16x16x32_bf16 v[58:61], v[154:157], v[178:181], v[58:61]
	v_mfma_f32_16x16x32_bf16 v[46:49], v[142:145], v[200:203], v[46:49]
	v_mfma_f32_16x16x32_bf16 v[42:45], v[154:157], v[200:203], v[42:45]
	v_mfma_f32_16x16x32_bf16 v[30:33], v[142:145], v[208:211], v[30:33]
	v_mfma_f32_16x16x32_bf16 v[26:29], v[154:157], v[208:211], v[26:29]
	v_mfma_f32_16x16x32_bf16 v[14:17], v[142:145], v[232:235], v[14:17]
	v_mfma_f32_16x16x32_bf16 v[10:13], v[154:157], v[232:235], v[10:13]
	v_mfma_f32_16x16x32_bf16 v[62:65], v[146:149], v[196:199], v[62:65]
	v_mfma_f32_16x16x32_bf16 v[58:61], v[158:161], v[196:199], v[58:61]
	v_mfma_f32_16x16x32_bf16 v[46:49], v[146:149], v[204:207], v[46:49]
	v_mfma_f32_16x16x32_bf16 v[42:45], v[158:161], v[204:207], v[42:45]
	v_mfma_f32_16x16x32_bf16 v[30:33], v[146:149], v[228:231], v[30:33]
	v_mfma_f32_16x16x32_bf16 v[26:29], v[158:161], v[228:231], v[26:29]
	v_mfma_f32_16x16x32_bf16 v[14:17], v[146:149], v[236:239], v[14:17]
	v_mfma_f32_16x16x32_bf16 v[10:13], v[158:161], v[236:239], v[10:13]
	v_mfma_f32_16x16x32_bf16 v[54:57], v[162:165], v[178:181], v[54:57]
	v_mfma_f32_16x16x32_bf16 v[50:53], v[170:173], v[178:181], v[50:53]
	v_mfma_f32_16x16x32_bf16 v[38:41], v[162:165], v[200:203], v[38:41]
	v_mfma_f32_16x16x32_bf16 v[34:37], v[170:173], v[200:203], v[34:37]
	v_mfma_f32_16x16x32_bf16 v[22:25], v[162:165], v[208:211], v[22:25]
	v_mfma_f32_16x16x32_bf16 v[18:21], v[170:173], v[208:211], v[18:21]
	v_mfma_f32_16x16x32_bf16 v[6:9], v[162:165], v[232:235], v[6:9]
	v_mfma_f32_16x16x32_bf16 v[2:5], v[170:173], v[232:235], v[2:5]
	v_mfma_f32_16x16x32_bf16 v[54:57], v[166:169], v[196:199], v[54:57]
	v_mfma_f32_16x16x32_bf16 v[50:53], v[174:177], v[196:199], v[50:53]
	v_mfma_f32_16x16x32_bf16 v[38:41], v[166:169], v[204:207], v[38:41]
	v_mfma_f32_16x16x32_bf16 v[34:37], v[174:177], v[204:207], v[34:37]
	v_mfma_f32_16x16x32_bf16 v[22:25], v[166:169], v[228:231], v[22:25]
	v_mfma_f32_16x16x32_bf16 v[18:21], v[174:177], v[228:231], v[18:21]
	v_mfma_f32_16x16x32_bf16 v[6:9], v[166:169], v[236:239], v[6:9]
	v_mfma_f32_16x16x32_bf16 v[2:5], v[174:177], v[236:239], v[2:5]
	s_setprio 0
	s_barrier
	s_add_i32 s12, 0, 0x18000
	v_add_u32_e32 v0, s12, v151
	s_add_i32 s65, 0, 0x1c000
	ds_read_b128 v[142:145], v0
	ds_read_b128 v[146:149], v0 offset:1024
	ds_read_b128 v[154:157], v0 offset:2048
	ds_read_b128 v[158:161], v0 offset:3072
	v_add_u32_e32 v0, s65, v151
	ds_read_b128 v[162:165], v0
	ds_read_b128 v[166:169], v0 offset:1024
	ds_read_b128 v[170:173], v0 offset:2048
	ds_read_b128 v[174:177], v0 offset:3072
	s_add_u32 s48, s48, 0x40000
	s_addc_u32 s49, s49, 0
	s_mov_b32 m0, s55
	v_lshl_add_u64 v[214:215], s[48:49], 0, v[136:137]
	ds_read_b128 v[178:181], v153 offset:32768
	ds_read_b128 v[196:199], v153 offset:33792
	ds_read_b128 v[200:203], v153 offset:34816
	ds_read_b128 v[204:207], v153 offset:35840
	ds_read_b128 v[208:211], v153 offset:36864
	ds_read_b128 v[228:231], v153 offset:37888
	ds_read_b128 v[232:235], v153 offset:38912
	ds_read_b128 v[236:239], v153 offset:39936
	global_load_lds_dwordx4 v[214:215], off
	v_lshl_add_u64 v[214:215], s[48:49], 0, v[132:133]
	s_mov_b32 m0, s56
	s_nop 0
	global_load_lds_dwordx4 v[214:215], off
	s_waitcnt vmcnt(8)
	s_waitcnt lgkmcnt(0)
	s_barrier
	s_setprio 1
	v_mfma_f32_16x16x32_bf16 v[126:129], v[142:145], v[178:181], v[126:129]
	v_mfma_f32_16x16x32_bf16 v[122:125], v[154:157], v[178:181], v[122:125]
	v_mfma_f32_16x16x32_bf16 v[110:113], v[142:145], v[200:203], v[110:113]
	v_mfma_f32_16x16x32_bf16 v[106:109], v[154:157], v[200:203], v[106:109]
	v_mfma_f32_16x16x32_bf16 v[94:97], v[142:145], v[208:211], v[94:97]
	v_mfma_f32_16x16x32_bf16 v[90:93], v[154:157], v[208:211], v[90:93]
	v_mfma_f32_16x16x32_bf16 v[78:81], v[142:145], v[232:235], v[78:81]
	v_mfma_f32_16x16x32_bf16 v[74:77], v[154:157], v[232:235], v[74:77]
	v_mfma_f32_16x16x32_bf16 v[126:129], v[146:149], v[196:199], v[126:129]
	v_mfma_f32_16x16x32_bf16 v[122:125], v[158:161], v[196:199], v[122:125]
	v_mfma_f32_16x16x32_bf16 v[110:113], v[146:149], v[204:207], v[110:113]
	v_mfma_f32_16x16x32_bf16 v[106:109], v[158:161], v[204:207], v[106:109]
	v_mfma_f32_16x16x32_bf16 v[94:97], v[146:149], v[228:231], v[94:97]
	v_mfma_f32_16x16x32_bf16 v[90:93], v[158:161], v[228:231], v[90:93]
	v_mfma_f32_16x16x32_bf16 v[78:81], v[146:149], v[236:239], v[78:81]
	v_mfma_f32_16x16x32_bf16 v[74:77], v[158:161], v[236:239], v[74:77]
	v_mfma_f32_16x16x32_bf16 v[118:121], v[162:165], v[178:181], v[118:121]
	v_mfma_f32_16x16x32_bf16 v[114:117], v[170:173], v[178:181], v[114:117]
	v_mfma_f32_16x16x32_bf16 v[102:105], v[162:165], v[200:203], v[102:105]
	v_mfma_f32_16x16x32_bf16 v[98:101], v[170:173], v[200:203], v[98:101]
	v_mfma_f32_16x16x32_bf16 v[86:89], v[162:165], v[208:211], v[86:89]
	v_mfma_f32_16x16x32_bf16 v[82:85], v[170:173], v[208:211], v[82:85]
	v_mfma_f32_16x16x32_bf16 v[70:73], v[162:165], v[232:235], v[70:73]
	v_mfma_f32_16x16x32_bf16 v[66:69], v[170:173], v[232:235], v[66:69]
	v_mfma_f32_16x16x32_bf16 v[118:121], v[166:169], v[196:199], v[118:121]
	v_mfma_f32_16x16x32_bf16 v[114:117], v[174:177], v[196:199], v[114:117]
	v_mfma_f32_16x16x32_bf16 v[102:105], v[166:169], v[204:207], v[102:105]
	v_mfma_f32_16x16x32_bf16 v[98:101], v[174:177], v[204:207], v[98:101]
	v_mfma_f32_16x16x32_bf16 v[86:89], v[166:169], v[228:231], v[86:89]
	v_mfma_f32_16x16x32_bf16 v[82:85], v[174:177], v[228:231], v[82:85]
	v_mfma_f32_16x16x32_bf16 v[70:73], v[166:169], v[236:239], v[70:73]
	v_mfma_f32_16x16x32_bf16 v[66:69], v[174:177], v[236:239], v[66:69]
	s_setprio 0
	s_barrier
; #define PG8_STAGE(bufoff, gbase, voff) do { _Pragma("unroll") for (int _i = 0; _i < 2; ++_i) \
;         __builtin_amdgcn_global_load_lds((const unsigned*)((const char*)(gbase) + (voff)[_i]), (LAS unsigned*)(lds + (bufoff) + ldsw + _i * 8192), 16, 0, 0); } while (0)
; #define PG8_LDA(dst, b, h) do { _Pragma("unroll") for (int m = 0; m < 4; ++m) _Pragma("unroll") for (int k = 0; k < 2; ++k) dst[m][k] = *(const LAS bf16x8*)(lds + PG8_SA(b, h) + aoff + m * 2048 + k * 1024); } while (0)
; #define PG8_MMA(ai, bj, At, Bt) do { __builtin_amdgcn_s_setprio(1); _Pragma("unroll") for (int m = 0; m < 4; ++m) _Pragma("unroll") for (int n = 0; n < 2; ++n) _Pragma("unroll") for (int k = 0; k < 2; ++k) \
;         acc[ai][bj][m][n] = __builtin_amdgcn_mfma_f32_16x16x32_bf16(Bt[n][k], At[m][k], acc[ai][bj][m][n], 0, 0, 0); __builtin_amdgcn_s_setprio(0); } while (0)
; #define PG8_WAIT_V(n) asm volatile("s_waitcnt vmcnt(" #n ")" ::: "memory")
; #define PG8_WAIT_L(n) asm volatile("s_waitcnt lgkmcnt(" #n ")" ::: "memory")
; #define PG8_BAR __builtin_amdgcn_s_barrier()
; #define PG8_SCHED __builtin_amdgcn_sched_barrier(0)
; template <class Epi>
; DI void gemm_phase(LAS unsigned char* lds, const Gemm g, const Epi& E, const int tid) {
;     ...
;             PG8_LDA(At, 1, 1); PG8_STAGE(PG8_SB(1, 0), b3, voffB); PG8_STAGE(PG8_SB(1, 1), b3 + hstepB, voffB); PG8_STAGE(PG8_SA(1, 0), a3, voffA);
;             PG8_WAIT_V(8); PG8_WAIT_L(0); PG8_BAR; PG8_MMA(1, 0, At, B0); PG8_MMA(1, 1, At, B1); PG8_BAR; PG8_SCHED;
;         }
;         if (wr == 0) PG8_BAR;
	s_add_i32 s12, s12, s52
	v_lshl_add_u64 v[182:183], v[182:183], 0, s[8:9]
	s_mov_b32 m0, s12
	ds_read_b128 v[178:181], v153 offset:49152
	ds_read_b128 v[196:199], v153 offset:50176
	ds_read_b128 v[200:203], v153 offset:51200
	ds_read_b128 v[204:207], v153 offset:52224
	ds_read_b128 v[208:211], v153 offset:53248
	ds_read_b128 v[228:231], v153 offset:54272
	ds_read_b128 v[232:235], v153 offset:55296
	ds_read_b128 v[236:239], v153 offset:56320
	global_load_lds_dwordx4 v[182:183], off
	s_add_i32 m0, s12, 0x2000
	s_add_u32 s40, s40, 0x40080
	v_lshl_add_u64 v[182:183], v[186:187], 0, s[8:9]
	s_addc_u32 s41, s41, 0
	s_add_i32 s12, s65, s52
	global_load_lds_dwordx4 v[182:183], off
	v_lshl_add_u64 v[182:183], s[40:41], 0, v[134:135]
	s_mov_b32 m0, s12
	s_nop 0
	global_load_lds_dwordx4 v[182:183], off
	v_lshl_add_u64 v[182:183], s[40:41], 0, v[130:131]
	s_add_i32 m0, s12, 0x2000
	s_nop 0
	global_load_lds_dwordx4 v[182:183], off
	v_lshl_add_u64 v[182:183], v[188:189], 0, s[8:9]
	s_mov_b32 m0, s57
	s_nop 0
	global_load_lds_dwordx4 v[182:183], off
	v_lshl_add_u64 v[182:183], v[212:213], 0, s[8:9]
	s_mov_b32 m0, s58
	s_nop 0
	global_load_lds_dwordx4 v[182:183], off
	s_waitcnt vmcnt(8)
	s_waitcnt lgkmcnt(0)
	s_barrier
	s_setprio 1
	v_mfma_f32_16x16x32_bf16 v[62:65], v[142:145], v[178:181], v[62:65]
	v_mfma_f32_16x16x32_bf16 v[58:61], v[154:157], v[178:181], v[58:61]
	v_mfma_f32_16x16x32_bf16 v[46:49], v[142:145], v[200:203], v[46:49]
	v_mfma_f32_16x16x32_bf16 v[42:45], v[154:157], v[200:203], v[42:45]
	v_mfma_f32_16x16x32_bf16 v[30:33], v[142:145], v[208:211], v[30:33]
	v_mfma_f32_16x16x32_bf16 v[26:29], v[154:157], v[208:211], v[26:29]
	v_mfma_f32_16x16x32_bf16 v[14:17], v[142:145], v[232:235], v[14:17]
	v_mfma_f32_16x16x32_bf16 v[10:13], v[154:157], v[232:235], v[10:13]
	v_mfma_f32_16x16x32_bf16 v[62:65], v[146:149], v[196:199], v[62:65]
	v_mfma_f32_16x16x32_bf16 v[58:61], v[158:161], v[196:199], v[58:61]
	v_mfma_f32_16x16x32_bf16 v[46:49], v[146:149], v[204:207], v[46:49]
	v_mfma_f32_16x16x32_bf16 v[42:45], v[158:161], v[204:207], v[42:45]
	v_mfma_f32_16x16x32_bf16 v[30:33], v[146:149], v[228:231], v[30:33]
	v_mfma_f32_16x16x32_bf16 v[26:29], v[158:161], v[228:231], v[26:29]
	v_mfma_f32_16x16x32_bf16 v[14:17], v[146:149], v[236:239], v[14:17]
	v_mfma_f32_16x16x32_bf16 v[10:13], v[158:161], v[236:239], v[10:13]
	v_mfma_f32_16x16x32_bf16 v[54:57], v[162:165], v[178:181], v[54:57]
	v_mfma_f32_16x16x32_bf16 v[50:53], v[170:173], v[178:181], v[50:53]
	v_mfma_f32_16x16x32_bf16 v[38:41], v[162:165], v[200:203], v[38:41]
	v_mfma_f32_16x16x32_bf16 v[34:37], v[170:173], v[200:203], v[34:37]
	v_mfma_f32_16x16x32_bf16 v[22:25], v[162:165], v[208:211], v[22:25]
	v_mfma_f32_16x16x32_bf16 v[18:21], v[170:173], v[208:211], v[18:21]
	v_mfma_f32_16x16x32_bf16 v[6:9], v[162:165], v[232:235], v[6:9]
	v_mfma_f32_16x16x32_bf16 v[2:5], v[170:173], v[232:235], v[2:5]
	v_mfma_f32_16x16x32_bf16 v[54:57], v[166:169], v[196:199], v[54:57]
	v_mfma_f32_16x16x32_bf16 v[50:53], v[174:177], v[196:199], v[50:53]
	v_mfma_f32_16x16x32_bf16 v[38:41], v[166:169], v[204:207], v[38:41]
	v_mfma_f32_16x16x32_bf16 v[34:37], v[174:177], v[204:207], v[34:37]
	v_mfma_f32_16x16x32_bf16 v[22:25], v[166:169], v[228:231], v[22:25]
	v_mfma_f32_16x16x32_bf16 v[18:21], v[174:177], v[228:231], v[18:21]
	v_mfma_f32_16x16x32_bf16 v[6:9], v[166:169], v[236:239], v[6:9]
	v_mfma_f32_16x16x32_bf16 v[2:5], v[174:177], v[236:239], v[2:5]
	s_setprio 0
	s_barrier
	s_add_i32 s64, s64, 2
	s_add_u32 s0, s0, 0x100
	s_addc_u32 s1, s1, 0
	s_add_u32 s62, s62, 0x100
	s_addc_u32 s63, s63, 0
	s_cmp_gt_u32 s64, 13
	s_cbranch_scc0 .LBB0_523
	s_and_b64 vcc, exec, s[24:25]
	s_cbranch_vccz .LBB0_526
	s_barrier
